# all GEMM epilogue flat loads/stores/f32 atomics converted to global (no lgkmcnt coupling with the next unit's LDS waits), on v49
# speedup vs baseline: 1.0020x; 1.0020x over previous
; __device__ __forceinline__ int lane_id_asm() { int l; asm volatile("v_mbcnt_lo_u32_b32 %0, -1, 0\n\tv_mbcnt_hi_u32_b32 %0, -1, %0" : "=v"(l)); return l; }
; __device__ __forceinline__ u32x4 pack8(f32x4 a, f32x4 b) { u32x4 w; w.x = pk2(a[0], a[1]); w.y = pk2(a[2], a[3]); w.z = pk2(b[0], b[1]); w.w = pk2(b[2], b[3]); return w; }
;     __device__ __forceinline__ void operator()(const Acc& acc, const pg8::Unit& u, int wid) const {
;         const int lane_ = lane_id_asm(), wr = wid >> 2, wc = wid & 3, fr = lane_ & 15, fq = lane_ >> 4;
;         const int row0 = u.pm * 256 + wr * 64 + fr, colL = wc * 32 + 8 * fq, pn = u.pn;
;         float scv[8];
; #pragma unroll
;         for (int i = 0; i < 8; ++i) scv[i] = ssq[row0 + (i >> 2) * 128 + (i & 3) * 16];
;     ...
;             const float lgh = __builtin_amdgcn_logf(1.f - __builtin_amdgcn_exp2f(-5.f - (float)((pn - 8) >> 1)));
; #pragma unroll
;             for (int ai = 0; ai < 2; ++ai)
; #pragma unroll
;                 for (int m = 0; m < 4; ++m) { const int row = row0 + ai * 128 + m * 16;
;                     const float sc = __builtin_amdgcn_rsqf(scv[ai * 4 + m] * (1.f / 1024.f) + EPS) * __builtin_amdgcn_exp2f(lgh * (float)(63 - (row & 63)));
;                     bf16_t* p = V + (size_t)row * 2048 + (pn - 8) * 256 + colL;
; #pragma unroll
;                     for (int bj = 0; bj < 2; ++bj) *(u32x4*)(p + bj * 128) = pack8(acc[ai][bj][m][0] * sc, acc[ai][bj][m][1] * sc); }
.LBB0_194:
	s_lshl_b32 s4, s4, 8
	v_mbcnt_lo_u32_b32 v130, -1, 0
	v_mbcnt_hi_u32_b32 v130, -1, v130
	s_add_i32 s4, s4, s78
	v_and_b32_e32 v144, 15, v130
	v_or_b32_e32 v156, s4, v144
	v_ashrrev_i32_e32 v157, 31, v156
	v_lshl_add_u64 v[128:129], v[156:157], 2, s[54:55]
	global_load_dword v131, v[128:129], off
	global_load_dword v132, v[128:129], off offset:64
	global_load_dword v133, v[128:129], off offset:128
	global_load_dword v134, v[128:129], off offset:192
	global_load_dword v135, v[128:129], off offset:512
	global_load_dword v158, v[128:129], off offset:576
	global_load_dword v159, v[128:129], off offset:640
	global_load_dword v160, v[128:129], off offset:704
	v_ashrrev_i32_e32 v128, 1, v130
	v_and_b32_e32 v129, -8, v128
	v_add_u32_e32 v128, 0x80, v156
	v_add_u32_e32 v164, s69, v129
	v_ashrrev_i32_e32 v129, 31, v128
	v_lshlrev_b64 v[154:155], 12, v[128:129]
	v_lshlrev_b64 v[166:167], 12, v[156:157]
	s_mov_b64 s[34:35], -1
	s_cmp_gt_i32 s93, 7
	v_ashrrev_i32_e32 v165, 31, v164
	v_or_b32_e32 v162, 16, v156
	s_waitcnt vmcnt(0) lgkmcnt(0)
	v_fmamk_f32 v128, v131, 0x3a800000, v174
	v_fmamk_f32 v129, v132, 0x3a800000, v174
	v_fmamk_f32 v130, v133, 0x3a800000, v174
	v_fmamk_f32 v131, v134, 0x3a800000, v174
	v_fmamk_f32 v132, v135, 0x3a800000, v174
	v_fmamk_f32 v133, v158, 0x3a800000, v174
	v_fmamk_f32 v134, v159, 0x3a800000, v174
	v_fmamk_f32 v135, v160, 0x3a800000, v174
	v_rsq_f32_e32 v183, v128
	v_rsq_f32_e32 v182, v129
	v_rsq_f32_e32 v181, v130
	v_rsq_f32_e32 v180, v131
	v_rsq_f32_e32 v179, v132
	v_rsq_f32_e32 v178, v133
	v_rsq_f32_e32 v177, v134
	v_rsq_f32_e32 v157, v135
	v_or_b32_e32 v160, 32, v156
	v_or_b32_e32 v158, 48, v156
	s_cbranch_scc0 .LBB0_196
	s_add_i32 s4, s93, -8
	s_lshr_b32 s25, s4, 1
	v_cvt_f32_u32_e32 v128, s25
	v_xor_b32_e32 v130, 63, v144
	v_cvt_f32_ubyte0_e32 v130, v130
	s_lshl_b32 s4, s4, 9
	v_sub_f32_e32 v128, 0xc0a00000, v128
	v_exp_f32_e32 v128, v128
	v_lshlrev_b64 v[134:135], 1, v[164:165]
	v_ashrrev_i32_e32 v163, 31, v162
	v_ashrrev_i32_e32 v161, 31, v160
	v_sub_f32_e32 v128, 1.0, v128
	v_log_f32_e32 v159, v128
	v_lshl_add_u64 v[128:129], s[36:37], 0, v[166:167]
	v_lshl_add_u64 v[128:129], v[128:129], 0, s[4:5]
	v_lshl_add_u64 v[128:129], v[128:129], 0, v[134:135]
	v_mul_f32_e32 v130, v159, v130
	v_exp_f32_e32 v190, v130
	s_mov_b64 s[34:35], 0
	v_mul_f32_e32 v168, v183, v190
	v_pk_mul_f32 v[132:133], v[126:127], v[168:169] op_sel_hi:[1,0]
	v_pk_mul_f32 v[130:131], v[124:125], v[168:169] op_sel_hi:[1,0]
	v_pk_mul_f32 v[184:185], v[122:123], v[168:169] op_sel_hi:[1,0]
	v_pk_mul_f32 v[186:187], v[120:121], v[168:169] op_sel_hi:[1,0]
	v_cvt_pk_bf16_f32 v130, v130, v131
	v_cvt_pk_bf16_f32 v131, v132, v133
	v_cvt_pk_bf16_f32 v132, v186, v187
	v_cvt_pk_bf16_f32 v133, v184, v185
	global_store_dwordx4 v[128:129], v[130:133], off
	v_pk_mul_f32 v[184:185], v[110:111], v[168:169] op_sel_hi:[1,0]
	s_nop 0
	v_pk_mul_f32 v[132:133], v[114:115], v[168:169] op_sel_hi:[1,0]
	v_pk_mul_f32 v[130:131], v[112:113], v[168:169] op_sel_hi:[1,0]
	v_pk_mul_f32 v[168:169], v[108:109], v[168:169] op_sel_hi:[1,0]
	v_cvt_pk_bf16_f32 v130, v130, v131
	v_cvt_pk_bf16_f32 v131, v132, v133
	v_xor_b32_e32 v132, 47, v144
	v_cvt_f32_ubyte0_e32 v132, v132
	v_mul_f32_e32 v132, v159, v132
	v_exp_f32_e32 v191, v132
	v_cvt_pk_bf16_f32 v132, v168, v169
	v_cvt_pk_bf16_f32 v133, v184, v185
	global_store_dwordx4 v[128:129], v[130:133], off offset:256
	v_mul_f32_e32 v168, v191, v182
	v_pk_mul_f32 v[186:187], v[106:107], v[168:169] op_sel_hi:[1,0]
	v_lshlrev_b64 v[130:131], 12, v[162:163]
	v_lshl_add_u64 v[130:131], s[36:37], 0, v[130:131]
	v_lshl_add_u64 v[130:131], v[130:131], 0, s[4:5]
	v_lshl_add_u64 v[184:185], v[130:131], 0, v[134:135]
	v_pk_mul_f32 v[132:133], v[118:119], v[168:169] op_sel_hi:[1,0]
	v_pk_mul_f32 v[130:131], v[116:117], v[168:169] op_sel_hi:[1,0]
	v_pk_mul_f32 v[188:189], v[104:105], v[168:169] op_sel_hi:[1,0]
	v_cvt_pk_bf16_f32 v130, v130, v131
	v_cvt_pk_bf16_f32 v131, v132, v133
	v_cvt_pk_bf16_f32 v132, v188, v189
	v_cvt_pk_bf16_f32 v133, v186, v187
	global_store_dwordx4 v[184:185], v[130:133], off
	v_pk_mul_f32 v[186:187], v[98:99], v[168:169] op_sel_hi:[1,0]
	s_nop 0
	v_pk_mul_f32 v[132:133], v[102:103], v[168:169] op_sel_hi:[1,0]
	v_pk_mul_f32 v[130:131], v[100:101], v[168:169] op_sel_hi:[1,0]
	v_pk_mul_f32 v[168:169], v[96:97], v[168:169] op_sel_hi:[1,0]
	v_cvt_pk_bf16_f32 v130, v130, v131
	v_cvt_pk_bf16_f32 v131, v132, v133
	v_xor_b32_e32 v132, 31, v144
	v_cvt_f32_ubyte0_e32 v132, v132
	v_mul_f32_e32 v132, v159, v132
	v_exp_f32_e32 v163, v132
	v_cvt_pk_bf16_f32 v132, v168, v169
	v_cvt_pk_bf16_f32 v133, v186, v187
	global_store_dwordx4 v[184:185], v[130:133], off offset:256
	v_mul_f32_e32 v168, v163, v181
	v_pk_mul_f32 v[186:187], v[90:91], v[168:169] op_sel_hi:[1,0]
	v_lshlrev_b64 v[130:131], 12, v[160:161]
	v_lshl_add_u64 v[130:131], s[36:37], 0, v[130:131]
	v_lshl_add_u64 v[130:131], v[130:131], 0, s[4:5]
	v_lshl_add_u64 v[184:185], v[130:131], 0, v[134:135]
	v_pk_mul_f32 v[132:133], v[94:95], v[168:169] op_sel_hi:[1,0]
	v_pk_mul_f32 v[130:131], v[92:93], v[168:169] op_sel_hi:[1,0]
	v_pk_mul_f32 v[188:189], v[88:89], v[168:169] op_sel_hi:[1,0]
	v_cvt_pk_bf16_f32 v130, v130, v131
	v_cvt_pk_bf16_f32 v131, v132, v133
	v_cvt_pk_bf16_f32 v132, v188, v189
	v_cvt_pk_bf16_f32 v133, v186, v187
	global_store_dwordx4 v[184:185], v[130:133], off
	v_pk_mul_f32 v[186:187], v[78:79], v[168:169] op_sel_hi:[1,0]
	s_nop 0
	v_pk_mul_f32 v[132:133], v[82:83], v[168:169] op_sel_hi:[1,0]
	v_pk_mul_f32 v[130:131], v[80:81], v[168:169] op_sel_hi:[1,0]
	v_pk_mul_f32 v[168:169], v[76:77], v[168:169] op_sel_hi:[1,0]
	v_cvt_pk_bf16_f32 v130, v130, v131
; __device__ __forceinline__ u32x4 pack8(f32x4 a, f32x4 b) { u32x4 w; w.x = pk2(a[0], a[1]); w.y = pk2(a[2], a[3]); w.z = pk2(b[0], b[1]); w.w = pk2(b[2], b[3]); return w; }
;     __device__ __forceinline__ void operator()(const Acc& acc, const pg8::Unit& u, int wid) const {
;     ...
;             const float lgh = __builtin_amdgcn_logf(1.f - __builtin_amdgcn_exp2f(-5.f - (float)((pn - 8) >> 1)));
; #pragma unroll
;             for (int ai = 0; ai < 2; ++ai)
; #pragma unroll
;                 for (int m = 0; m < 4; ++m) { const int row = row0 + ai * 128 + m * 16;
;                     const float sc = __builtin_amdgcn_rsqf(scv[ai * 4 + m] * (1.f / 1024.f) + EPS) * __builtin_amdgcn_exp2f(lgh * (float)(63 - (row & 63)));
;                     bf16_t* p = V + (size_t)row * 2048 + (pn - 8) * 256 + colL;
; #pragma unroll
;                     for (int bj = 0; bj < 2; ++bj) *(u32x4*)(p + bj * 128) = pack8(acc[ai][bj][m][0] * sc, acc[ai][bj][m][1] * sc); }
	v_cvt_pk_bf16_f32 v131, v132, v133
	v_xor_b32_e32 v132, 15, v144
	v_cvt_f32_ubyte0_e32 v132, v132
	v_mul_f32_e32 v132, v159, v132
	v_exp_f32_e32 v161, v132
	v_cvt_pk_bf16_f32 v132, v168, v169
	v_cvt_pk_bf16_f32 v133, v186, v187
	v_ashrrev_i32_e32 v159, 31, v158
	global_store_dwordx4 v[184:185], v[130:133], off offset:256
	v_mul_f32_e32 v144, v161, v180
	v_pk_mul_f32 v[184:185], v[70:71], v[144:145] op_sel_hi:[1,0]
	v_lshlrev_b64 v[130:131], 12, v[158:159]
	v_lshl_add_u64 v[130:131], s[36:37], 0, v[130:131]
	v_lshl_add_u64 v[130:131], v[130:131], 0, s[4:5]
	v_lshl_add_u64 v[168:169], v[130:131], 0, v[134:135]
	v_pk_mul_f32 v[132:133], v[86:87], v[144:145] op_sel_hi:[1,0]
	v_pk_mul_f32 v[130:131], v[84:85], v[144:145] op_sel_hi:[1,0]
	v_pk_mul_f32 v[186:187], v[68:69], v[144:145] op_sel_hi:[1,0]
	v_cvt_pk_bf16_f32 v130, v130, v131
	v_cvt_pk_bf16_f32 v131, v132, v133
	v_cvt_pk_bf16_f32 v132, v186, v187
	v_cvt_pk_bf16_f32 v133, v184, v185
	global_store_dwordx4 v[168:169], v[130:133], off
	v_pk_mul_f32 v[184:185], v[66:67], v[144:145] op_sel_hi:[1,0]
	v_pk_mul_f32 v[186:187], v[64:65], v[144:145] op_sel_hi:[1,0]
	v_pk_mul_f32 v[132:133], v[74:75], v[144:145] op_sel_hi:[1,0]
	v_pk_mul_f32 v[130:131], v[72:73], v[144:145] op_sel_hi:[1,0]
	v_mul_f32_e32 v144, v190, v179
	v_cvt_pk_bf16_f32 v130, v130, v131
	v_cvt_pk_bf16_f32 v131, v132, v133
	v_cvt_pk_bf16_f32 v132, v186, v187
	v_cvt_pk_bf16_f32 v133, v184, v185
	global_store_dwordx4 v[168:169], v[130:133], off offset:256
	v_pk_mul_f32 v[168:169], v[58:59], v[144:145] op_sel_hi:[1,0]
	v_pk_mul_f32 v[184:185], v[56:57], v[144:145] op_sel_hi:[1,0]
	v_lshl_add_u64 v[130:131], s[36:37], 0, v[154:155]
	v_lshl_add_u64 v[130:131], v[130:131], 0, s[4:5]
	v_lshl_add_u64 v[134:135], v[130:131], 0, v[134:135]
	v_pk_mul_f32 v[132:133], v[62:63], v[144:145] op_sel_hi:[1,0]
	v_pk_mul_f32 v[130:131], v[60:61], v[144:145] op_sel_hi:[1,0]
	s_nop 0
	v_cvt_pk_bf16_f32 v130, v130, v131
	v_cvt_pk_bf16_f32 v131, v132, v133
	v_cvt_pk_bf16_f32 v132, v184, v185
	v_cvt_pk_bf16_f32 v133, v168, v169
	global_store_dwordx4 v[134:135], v[130:133], off
	v_pk_mul_f32 v[168:169], v[50:51], v[144:145] op_sel_hi:[1,0]
	v_pk_mul_f32 v[184:185], v[48:49], v[144:145] op_sel_hi:[1,0]
	v_pk_mul_f32 v[132:133], v[54:55], v[144:145] op_sel_hi:[1,0]
	v_pk_mul_f32 v[130:131], v[52:53], v[144:145] op_sel_hi:[1,0]
	v_mul_f32_e32 v144, v161, v157
	v_cvt_pk_bf16_f32 v130, v130, v131
	v_cvt_pk_bf16_f32 v131, v132, v133
	v_cvt_pk_bf16_f32 v132, v184, v185
	v_cvt_pk_bf16_f32 v133, v168, v169
	global_store_dwordx4 v[134:135], v[130:133], off offset:256
	v_mul_f32_e32 v134, v191, v178
	v_pk_mul_f32 v[184:185], v[42:43], v[134:135] op_sel_hi:[1,0]
	v_pk_mul_f32 v[132:133], v[46:47], v[134:135] op_sel_hi:[1,0]
	v_pk_mul_f32 v[130:131], v[44:45], v[134:135] op_sel_hi:[1,0]
	v_pk_mul_f32 v[186:187], v[40:41], v[134:135] op_sel_hi:[1,0]
	v_cvt_pk_bf16_f32 v130, v130, v131
	v_cvt_pk_bf16_f32 v131, v132, v133
	v_cvt_pk_bf16_f32 v133, v184, v185
	v_add_co_u32_e32 v184, vcc, s83, v128
	v_cvt_pk_bf16_f32 v132, v186, v187
	s_nop 0
	v_addc_co_u32_e32 v185, vcc, 0, v129, vcc
	global_store_dwordx4 v[184:185], v[130:133], off
	v_pk_mul_f32 v[184:185], v[34:35], v[134:135] op_sel_hi:[1,0]
	v_lshl_add_u64 v[168:169], v[128:129], 0, s[18:19]
	v_pk_mul_f32 v[132:133], v[38:39], v[134:135] op_sel_hi:[1,0]
	v_pk_mul_f32 v[130:131], v[36:37], v[134:135] op_sel_hi:[1,0]
	v_pk_mul_f32 v[134:135], v[32:33], v[134:135] op_sel_hi:[1,0]
	v_cvt_pk_bf16_f32 v130, v130, v131
	v_cvt_pk_bf16_f32 v131, v132, v133
	v_cvt_pk_bf16_f32 v132, v134, v135
	v_cvt_pk_bf16_f32 v133, v184, v185
	v_mul_f32_e32 v134, v163, v177
	global_store_dwordx4 v[168:169], v[130:133], off offset:256
	v_pk_mul_f32 v[184:185], v[26:27], v[134:135] op_sel_hi:[1,0]
	v_pk_mul_f32 v[186:187], v[24:25], v[134:135] op_sel_hi:[1,0]
	v_pk_mul_f32 v[132:133], v[30:31], v[134:135] op_sel_hi:[1,0]
	v_pk_mul_f32 v[130:131], v[28:29], v[134:135] op_sel_hi:[1,0]
	v_lshl_add_u64 v[168:169], v[128:129], 0, s[20:21]
	v_cvt_pk_bf16_f32 v130, v130, v131
	v_cvt_pk_bf16_f32 v131, v132, v133
	v_cvt_pk_bf16_f32 v133, v184, v185
	v_add_co_u32_e32 v184, vcc, s90, v128
	v_cvt_pk_bf16_f32 v132, v186, v187
	s_nop 0
	v_addc_co_u32_e32 v185, vcc, 0, v129, vcc
	global_store_dwordx4 v[184:185], v[130:133], off
	v_pk_mul_f32 v[184:185], v[18:19], v[134:135] op_sel_hi:[1,0]
	s_nop 0
	v_pk_mul_f32 v[132:133], v[22:23], v[134:135] op_sel_hi:[1,0]
	v_pk_mul_f32 v[130:131], v[20:21], v[134:135] op_sel_hi:[1,0]
	v_pk_mul_f32 v[134:135], v[16:17], v[134:135] op_sel_hi:[1,0]
	v_cvt_pk_bf16_f32 v130, v130, v131
	v_cvt_pk_bf16_f32 v131, v132, v133
	v_cvt_pk_bf16_f32 v132, v134, v135
	v_cvt_pk_bf16_f32 v133, v184, v185
	global_store_dwordx4 v[168:169], v[130:133], off offset:256
	v_lshl_add_u64 v[168:169], v[128:129], 0, s[22:23]
	v_pk_mul_f32 v[134:135], v[10:11], v[144:145] op_sel_hi:[1,0]
	v_pk_mul_f32 v[132:133], v[14:15], v[144:145] op_sel_hi:[1,0]
	v_pk_mul_f32 v[130:131], v[12:13], v[144:145] op_sel_hi:[1,0]
	v_pk_mul_f32 v[184:185], v[8:9], v[144:145] op_sel_hi:[1,0]
	v_add_co_u32_e32 v128, vcc, s91, v128
	v_cvt_pk_bf16_f32 v130, v130, v131
	v_cvt_pk_bf16_f32 v131, v132, v133
	v_cvt_pk_bf16_f32 v132, v184, v185
	v_cvt_pk_bf16_f32 v133, v134, v135
	v_addc_co_u32_e32 v129, vcc, 0, v129, vcc
	global_store_dwordx4 v[128:129], v[130:133], off
	v_pk_mul_f32 v[128:129], v[4:5], v[144:145] op_sel_hi:[1,0]
	v_pk_mul_f32 v[134:135], v[2:3], v[144:145] op_sel_hi:[1,0]
	v_pk_mul_f32 v[130:131], v[6:7], v[144:145] op_sel_hi:[1,0]
	v_pk_mul_f32 v[132:133], v[0:1], v[144:145] op_sel_hi:[1,0]
; __device__ __forceinline__ u32x4 pack8(f32x4 a, f32x4 b) { u32x4 w; w.x = pk2(a[0], a[1]); w.y = pk2(a[2], a[3]); w.z = pk2(b[0], b[1]); w.w = pk2(b[2], b[3]); return w; }
;     __device__ __forceinline__ void operator()(const Acc& acc, const pg8::Unit& u, int wid) const {
;     ...
;         if (pn < 8) {
;             const float kmul = pn >= 4 ? 0.0625f : 1.f;
; #pragma unroll
;             for (int ai = 0; ai < 2; ++ai)
; #pragma unroll
;                 for (int mp = 0; mp < 2; ++mp) {
;                     f32x4 c4[2][2], s4[2][2];
; #pragma unroll
;                     for (int mm = 0; mm < 2; ++mm) { const int s = (row0 + ai * 128 + (2 * mp + mm) * 16) & (SEQ - 1);
; #pragma unroll
;                         for (int n = 0; n < 2; ++n) { c4[mm][n] = *(const f32x4*)(cosT + (size_t)s * 128 + colL + 4 * n); s4[mm][n] = *(const f32x4*)(sinT + (size_t)s * 128 + colL + 4 * n); } }
; #pragma unroll
;                     for (int mm = 0; mm < 2; ++mm) { const int m = 2 * mp + mm, row = row0 + ai * 128 + m * 16;
;                         const float ks = __builtin_amdgcn_rsqf(scv[ai * 4 + m] * (1.f / 1024.f) + EPS) * kmul;
;                         f32x4 o1[2], o2[2];
; #pragma unroll
;                         for (int n = 0; n < 2; ++n) { const f32x4 x1 = acc[ai][0][m][n] * ks, x2 = acc[ai][1][m][n] * ks;
;                             o1[n] = x1 * c4[mm][n] - x2 * s4[mm][n]; o2[n] = x2 * c4[mm][n] + x1 * s4[mm][n]; }
;                         bf16_t* p = QK + (size_t)row * 2048 + pn * 256 + colL;
;                         *(u32x4*)p = pack8(o1[0], o1[1]); *(u32x4*)(p + 128) = pack8(o2[0], o2[1]); }
.LBB0_196:
	s_andn2_b64 vcc, exec, s[34:35]
	s_cbranch_vccnz .LBB0_198
	v_lshlrev_b64 v[130:131], 2, v[164:165]
	v_lshlrev_b32_e32 v132, 9, v156
	v_lshl_add_u64 v[128:129], s[10:11], 0, v[130:131]
	v_and_b32_e32 v144, 0x1f9e00, v132
	v_lshl_add_u64 v[132:133], v[128:129], 0, v[144:145]
	v_lshl_add_u64 v[130:131], s[8:9], 0, v[130:131]
	global_load_dwordx4 v[184:187], v[132:133], off
	global_load_dwordx4 v[188:191], v[132:133], off offset:16
	v_lshl_add_u64 v[132:133], v[130:131], 0, v[144:145]
	global_load_dwordx4 v[192:195], v[132:133], off
	global_load_dwordx4 v[196:199], v[132:133], off offset:16
	v_mov_b32_e32 v133, v145
	v_or_b32_e32 v132, 0x2000, v144
	v_lshl_add_u64 v[134:135], v[128:129], 0, v[132:133]
	global_load_dwordx4 v[200:203], v[134:135], off
	global_load_dwordx4 v[204:207], v[134:135], off offset:16
	v_lshl_add_u64 v[132:133], v[130:131], 0, v[132:133]
	global_load_dwordx4 v[208:211], v[132:133], off
	global_load_dwordx4 v[212:215], v[132:133], off offset:16
	v_or_b32_e32 v132, 0x4000, v144
	v_mov_b32_e32 v133, v145
	v_lshl_add_u64 v[134:135], v[128:129], 0, v[132:133]
	global_load_dwordx4 v[220:223], v[134:135], off
	global_load_dwordx4 v[224:227], v[134:135], off offset:16
	v_lshl_add_u64 v[134:135], v[130:131], 0, v[132:133]
	global_load_dwordx4 v[232:235], v[134:135], off
	global_load_dwordx4 v[236:239], v[134:135], off offset:16
	v_or_b32_e32 v132, 0x6000, v144
	v_lshl_add_u64 v[134:135], v[128:129], 0, v[132:133]
	global_load_dwordx4 v[228:231], v[134:135], off
	global_load_dwordx4 v[246:249], v[134:135], off offset:16
	v_lshl_add_u64 v[134:135], v[130:131], 0, v[132:133]
	global_load_dwordx4 v[240:243], v[134:135], off
	global_load_dwordx4 v[250:253], v[134:135], off offset:16
	s_cmp_gt_i32 s93, 3
	s_cselect_b64 vcc, -1, 0
	v_cndmask_b32_e32 v134, 1.0, v175, vcc
	s_lshl_b32 s34, s93, 8
	v_lshlrev_b64 v[132:133], 1, v[164:165]
	s_ashr_i32 s35, s34, 31
	v_mul_f32_e32 v164, v134, v183
	v_lshl_add_u64 v[166:167], s[44:45], 0, v[166:167]
	v_mul_f32_e32 v168, v134, v182
	v_pk_mul_f32 v[124:125], v[124:125], v[164:165] op_sel_hi:[1,0]
	v_pk_mul_f32 v[126:127], v[126:127], v[164:165] op_sel_hi:[1,0]
	v_pk_mul_f32 v[114:115], v[114:115], v[164:165] op_sel_hi:[1,0]
	v_pk_mul_f32 v[112:113], v[112:113], v[164:165] op_sel_hi:[1,0]
	v_pk_mul_f32 v[110:111], v[110:111], v[164:165] op_sel_hi:[1,0]
	v_pk_mul_f32 v[108:109], v[108:109], v[164:165] op_sel_hi:[1,0]
	s_lshl_b64 s[34:35], s[34:35], 1
	v_pk_mul_f32 v[120:121], v[120:121], v[164:165] op_sel_hi:[1,0]
	v_pk_mul_f32 v[122:123], v[122:123], v[164:165] op_sel_hi:[1,0]
	v_pk_mul_f32 v[116:117], v[116:117], v[168:169] op_sel_hi:[1,0]
	v_pk_mul_f32 v[118:119], v[118:119], v[168:169] op_sel_hi:[1,0]
	v_pk_mul_f32 v[164:165], v[102:103], v[168:169] op_sel_hi:[1,0]
	v_pk_mul_f32 v[182:183], v[100:101], v[168:169] op_sel_hi:[1,0]
	v_pk_mul_f32 v[216:217], v[104:105], v[168:169] op_sel_hi:[1,0]
	v_pk_mul_f32 v[106:107], v[106:107], v[168:169] op_sel_hi:[1,0]
	v_pk_mul_f32 v[218:219], v[98:99], v[168:169] op_sel_hi:[1,0]
	v_pk_mul_f32 v[168:169], v[96:97], v[168:169] op_sel_hi:[1,0]
	v_lshl_add_u64 v[96:97], v[166:167], 0, s[34:35]
	v_lshl_add_u64 v[96:97], v[96:97], 0, v[132:133]
	v_ashrrev_i32_e32 v163, 31, v162
	v_ashrrev_i32_e32 v161, 31, v160
	v_ashrrev_i32_e32 v159, 31, v158
	s_waitcnt vmcnt(8)
	v_pk_mul_f32 v[98:99], v[112:113], v[184:185]
	v_pk_mul_f32 v[100:101], v[114:115], v[186:187]
	v_pk_mul_f32 v[102:103], v[124:125], v[184:185]
	v_pk_mul_f32 v[104:105], v[126:127], v[186:187]
	v_pk_mul_f32 v[166:167], v[108:109], v[188:189]
	v_pk_mul_f32 v[184:185], v[110:111], v[190:191]
	v_pk_mul_f32 v[186:187], v[120:121], v[188:189]
	v_pk_mul_f32 v[188:189], v[122:123], v[190:191]
	v_pk_fma_f32 v[100:101], v[126:127], v[194:195], v[100:101] neg_lo:[0,0,1] neg_hi:[0,0,1]
	v_pk_fma_f32 v[98:99], v[124:125], v[192:193], v[98:99] neg_lo:[0,0,1] neg_hi:[0,0,1]
	v_pk_fma_f32 v[104:105], v[114:115], v[194:195], v[104:105]
	v_pk_fma_f32 v[102:103], v[112:113], v[192:193], v[102:103]
	v_pk_fma_f32 v[112:113], v[122:123], v[198:199], v[184:185] neg_lo:[0,0,1] neg_hi:[0,0,1]
	v_pk_fma_f32 v[114:115], v[120:121], v[196:197], v[166:167] neg_lo:[0,0,1] neg_hi:[0,0,1]
	v_pk_fma_f32 v[110:111], v[110:111], v[198:199], v[188:189]
	v_pk_fma_f32 v[108:109], v[108:109], v[196:197], v[186:187]
	v_cvt_pk_bf16_f32 v98, v98, v99
	v_cvt_pk_bf16_f32 v99, v100, v101
	v_cvt_pk_bf16_f32 v100, v114, v115
	v_cvt_pk_bf16_f32 v101, v112, v113
	v_cvt_pk_bf16_f32 v102, v102, v103
	v_cvt_pk_bf16_f32 v103, v104, v105
	v_cvt_pk_bf16_f32 v104, v108, v109
	v_cvt_pk_bf16_f32 v105, v110, v111
	global_store_dwordx4 v[96:97], v[98:101], off
	global_store_dwordx4 v[96:97], v[102:105], off offset:256
	v_pk_mul_f32 v[120:121], v[182:183], v[200:201]
	v_lshlrev_b64 v[98:99], 12, v[162:163]
	v_pk_mul_f32 v[122:123], v[164:165], v[202:203]
	v_pk_mul_f32 v[166:167], v[168:169], v[204:205]
	v_pk_mul_f32 v[184:185], v[218:219], v[206:207]
	v_lshl_add_u64 v[98:99], s[44:45], 0, v[98:99]
	v_pk_mul_f32 v[124:125], v[116:117], v[200:201]
	v_pk_mul_f32 v[126:127], v[118:119], v[202:203]
	v_pk_mul_f32 v[186:187], v[216:217], v[204:205]
	v_pk_mul_f32 v[188:189], v[106:107], v[206:207]
	v_pk_fma_f32 v[108:109], v[118:119], v[210:211], v[122:123] neg_lo:[0,0,1] neg_hi:[0,0,1]
	v_pk_fma_f32 v[110:111], v[116:117], v[208:209], v[120:121] neg_lo:[0,0,1] neg_hi:[0,0,1]
	v_pk_fma_f32 v[106:107], v[106:107], v[214:215], v[184:185] neg_lo:[0,0,1] neg_hi:[0,0,1]
	v_pk_fma_f32 v[116:117], v[216:217], v[212:213], v[166:167] neg_lo:[0,0,1] neg_hi:[0,0,1]
	v_lshl_add_u64 v[98:99], v[98:99], 0, s[34:35]
	v_pk_fma_f32 v[112:113], v[164:165], v[210:211], v[126:127]
; __device__ __forceinline__ u32x4 pack8(f32x4 a, f32x4 b) { u32x4 w; w.x = pk2(a[0], a[1]); w.y = pk2(a[2], a[3]); w.z = pk2(b[0], b[1]); w.w = pk2(b[2], b[3]); return w; }
;     __device__ __forceinline__ void operator()(const Acc& acc, const pg8::Unit& u, int wid) const {
;     ...
;         if (pn < 8) {
;             const float kmul = pn >= 4 ? 0.0625f : 1.f;
; #pragma unroll
;             for (int ai = 0; ai < 2; ++ai)
; #pragma unroll
;                 for (int mp = 0; mp < 2; ++mp) {
;                     f32x4 c4[2][2], s4[2][2];
; #pragma unroll
;                     for (int mm = 0; mm < 2; ++mm) { const int s = (row0 + ai * 128 + (2 * mp + mm) * 16) & (SEQ - 1);
; #pragma unroll
;                         for (int n = 0; n < 2; ++n) { c4[mm][n] = *(const f32x4*)(cosT + (size_t)s * 128 + colL + 4 * n); s4[mm][n] = *(const f32x4*)(sinT + (size_t)s * 128 + colL + 4 * n); } }
; #pragma unroll
;                     for (int mm = 0; mm < 2; ++mm) { const int m = 2 * mp + mm, row = row0 + ai * 128 + m * 16;
;                         const float ks = __builtin_amdgcn_rsqf(scv[ai * 4 + m] * (1.f / 1024.f) + EPS) * kmul;
;                         f32x4 o1[2], o2[2];
; #pragma unroll
;                         for (int n = 0; n < 2; ++n) { const f32x4 x1 = acc[ai][0][m][n] * ks, x2 = acc[ai][1][m][n] * ks;
;                             o1[n] = x1 * c4[mm][n] - x2 * s4[mm][n]; o2[n] = x2 * c4[mm][n] + x1 * s4[mm][n]; }
;                         bf16_t* p = QK + (size_t)row * 2048 + pn * 256 + colL;
;                         *(u32x4*)p = pack8(o1[0], o1[1]); *(u32x4*)(p + 128) = pack8(o2[0], o2[1]); }
	v_pk_fma_f32 v[114:115], v[182:183], v[208:209], v[124:125]
	v_pk_fma_f32 v[102:103], v[218:219], v[214:215], v[188:189]
	v_pk_fma_f32 v[104:105], v[168:169], v[212:213], v[186:187]
	v_lshl_add_u64 v[118:119], v[98:99], 0, v[132:133]
	v_cvt_pk_bf16_f32 v98, v110, v111
	v_cvt_pk_bf16_f32 v99, v108, v109
	v_cvt_pk_bf16_f32 v100, v116, v117
	v_cvt_pk_bf16_f32 v101, v106, v107
	global_store_dwordx4 v[118:119], v[98:101], off
	s_nop 1
	v_cvt_pk_bf16_f32 v98, v114, v115
	v_cvt_pk_bf16_f32 v99, v112, v113
	v_cvt_pk_bf16_f32 v100, v104, v105
	v_cvt_pk_bf16_f32 v101, v102, v103
	global_store_dwordx4 v[118:119], v[98:101], off offset:256
	v_lshl_add_u32 v216, v156, 7, v176
	v_and_b32_e32 v216, 0x7e780, v216
	v_lshlrev_b32_e32 v216, 2, v216
	v_mov_b32_e32 v217, v145
	v_lshl_add_u64 v[102:103], v[128:129], 0, v[216:217]
	global_load_dwordx4 v[184:187], v[102:103], off
	global_load_dwordx4 v[188:191], v[102:103], off offset:16
	v_lshl_add_u64 v[102:103], v[130:131], 0, v[216:217]
	global_load_dwordx4 v[192:195], v[102:103], off
	global_load_dwordx4 v[196:199], v[102:103], off offset:16
	v_or_b32_e32 v104, 0x2000, v216
	v_mov_b32_e32 v105, v145
	v_lshl_add_u64 v[102:103], v[128:129], 0, v[104:105]
	global_load_dwordx4 v[200:203], v[102:103], off
	global_load_dwordx4 v[208:211], v[102:103], off offset:16
	v_lshl_add_u64 v[102:103], v[130:131], 0, v[104:105]
	global_load_dwordx4 v[204:207], v[102:103], off
	global_load_dwordx4 v[212:215], v[102:103], off offset:16
	v_mul_f32_e32 v144, v134, v181
	v_lshlrev_b64 v[126:127], 12, v[160:161]
	v_mul_f32_e32 v160, v134, v180
	v_pk_mul_f32 v[82:83], v[82:83], v[144:145] op_sel_hi:[1,0]
	v_pk_mul_f32 v[80:81], v[80:81], v[144:145] op_sel_hi:[1,0]
	v_pk_mul_f32 v[78:79], v[78:79], v[144:145] op_sel_hi:[1,0]
	v_pk_mul_f32 v[76:77], v[76:77], v[144:145] op_sel_hi:[1,0]
	v_lshl_add_u64 v[126:127], s[44:45], 0, v[126:127]
	v_pk_mul_f32 v[92:93], v[92:93], v[144:145] op_sel_hi:[1,0]
	v_pk_mul_f32 v[94:95], v[94:95], v[144:145] op_sel_hi:[1,0]
	v_pk_mul_f32 v[88:89], v[88:89], v[144:145] op_sel_hi:[1,0]
	v_pk_mul_f32 v[90:91], v[90:91], v[144:145] op_sel_hi:[1,0]
	v_pk_mul_f32 v[84:85], v[84:85], v[160:161] op_sel_hi:[1,0]
	v_pk_mul_f32 v[86:87], v[86:87], v[160:161] op_sel_hi:[1,0]
	v_pk_mul_f32 v[74:75], v[74:75], v[160:161] op_sel_hi:[1,0]
	v_pk_mul_f32 v[72:73], v[72:73], v[160:161] op_sel_hi:[1,0]
	v_lshl_add_u64 v[126:127], v[126:127], 0, s[34:35]
	v_lshl_add_u64 v[126:127], v[126:127], 0, v[132:133]
	v_pk_mul_f32 v[64:65], v[64:65], v[160:161] op_sel_hi:[1,0]
	v_pk_mul_f32 v[68:69], v[68:69], v[160:161] op_sel_hi:[1,0]
	v_pk_mul_f32 v[66:67], v[66:67], v[160:161] op_sel_hi:[1,0]
	v_pk_mul_f32 v[70:71], v[70:71], v[160:161] op_sel_hi:[1,0]
	s_waitcnt vmcnt(12)
	v_pk_mul_f32 v[166:167], v[80:81], v[220:221]
	v_pk_mul_f32 v[168:169], v[82:83], v[222:223]
	v_pk_mul_f32 v[180:181], v[76:77], v[224:225]
	v_pk_mul_f32 v[182:183], v[78:79], v[226:227]
	v_pk_mul_f32 v[220:221], v[92:93], v[220:221]
	v_pk_mul_f32 v[222:223], v[94:95], v[222:223]
	v_pk_mul_f32 v[224:225], v[88:89], v[224:225]
	v_pk_mul_f32 v[226:227], v[90:91], v[226:227]
	v_pk_mul_f32 v[98:99], v[72:73], v[228:229]
	v_pk_mul_f32 v[100:101], v[74:75], v[230:231]
	v_pk_mul_f32 v[228:229], v[84:85], v[228:229]
	v_pk_mul_f32 v[230:231], v[86:87], v[230:231]
	v_pk_fma_f32 v[94:95], v[94:95], v[234:235], v[168:169] neg_lo:[0,0,1] neg_hi:[0,0,1]
	v_pk_fma_f32 v[92:93], v[92:93], v[232:233], v[166:167] neg_lo:[0,0,1] neg_hi:[0,0,1]
	v_pk_fma_f32 v[90:91], v[90:91], v[238:239], v[182:183] neg_lo:[0,0,1] neg_hi:[0,0,1]
	v_pk_fma_f32 v[88:89], v[88:89], v[236:237], v[180:181] neg_lo:[0,0,1] neg_hi:[0,0,1]
	v_pk_fma_f32 v[82:83], v[82:83], v[234:235], v[222:223]
	v_pk_fma_f32 v[80:81], v[80:81], v[232:233], v[220:221]
	v_pk_fma_f32 v[220:221], v[78:79], v[238:239], v[226:227]
	v_pk_fma_f32 v[78:79], v[76:77], v[236:237], v[224:225]
	v_pk_fma_f32 v[222:223], v[74:75], v[242:243], v[230:231]
	v_pk_fma_f32 v[224:225], v[72:73], v[240:241], v[228:229]
	v_cvt_pk_bf16_f32 v72, v92, v93
	v_cvt_pk_bf16_f32 v73, v94, v95
	v_cvt_pk_bf16_f32 v74, v88, v89
	v_cvt_pk_bf16_f32 v75, v90, v91
	v_cvt_pk_bf16_f32 v76, v80, v81
	v_cvt_pk_bf16_f32 v77, v82, v83
	v_cvt_pk_bf16_f32 v78, v78, v79
	v_cvt_pk_bf16_f32 v79, v220, v221
	global_store_dwordx4 v[126:127], v[72:75], off
	global_store_dwordx4 v[126:127], v[76:79], off offset:256
	v_pk_fma_f32 v[86:87], v[86:87], v[242:243], v[100:101] neg_lo:[0,0,1] neg_hi:[0,0,1]
	v_pk_mul_f32 v[72:73], v[64:65], v[246:247]
	v_pk_mul_f32 v[74:75], v[66:67], v[248:249]
	v_pk_fma_f32 v[72:73], v[68:69], v[250:251], v[72:73] neg_lo:[0,0,1] neg_hi:[0,0,1]
	v_pk_mul_f32 v[68:69], v[68:69], v[246:247]
	v_pk_fma_f32 v[84:85], v[84:85], v[240:241], v[98:99] neg_lo:[0,0,1] neg_hi:[0,0,1]
	v_pk_fma_f32 v[68:69], v[64:65], v[250:251], v[68:69]
	v_lshlrev_b64 v[64:65], 12, v[158:159]
	v_lshl_add_u64 v[64:65], s[44:45], 0, v[64:65]
	v_pk_fma_f32 v[74:75], v[70:71], v[252:253], v[74:75] neg_lo:[0,0,1] neg_hi:[0,0,1]
	v_pk_mul_f32 v[70:71], v[70:71], v[248:249]
	v_lshl_add_u64 v[64:65], v[64:65], 0, s[34:35]
	v_pk_fma_f32 v[70:71], v[66:67], v[252:253], v[70:71]
	v_lshl_add_u64 v[76:77], v[64:65], 0, v[132:133]
	v_cvt_pk_bf16_f32 v64, v84, v85
	v_cvt_pk_bf16_f32 v65, v86, v87
	v_cvt_pk_bf16_f32 v66, v72, v73
	v_cvt_pk_bf16_f32 v67, v74, v75
	global_store_dwordx4 v[76:77], v[64:67], off
	s_nop 1
	v_cvt_pk_bf16_f32 v64, v224, v225
	v_cvt_pk_bf16_f32 v65, v222, v223
	v_cvt_pk_bf16_f32 v66, v68, v69
	v_cvt_pk_bf16_f32 v67, v70, v71
	global_store_dwordx4 v[76:77], v[64:67], off offset:256
	v_lshl_add_u64 v[98:99], s[44:45], 0, v[154:155]
	v_or_b32_e32 v104, 0x4000, v216
; __device__ __forceinline__ u32x4 pack8(f32x4 a, f32x4 b) { u32x4 w; w.x = pk2(a[0], a[1]); w.y = pk2(a[2], a[3]); w.z = pk2(b[0], b[1]); w.w = pk2(b[2], b[3]); return w; }
;     __device__ __forceinline__ void operator()(const Acc& acc, const pg8::Unit& u, int wid) const {
;     ...
;         if (pn < 8) {
;             const float kmul = pn >= 4 ? 0.0625f : 1.f;
; #pragma unroll
;             for (int ai = 0; ai < 2; ++ai)
; #pragma unroll
;                 for (int mp = 0; mp < 2; ++mp) {
;                     f32x4 c4[2][2], s4[2][2];
; #pragma unroll
;                     for (int mm = 0; mm < 2; ++mm) { const int s = (row0 + ai * 128 + (2 * mp + mm) * 16) & (SEQ - 1);
; #pragma unroll
;                         for (int n = 0; n < 2; ++n) { c4[mm][n] = *(const f32x4*)(cosT + (size_t)s * 128 + colL + 4 * n); s4[mm][n] = *(const f32x4*)(sinT + (size_t)s * 128 + colL + 4 * n); } }
; #pragma unroll
;                     for (int mm = 0; mm < 2; ++mm) { const int m = 2 * mp + mm, row = row0 + ai * 128 + m * 16;
;                         const float ks = __builtin_amdgcn_rsqf(scv[ai * 4 + m] * (1.f / 1024.f) + EPS) * kmul;
;                         f32x4 o1[2], o2[2];
; #pragma unroll
;                         for (int n = 0; n < 2; ++n) { const f32x4 x1 = acc[ai][0][m][n] * ks, x2 = acc[ai][1][m][n] * ks;
;                             o1[n] = x1 * c4[mm][n] - x2 * s4[mm][n]; o2[n] = x2 * c4[mm][n] + x1 * s4[mm][n]; }
;                         bf16_t* p = QK + (size_t)row * 2048 + pn * 256 + colL;
;                         *(u32x4*)p = pack8(o1[0], o1[1]); *(u32x4*)(p + 128) = pack8(o2[0], o2[1]); }
	v_mov_b32_e32 v105, v145
	v_lshl_add_u64 v[106:107], v[128:129], 0, v[104:105]
	global_load_dwordx4 v[220:223], v[106:107], off
	global_load_dwordx4 v[224:227], v[106:107], off offset:16
	v_lshl_add_u64 v[106:107], v[130:131], 0, v[104:105]
	global_load_dwordx4 v[228:231], v[106:107], off
	global_load_dwordx4 v[232:235], v[106:107], off offset:16
	v_or_b32_e32 v104, 0x6000, v216
	v_lshl_add_u64 v[106:107], v[128:129], 0, v[104:105]
	global_load_dwordx4 v[236:239], v[106:107], off
	global_load_dwordx4 v[246:249], v[106:107], off offset:16
	v_lshl_add_u64 v[106:107], v[130:131], 0, v[104:105]
	global_load_dwordx4 v[240:243], v[106:107], off
	global_load_dwordx4 v[250:253], v[106:107], off offset:16
	v_mul_f32_e32 v100, v134, v179
	v_pk_mul_f32 v[54:55], v[54:55], v[100:101] op_sel_hi:[1,0]
	v_pk_mul_f32 v[52:53], v[52:53], v[100:101] op_sel_hi:[1,0]
	v_pk_mul_f32 v[50:51], v[50:51], v[100:101] op_sel_hi:[1,0]
	v_pk_mul_f32 v[48:49], v[48:49], v[100:101] op_sel_hi:[1,0]
	v_pk_mul_f32 v[60:61], v[60:61], v[100:101] op_sel_hi:[1,0]
	v_pk_mul_f32 v[62:63], v[62:63], v[100:101] op_sel_hi:[1,0]
	v_pk_mul_f32 v[56:57], v[56:57], v[100:101] op_sel_hi:[1,0]
	v_pk_mul_f32 v[58:59], v[58:59], v[100:101] op_sel_hi:[1,0]
	v_mul_f32_e32 v102, v134, v178
	v_lshl_add_u64 v[98:99], v[98:99], 0, s[34:35]
	v_lshl_add_u64 v[98:99], v[98:99], 0, v[132:133]
	v_pk_mul_f32 v[38:39], v[38:39], v[102:103] op_sel_hi:[1,0]
	v_pk_mul_f32 v[36:37], v[36:37], v[102:103] op_sel_hi:[1,0]
	v_pk_mul_f32 v[44:45], v[44:45], v[102:103] op_sel_hi:[1,0]
	v_pk_mul_f32 v[46:47], v[46:47], v[102:103] op_sel_hi:[1,0]
	v_pk_mul_f32 v[34:35], v[34:35], v[102:103] op_sel_hi:[1,0]
	v_pk_mul_f32 v[32:33], v[32:33], v[102:103] op_sel_hi:[1,0]
	v_pk_mul_f32 v[40:41], v[40:41], v[102:103] op_sel_hi:[1,0]
	v_pk_mul_f32 v[42:43], v[42:43], v[102:103] op_sel_hi:[1,0]
	v_lshl_add_u64 v[168:169], v[96:97], 0, s[22:23]
	s_waitcnt vmcnt(12)
	v_pk_mul_f32 v[100:101], v[52:53], v[184:185]
	v_pk_mul_f32 v[104:105], v[54:55], v[186:187]
	v_pk_mul_f32 v[106:107], v[48:49], v[188:189]
	v_pk_mul_f32 v[108:109], v[50:51], v[190:191]
	v_pk_mul_f32 v[184:185], v[60:61], v[184:185]
	v_pk_mul_f32 v[186:187], v[62:63], v[186:187]
	v_pk_mul_f32 v[188:189], v[56:57], v[188:189]
	v_pk_mul_f32 v[190:191], v[58:59], v[190:191]
	v_pk_fma_f32 v[62:63], v[62:63], v[194:195], v[104:105] neg_lo:[0,0,1] neg_hi:[0,0,1]
	v_pk_fma_f32 v[60:61], v[60:61], v[192:193], v[100:101] neg_lo:[0,0,1] neg_hi:[0,0,1]
	v_pk_fma_f32 v[58:59], v[58:59], v[198:199], v[108:109] neg_lo:[0,0,1] neg_hi:[0,0,1]
	v_pk_fma_f32 v[56:57], v[56:57], v[196:197], v[106:107] neg_lo:[0,0,1] neg_hi:[0,0,1]
	v_pk_fma_f32 v[54:55], v[54:55], v[194:195], v[186:187]
	v_pk_fma_f32 v[52:53], v[52:53], v[192:193], v[184:185]
	v_pk_fma_f32 v[184:185], v[50:51], v[198:199], v[190:191]
	v_pk_fma_f32 v[186:187], v[48:49], v[196:197], v[188:189]
	v_cvt_pk_bf16_f32 v48, v60, v61
	v_cvt_pk_bf16_f32 v49, v62, v63
	v_cvt_pk_bf16_f32 v50, v56, v57
	v_cvt_pk_bf16_f32 v51, v58, v59
	v_cvt_pk_bf16_f32 v52, v52, v53
	v_cvt_pk_bf16_f32 v53, v54, v55
	v_cvt_pk_bf16_f32 v54, v186, v187
	v_cvt_pk_bf16_f32 v55, v184, v185
	global_store_dwordx4 v[98:99], v[48:51], off
	global_store_dwordx4 v[98:99], v[52:55], off offset:256
	v_mul_f32_e32 v184, v134, v177
	v_pk_mul_f32 v[48:49], v[36:37], v[200:201]
	v_pk_mul_f32 v[50:51], v[38:39], v[202:203]
	v_pk_fma_f32 v[48:49], v[44:45], v[204:205], v[48:49] neg_lo:[0,0,1] neg_hi:[0,0,1]
	v_pk_fma_f32 v[50:51], v[46:47], v[206:207], v[50:51] neg_lo:[0,0,1] neg_hi:[0,0,1]
	v_pk_mul_f32 v[44:45], v[44:45], v[200:201]
	v_pk_mul_f32 v[46:47], v[46:47], v[202:203]
	v_pk_fma_f32 v[36:37], v[36:37], v[204:205], v[44:45]
	v_pk_fma_f32 v[38:39], v[38:39], v[206:207], v[46:47]
	v_pk_mul_f32 v[44:45], v[32:33], v[208:209]
	v_pk_mul_f32 v[46:47], v[34:35], v[210:211]
	v_pk_fma_f32 v[44:45], v[40:41], v[212:213], v[44:45] neg_lo:[0,0,1] neg_hi:[0,0,1]
	v_pk_fma_f32 v[46:47], v[42:43], v[214:215], v[46:47] neg_lo:[0,0,1] neg_hi:[0,0,1]
	v_pk_mul_f32 v[42:43], v[42:43], v[210:211]
	v_pk_mul_f32 v[40:41], v[40:41], v[208:209]
	v_pk_fma_f32 v[42:43], v[34:35], v[214:215], v[42:43]
	v_cvt_pk_bf16_f32 v34, v44, v45
	v_add_co_u32_e32 v44, vcc, s83, v96
	v_pk_fma_f32 v[40:41], v[32:33], v[212:213], v[40:41]
	v_cvt_pk_bf16_f32 v32, v48, v49
	v_cvt_pk_bf16_f32 v33, v50, v51
	v_cvt_pk_bf16_f32 v35, v46, v47
	v_addc_co_u32_e32 v45, vcc, 0, v97, vcc
	v_lshl_add_u64 v[52:53], v[96:97], 0, s[18:19]
	global_store_dwordx4 v[44:45], v[32:35], off
	v_pk_mul_f32 v[16:17], v[16:17], v[184:185] op_sel_hi:[1,0]
	v_pk_mul_f32 v[28:29], v[28:29], v[184:185] op_sel_hi:[1,0]
	v_cvt_pk_bf16_f32 v32, v36, v37
	v_cvt_pk_bf16_f32 v33, v38, v39
	v_cvt_pk_bf16_f32 v34, v40, v41
	v_cvt_pk_bf16_f32 v35, v42, v43
	global_store_dwordx4 v[52:53], v[32:35], off offset:256
	v_pk_mul_f32 v[22:23], v[22:23], v[184:185] op_sel_hi:[1,0]
	v_pk_mul_f32 v[20:21], v[20:21], v[184:185] op_sel_hi:[1,0]
	v_pk_mul_f32 v[24:25], v[24:25], v[184:185] op_sel_hi:[1,0]
	v_pk_mul_f32 v[26:27], v[26:27], v[184:185] op_sel_hi:[1,0]
	v_pk_mul_f32 v[18:19], v[18:19], v[184:185] op_sel_hi:[1,0]
	v_pk_mul_f32 v[30:31], v[30:31], v[184:185] op_sel_hi:[1,0]
	v_lshl_add_u64 v[64:65], v[96:97], 0, s[20:21]
	s_waitcnt vmcnt(4)
; #define PG8_BAR __builtin_amdgcn_s_barrier()
; __device__ __forceinline__ u32x4 pack8(f32x4 a, f32x4 b) { u32x4 w; w.x = pk2(a[0], a[1]); w.y = pk2(a[2], a[3]); w.z = pk2(b[0], b[1]); w.w = pk2(b[2], b[3]); return w; }
; template <class Epi>
; __device__ __forceinline__ void gemm_phase(LAS unsigned char* lds, const Gemm g, const StaticOrder& S, const Epi& E, const int wid) {
;     ...
;         if (wr == 0) PG8_BAR;
;         E(acc, cur, wid);
;         if (!has_next) break;
; #pragma unroll
;         for (int a = 0; a < 2; ++a)
; #pragma unroll
;             for (int b = 0; b < 2; ++b)
; #pragma unroll
;                 for (int m = 0; m < 4; ++m)
; #pragma unroll
;                     for (int n = 0; n < 2; ++n) acc[a][b][m][n] = (f32x4){0.f, 0.f, 0.f, 0.f};
;         cur = nxt; cA = nA; cB = nB; ++ui;
;         if (wr == 1) PG8_BAR;
;     __device__ __forceinline__ void operator()(const Acc& acc, const pg8::Unit& u, int wid) const {
;     ...
;                     for (int mm = 0; mm < 2; ++mm) { const int s = (row0 + ai * 128 + (2 * mp + mm) * 16) & (SEQ - 1);
; #pragma unroll
;                         for (int n = 0; n < 2; ++n) { c4[mm][n] = *(const f32x4*)(cosT + (size_t)s * 128 + colL + 4 * n); s4[mm][n] = *(const f32x4*)(sinT + (size_t)s * 128 + colL + 4 * n); } }
; #pragma unroll
;                     for (int mm = 0; mm < 2; ++mm) { const int m = 2 * mp + mm, row = row0 + ai * 128 + m * 16;
;                         const float ks = __builtin_amdgcn_rsqf(scv[ai * 4 + m] * (1.f / 1024.f) + EPS) * kmul;
;                         f32x4 o1[2], o2[2];
; #pragma unroll
;                         for (int n = 0; n < 2; ++n) { const f32x4 x1 = acc[ai][0][m][n] * ks, x2 = acc[ai][1][m][n] * ks;
;                             o1[n] = x1 * c4[mm][n] - x2 * s4[mm][n]; o2[n] = x2 * c4[mm][n] + x1 * s4[mm][n]; }
;                         bf16_t* p = QK + (size_t)row * 2048 + pn * 256 + colL;
;                         *(u32x4*)p = pack8(o1[0], o1[1]); *(u32x4*)(p + 128) = pack8(o2[0], o2[1]); }
	v_pk_mul_f32 v[66:67], v[20:21], v[220:221]
	v_pk_mul_f32 v[70:71], v[16:17], v[224:225]
	v_pk_mul_f32 v[68:69], v[22:23], v[222:223]
	v_pk_mul_f32 v[220:221], v[28:29], v[220:221]
	v_pk_mul_f32 v[72:73], v[18:19], v[226:227]
	v_pk_mul_f32 v[224:225], v[24:25], v[224:225]
	v_pk_mul_f32 v[226:227], v[26:27], v[226:227]
	v_pk_fma_f32 v[24:25], v[24:25], v[232:233], v[70:71] neg_lo:[0,0,1] neg_hi:[0,0,1]
	v_pk_mul_f32 v[222:223], v[30:31], v[222:223]
	v_pk_fma_f32 v[30:31], v[30:31], v[230:231], v[68:69] neg_lo:[0,0,1] neg_hi:[0,0,1]
	v_pk_fma_f32 v[28:29], v[28:29], v[228:229], v[66:67] neg_lo:[0,0,1] neg_hi:[0,0,1]
	v_pk_fma_f32 v[20:21], v[20:21], v[228:229], v[220:221]
	v_pk_fma_f32 v[26:27], v[26:27], v[234:235], v[72:73] neg_lo:[0,0,1] neg_hi:[0,0,1]
	v_pk_fma_f32 v[220:221], v[18:19], v[234:235], v[226:227]
	v_cvt_pk_bf16_f32 v18, v24, v25
	v_add_co_u32_e32 v24, vcc, s90, v96
	v_pk_fma_f32 v[22:23], v[22:23], v[230:231], v[222:223]
	v_pk_fma_f32 v[222:223], v[16:17], v[232:233], v[224:225]
	v_cvt_pk_bf16_f32 v16, v28, v29
	v_cvt_pk_bf16_f32 v17, v30, v31
	v_cvt_pk_bf16_f32 v19, v26, v27
	v_addc_co_u32_e32 v25, vcc, 0, v97, vcc
	global_store_dwordx4 v[24:25], v[16:19], off
	s_nop 1
	v_cvt_pk_bf16_f32 v16, v20, v21
	v_cvt_pk_bf16_f32 v17, v22, v23
	v_cvt_pk_bf16_f32 v18, v222, v223
	v_cvt_pk_bf16_f32 v19, v220, v221
	global_store_dwordx4 v[64:65], v[16:19], off offset:256
	s_nop 1
	v_mul_f32_e32 v16, v134, v157
	v_pk_mul_f32 v[4:5], v[4:5], v[16:17] op_sel_hi:[1,0]
	v_pk_mul_f32 v[12:13], v[12:13], v[16:17] op_sel_hi:[1,0]
	v_pk_mul_f32 v[6:7], v[6:7], v[16:17] op_sel_hi:[1,0]
	v_pk_mul_f32 v[18:19], v[4:5], v[236:237]
	v_pk_mul_f32 v[14:15], v[14:15], v[16:17] op_sel_hi:[1,0]
	v_pk_mul_f32 v[20:21], v[6:7], v[238:239]
	v_pk_fma_f32 v[18:19], v[12:13], v[240:241], v[18:19] neg_lo:[0,0,1] neg_hi:[0,0,1]
	v_pk_mul_f32 v[12:13], v[12:13], v[236:237]
	v_pk_mul_f32 v[0:1], v[0:1], v[16:17] op_sel_hi:[1,0]
	v_pk_fma_f32 v[20:21], v[14:15], v[242:243], v[20:21] neg_lo:[0,0,1] neg_hi:[0,0,1]
	v_pk_mul_f32 v[14:15], v[14:15], v[238:239]
	v_pk_fma_f32 v[128:129], v[4:5], v[240:241], v[12:13]
	v_pk_mul_f32 v[4:5], v[8:9], v[16:17] op_sel_hi:[1,0]
	v_pk_mul_f32 v[2:3], v[2:3], v[16:17] op_sel_hi:[1,0]
	v_pk_mul_f32 v[8:9], v[0:1], v[246:247]
	v_pk_fma_f32 v[130:131], v[6:7], v[242:243], v[14:15]
	v_pk_mul_f32 v[6:7], v[10:11], v[16:17] op_sel_hi:[1,0]
	v_pk_mul_f32 v[10:11], v[2:3], v[248:249]
	v_pk_fma_f32 v[8:9], v[4:5], v[250:251], v[8:9] neg_lo:[0,0,1] neg_hi:[0,0,1]
	v_pk_mul_f32 v[4:5], v[4:5], v[246:247]
	v_pk_fma_f32 v[10:11], v[6:7], v[252:253], v[10:11] neg_lo:[0,0,1] neg_hi:[0,0,1]
	v_pk_mul_f32 v[6:7], v[6:7], v[248:249]
	v_pk_fma_f32 v[132:133], v[0:1], v[250:251], v[4:5]
	v_add_co_u32_e32 v4, vcc, 0xb0000, v96
	v_pk_fma_f32 v[134:135], v[2:3], v[252:253], v[6:7]
	v_cvt_pk_bf16_f32 v0, v18, v19
	v_cvt_pk_bf16_f32 v1, v20, v21
	v_cvt_pk_bf16_f32 v2, v8, v9
	v_cvt_pk_bf16_f32 v3, v10, v11
	v_addc_co_u32_e32 v5, vcc, 0, v97, vcc
	global_store_dwordx4 v[4:5], v[0:3], off
.LBB0_198:
	s_nop 1
	v_cvt_pk_bf16_f32 v0, v128, v129
	v_cvt_pk_bf16_f32 v1, v130, v131
	v_cvt_pk_bf16_f32 v2, v132, v133
	v_cvt_pk_bf16_f32 v3, v134, v135
	s_andn2_b64 vcc, exec, s[0:1]
	s_mov_b64 s[0:1], -1
	global_store_dwordx4 v[168:169], v[0:3], off offset:256
	s_cbranch_vccnz .LBB0_183
	s_andn2_b64 vcc, exec, s[6:7]
	s_cbranch_vccnz .LBB0_182
	s_barrier
	s_branch .LBB0_182

;     __device__ __forceinline__ void operator()(const Acc& acc, const pg8::Unit& u, int wid) const {
;         const int lane_ = lane_id_asm(), wr = wid >> 2, wc = wid & 3, fr = lane_ & 15, fq = lane_ >> 4;
;         const int row0 = u.pm * 256 + wr * 64 + fr, col0 = u.pn * 256 + wc * 32 + 8 * fq, head = u.pn >> 1;
;         f32x4 g4[2][2];
; #pragma unroll
;         for (int bj = 0; bj < 2; ++bj) { g4[bj][0] = *(const f32x4*)(gn + col0 + bj * 128); g4[bj][1] = *(const f32x4*)(gn + col0 + bj * 128 + 4); }
; #pragma unroll
;         for (int ai = 0; ai < 2; ++ai)
; #pragma unroll
;             for (int mp = 0; mp < 2; ++mp) {
;                 float scv[2]; f32x4 rq[2][4]; u32x4 ov[2][2];
; #pragma unroll
;                 for (int mm = 0; mm < 2; ++mm) { const int row = row0 + ai * 128 + (2 * mp + mm) * 16;
;                     scv[mm] = ssq[row];
;                     const f32x4* rp = (const f32x4*)(rssq + (size_t)row * 64 + head * 16);
; #pragma unroll
;                     for (int i = 0; i < 4; ++i) rq[mm][i] = rp[i];
; #pragma unroll
;                     for (int bj = 0; bj < 2; ++bj) ov[mm][bj] = *(const u32x4*)(Y + (size_t)row * 2048 + col0 + bj * 128); }
; #pragma unroll
;                 for (int mm = 0; mm < 2; ++mm) { const int m = 2 * mp + mm, row = row0 + ai * 128 + m * 16;
;                     const float sc = __builtin_amdgcn_rsqf(scv[mm] * (1.f / 1024.f) + EPS);
;                     const f32x4 pa = (rq[mm][0] + rq[mm][1]) + (rq[mm][2] + rq[mm][3]);
;                     const float rg = __builtin_amdgcn_rsqf(((pa[0] + pa[1]) + (pa[2] + pa[3])) * (1.f / 512.f) + EPS);
; #pragma unroll
;                     for (int bj = 0; bj < 2; ++bj) {
;                         const u32x4 w = ov[mm][bj];
;                         f32x4 o0 = (f32x4){bflo(w.x), bfhi(w.x), bflo(w.y), bfhi(w.y)}, o1 = (f32x4){bflo(w.z), bfhi(w.z), bflo(w.w), bfhi(w.w)};
;                         f32x4 a0 = acc[ai][bj][m][0] * sc, a1 = acc[ai][bj][m][1] * sc;
; #pragma unroll
;                         for (int e = 0; e < 4; ++e) { a0[e] = a0[e] * __builtin_amdgcn_rcpf(1.f + __builtin_amdgcn_exp2f(-1.4426950408889634f * a0[e])); a1[e] = a1[e] * __builtin_amdgcn_rcpf(1.f + __builtin_amdgcn_exp2f(-1.4426950408889634f * a1[e])); }
;                         o0 = a0 * o0 * g4[bj][0] * rg; o1 = a1 * o1 * g4[bj][1] * rg;
.LBB0_334:
	s_lshl_b32 s11, s22, 8
	s_add_i32 s11, s11, s66
	v_mbcnt_lo_u32_b32 v50, -1, 0
	v_mbcnt_hi_u32_b32 v50, -1, v50
	s_lshl_b32 s15, s20, 8
	v_and_or_b32 v186, v50, 15, s11
	s_lshl_b32 s11, s20, 3
	s_and_b32 s20, s11, -16
	s_ashr_i32 s21, s20, 31
	s_or_b32 s15, s15, s69
	s_lshl_b64 s[20:21], s[20:21], 2
	s_add_u32 s20, s60, s20
	v_ashrrev_i32_e32 v187, 31, v186
	v_ashrrev_i32_e32 v48, 1, v50
	s_addc_u32 s21, s61, s21
	v_lshl_add_u64 v[188:189], v[186:187], 2, s[54:55]
	v_lshlrev_b64 v[50:51], 8, v[186:187]
	v_lshl_add_u64 v[50:51], s[20:21], 0, v[50:51]
	global_load_dword v199, v[188:189], off
	global_load_dwordx4 v[200:203], v[50:51], off
	global_load_dwordx4 v[204:207], v[50:51], off offset:16
	global_load_dwordx4 v[208:211], v[50:51], off offset:32
	global_load_dwordx4 v[212:215], v[50:51], off offset:48
	v_and_b32_e32 v48, -8, v48
	v_add_u32_e32 v48, s15, v48
	v_ashrrev_i32_e32 v49, 31, v48
	v_lshlrev_b64 v[184:185], 1, v[48:49]
	v_lshl_add_u64 v[190:191], s[36:37], 0, v[184:185]
	v_lshlrev_b64 v[224:225], 12, v[186:187]
	v_lshl_add_u64 v[144:145], v[190:191], 0, v[224:225]
	global_load_dwordx4 v[216:219], v[144:145], off
	v_lshl_add_u64 v[48:49], v[48:49], 2, s[48:49]
	v_or_b32_e32 v50, 16, v186
	global_load_dwordx4 v[64:67], v[48:49], off
	v_ashrrev_i32_e32 v51, 31, v50
	v_lshlrev_b64 v[146:147], 8, v[50:51]
	v_lshlrev_b64 v[192:193], 12, v[50:51]
	global_load_dwordx4 v[68:71], v[48:49], off offset:16
	global_load_dwordx4 v[56:59], v[48:49], off offset:512
	s_nop 0
	global_load_dwordx4 v[48:51], v[48:49], off offset:528
	v_lshl_add_u64 v[146:147], s[20:21], 0, v[146:147]
	global_load_dword v187, v[188:189], off offset:64
	global_load_dwordx4 v[160:163], v[146:147], off offset:16
	global_load_dwordx4 v[152:155], v[146:147], off offset:32
	v_lshl_add_u64 v[226:227], v[190:191], 0, v[192:193]
	global_load_dwordx4 v[220:223], v[144:145], off offset:256
	global_load_dwordx4 v[164:167], v[146:147], off
	global_load_dwordx4 v[156:159], v[146:147], off offset:48
	global_load_dwordx4 v[148:151], v[226:227], off
	s_nop 0
	global_load_dwordx4 v[144:147], v[226:227], off offset:256
	s_andn2_b64 vcc, exec, s[0:1]
	s_mov_b64 s[0:1], -1
	s_waitcnt vmcnt(0) lgkmcnt(0)
	v_fmamk_f32 v199, v199, 0x3a800000, v198
	v_rsq_f32_e32 v226, v199
	v_pk_add_f32 v[202:203], v[202:203], v[206:207]
	v_pk_add_f32 v[200:201], v[200:201], v[204:205]
	v_pk_add_f32 v[204:205], v[210:211], v[214:215]
	v_pk_add_f32 v[206:207], v[208:209], v[212:213]
	v_pk_add_f32 v[202:203], v[202:203], v[204:205]
	v_pk_add_f32 v[200:201], v[200:201], v[206:207]
	v_pk_mul_f32 v[140:141], v[140:141], v[226:227] op_sel_hi:[1,0]
	v_pk_mov_b32 v[212:213], v[200:201], v[202:203] op_sel:[1,0]
	v_mov_b32_e32 v201, v203
	v_pk_add_f32 v[200:201], v[212:213], v[200:201]
	v_pk_mul_f32 v[136:137], v[136:137], v[226:227] op_sel_hi:[1,0]
	v_pk_mul_f32 v[142:143], v[142:143], v[226:227] op_sel_hi:[1,0]
	v_add_f32_e32 v199, v200, v201
	v_mul_f32_e32 v200, 0xbfb8aa3b, v140
	v_mul_f32_e32 v201, 0xbfb8aa3b, v136
	v_mul_f32_e32 v202, 0xbfb8aa3b, v141
	v_mul_f32_e32 v212, 0xbfb8aa3b, v142
	v_exp_f32_e32 v214, v200
	v_exp_f32_e32 v201, v201
	v_exp_f32_e32 v202, v202
	v_exp_f32_e32 v212, v212
	v_fmamk_f32 v199, v199, 0x3b000000, v198
	v_pk_mul_f32 v[138:139], v[138:139], v[226:227] op_sel_hi:[1,0]
	v_mul_f32_e32 v215, 0xbfb8aa3b, v143
	v_rsq_f32_e32 v200, v199
	v_add_f32_e32 v199, 1.0, v214
	v_add_f32_e32 v201, 1.0, v201
	v_lshlrev_b32_e32 v204, 16, v216
	v_and_b32_e32 v205, 0xffff0000, v216
	v_mul_f32_e32 v203, 0xbfb8aa3b, v137
	v_mul_f32_e32 v213, 0xbfb8aa3b, v138
	v_add_f32_e32 v214, 1.0, v202
	v_add_f32_e32 v216, 1.0, v212
	v_rcp_f32_e32 v202, v199
	v_rcp_f32_e32 v212, v201
	v_exp_f32_e32 v199, v215
	v_mul_f32_e32 v201, 0xbfb8aa3b, v139
	v_exp_f32_e32 v203, v203
	v_exp_f32_e32 v213, v213
	v_exp_f32_e32 v201, v201
	v_add_f32_e32 v199, 1.0, v199
	v_lshlrev_b32_e32 v208, 16, v218
	v_and_b32_e32 v209, 0xffff0000, v218
	v_add_f32_e32 v218, 1.0, v203
	v_add_f32_e32 v213, 1.0, v213
	v_rcp_f32_e32 v215, v199
	v_add_f32_e32 v199, 1.0, v201
	v_lshlrev_b32_e32 v206, 16, v217
	v_and_b32_e32 v207, 0xffff0000, v217
	v_rcp_f32_e32 v203, v214
	v_rcp_f32_e32 v214, v216
	v_rcp_f32_e32 v216, v213
	v_rcp_f32_e32 v217, v199
	v_rcp_f32_e32 v213, v218
	v_lshlrev_b32_e32 v210, 16, v219
	v_and_b32_e32 v211, 0xffff0000, v219
	v_pk_mul_f32 v[142:143], v[142:143], v[214:215]
	v_pk_mul_f32 v[140:141], v[140:141], v[202:203]
	v_pk_mul_f32 v[138:139], v[138:139], v[216:217]
	v_pk_mul_f32 v[136:137], v[136:137], v[212:213]
	v_pk_mul_f32 v[140:141], v[140:141], v[204:205]
	v_pk_mul_f32 v[142:143], v[142:143], v[206:207]
	v_pk_mul_f32 v[136:137], v[136:137], v[208:209]
	v_pk_mul_f32 v[138:139], v[138:139], v[210:211]
	v_pk_mul_f32 v[132:133], v[132:133], v[226:227] op_sel_hi:[1,0]
	v_pk_mul_f32 v[142:143], v[66:67], v[142:143]
	v_pk_mul_f32 v[140:141], v[64:65], v[140:141]
	v_pk_mul_f32 v[138:139], v[70:71], v[138:139]
	v_pk_mul_f32 v[136:137], v[68:69], v[136:137]
	v_mul_f32_e32 v199, 0xbfb8aa3b, v132
	v_pk_mul_f32 v[128:129], v[128:129], v[226:227] op_sel_hi:[1,0]
	v_pk_mul_f32 v[142:143], v[200:201], v[142:143] op_sel_hi:[0,1]
	v_pk_mul_f32 v[140:141], v[200:201], v[140:141] op_sel_hi:[0,1]
	v_pk_mul_f32 v[202:203], v[200:201], v[138:139] op_sel_hi:[0,1]
	v_pk_mul_f32 v[138:139], v[200:201], v[136:137] op_sel_hi:[0,1]
	v_exp_f32_e32 v199, v199
	v_mul_f32_e32 v201, 0xbfb8aa3b, v128
	v_exp_f32_e32 v201, v201
	v_pk_mul_f32 v[134:135], v[134:135], v[226:227] op_sel_hi:[1,0]
	v_add_f32_e32 v199, 1.0, v199
	v_mul_f32_e32 v204, 0xbfb8aa3b, v133
	v_pk_mul_f32 v[130:131], v[130:131], v[226:227] op_sel_hi:[1,0]
	v_exp_f32_e32 v205, v204
; __device__ __forceinline__ u32x4 pack8(f32x4 a, f32x4 b) { u32x4 w; w.x = pk2(a[0], a[1]); w.y = pk2(a[2], a[3]); w.z = pk2(b[0], b[1]); w.w = pk2(b[2], b[3]); return w; }
;     __device__ __forceinline__ void operator()(const Acc& acc, const pg8::Unit& u, int wid) const {
;     ...
;                 for (int mm = 0; mm < 2; ++mm) { const int m = 2 * mp + mm, row = row0 + ai * 128 + m * 16;
;                     const float sc = __builtin_amdgcn_rsqf(scv[mm] * (1.f / 1024.f) + EPS);
;                     const f32x4 pa = (rq[mm][0] + rq[mm][1]) + (rq[mm][2] + rq[mm][3]);
;                     const float rg = __builtin_amdgcn_rsqf(((pa[0] + pa[1]) + (pa[2] + pa[3])) * (1.f / 512.f) + EPS);
; #pragma unroll
;                     for (int bj = 0; bj < 2; ++bj) {
;                         const u32x4 w = ov[mm][bj];
;                         f32x4 o0 = (f32x4){bflo(w.x), bfhi(w.x), bflo(w.y), bfhi(w.y)}, o1 = (f32x4){bflo(w.z), bfhi(w.z), bflo(w.w), bfhi(w.w)};
;                         f32x4 a0 = acc[ai][bj][m][0] * sc, a1 = acc[ai][bj][m][1] * sc;
; #pragma unroll
;                         for (int e = 0; e < 4; ++e) { a0[e] = a0[e] * __builtin_amdgcn_rcpf(1.f + __builtin_amdgcn_exp2f(-1.4426950408889634f * a0[e])); a1[e] = a1[e] * __builtin_amdgcn_rcpf(1.f + __builtin_amdgcn_exp2f(-1.4426950408889634f * a1[e])); }
;                         o0 = a0 * o0 * g4[bj][0] * rg; o1 = a1 * o1 * g4[bj][1] * rg;
;                         *(u32x4*)(Y + (size_t)row * 2048 + col0 + bj * 128) = pack8(o0, o1);
;                     } }
	v_rcp_f32_e32 v204, v199
	v_add_f32_e32 v199, 1.0, v201
	v_mul_f32_e32 v201, 0xbfb8aa3b, v134
	v_exp_f32_e32 v201, v201
	v_mul_f32_e32 v207, 0xbfb8aa3b, v130
	v_exp_f32_e32 v207, v207
	v_rcp_f32_e32 v206, v199
	v_add_f32_e32 v201, 1.0, v201
	v_add_f32_e32 v199, 1.0, v205
	v_rcp_f32_e32 v208, v201
	v_add_f32_e32 v201, 1.0, v207
	v_mul_f32_e32 v207, 0xbfb8aa3b, v135
	v_rcp_f32_e32 v205, v199
	v_mul_f32_e32 v199, 0xbfb8aa3b, v129
	v_exp_f32_e32 v207, v207
	v_mul_f32_e32 v209, 0xbfb8aa3b, v131
	v_exp_f32_e32 v199, v199
	v_exp_f32_e32 v211, v209
	v_rcp_f32_e32 v210, v201
	v_add_f32_e32 v201, 1.0, v207
	v_add_f32_e32 v199, 1.0, v199
	v_rcp_f32_e32 v209, v201
	v_add_f32_e32 v201, 1.0, v211
	v_rcp_f32_e32 v211, v201
	v_rcp_f32_e32 v207, v199
	v_cvt_pk_bf16_f32 v136, v140, v141
	v_lshl_add_u64 v[140:141], s[36:37], 0, v[224:225]
	v_cvt_pk_bf16_f32 v137, v142, v143
	v_cvt_pk_bf16_f32 v138, v138, v139
	v_cvt_pk_bf16_f32 v139, v202, v203
	v_lshl_add_u64 v[140:141], v[140:141], 0, v[184:185]
	global_store_dwordx4 v[140:141], v[136:139], off
	v_lshlrev_b32_e32 v142, 16, v222
	v_and_b32_e32 v143, 0xffff0000, v222
	v_lshlrev_b32_e32 v136, 16, v220
	v_and_b32_e32 v137, 0xffff0000, v220
	v_lshlrev_b32_e32 v138, 16, v221
	v_and_b32_e32 v139, 0xffff0000, v221
	v_lshlrev_b32_e32 v202, 16, v223
	v_and_b32_e32 v203, 0xffff0000, v223
	v_pk_mul_f32 v[134:135], v[134:135], v[208:209]
	v_pk_mul_f32 v[132:133], v[132:133], v[204:205]
	v_pk_mul_f32 v[130:131], v[130:131], v[210:211]
	v_pk_mul_f32 v[128:129], v[128:129], v[206:207]
	v_pk_mul_f32 v[132:133], v[132:133], v[136:137]
	v_pk_mul_f32 v[134:135], v[134:135], v[138:139]
	v_pk_mul_f32 v[128:129], v[128:129], v[142:143]
	v_pk_mul_f32 v[130:131], v[130:131], v[202:203]
	v_pk_mul_f32 v[134:135], v[58:59], v[134:135]
	v_pk_mul_f32 v[132:133], v[56:57], v[132:133]
	v_pk_mul_f32 v[130:131], v[50:51], v[130:131]
	v_pk_mul_f32 v[128:129], v[48:49], v[128:129]
	v_pk_mul_f32 v[134:135], v[200:201], v[134:135] op_sel_hi:[0,1]
	v_pk_mul_f32 v[132:133], v[200:201], v[132:133] op_sel_hi:[0,1]
	v_pk_mul_f32 v[136:137], v[200:201], v[130:131] op_sel_hi:[0,1]
	v_pk_mul_f32 v[130:131], v[200:201], v[128:129] op_sel_hi:[0,1]
	v_cvt_pk_bf16_f32 v128, v132, v133
	v_cvt_pk_bf16_f32 v129, v134, v135
	v_cvt_pk_bf16_f32 v130, v130, v131
	v_cvt_pk_bf16_f32 v131, v136, v137
	global_store_dwordx4 v[140:141], v[128:131], off offset:256
	v_pk_add_f32 v[132:133], v[154:155], v[158:159]
	v_pk_add_f32 v[136:137], v[152:153], v[156:157]
	v_fmamk_f32 v128, v187, 0x3a800000, v198
	v_rsq_f32_e32 v134, v128
	v_pk_add_f32 v[128:129], v[166:167], v[162:163]
	v_pk_add_f32 v[130:131], v[164:165], v[160:161]
	v_pk_add_f32 v[128:129], v[128:129], v[132:133]
	v_pk_add_f32 v[130:131], v[130:131], v[136:137]
	v_pk_mul_f32 v[124:125], v[124:125], v[134:135] op_sel_hi:[1,0]
	v_pk_mov_b32 v[132:133], v[130:131], v[128:129] op_sel:[1,0]
	v_mov_b32_e32 v131, v129
	v_pk_add_f32 v[128:129], v[132:133], v[130:131]
	v_pk_mul_f32 v[120:121], v[120:121], v[134:135] op_sel_hi:[1,0]
	v_add_f32_e32 v128, v128, v129
	v_mul_f32_e32 v129, 0xbfb8aa3b, v124
	v_exp_f32_e32 v129, v129
	v_pk_mul_f32 v[126:127], v[126:127], v[134:135] op_sel_hi:[1,0]
	v_pk_mul_f32 v[122:123], v[122:123], v[134:135] op_sel_hi:[1,0]
	v_mul_f32_e32 v135, 0xbfb8aa3b, v120
	v_exp_f32_e32 v135, v135
	v_add_f32_e32 v129, 1.0, v129
	v_mul_f32_e32 v140, 0xbfb8aa3b, v125
	v_exp_f32_e32 v141, v140
	v_rcp_f32_e32 v140, v129
	v_add_f32_e32 v129, 1.0, v135
	v_mul_f32_e32 v135, 0xbfb8aa3b, v126
	v_exp_f32_e32 v135, v135
	v_mul_f32_e32 v143, 0xbfb8aa3b, v122
	v_exp_f32_e32 v143, v143
	v_lshlrev_b32_e32 v130, 16, v148
	v_add_f32_e32 v135, 1.0, v135
	v_and_b32_e32 v131, 0xffff0000, v148
	v_rcp_f32_e32 v142, v129
	v_add_f32_e32 v129, 1.0, v141
	v_rcp_f32_e32 v148, v135
	v_add_f32_e32 v135, 1.0, v143
	v_mul_f32_e32 v143, 0xbfb8aa3b, v127
	v_lshlrev_b32_e32 v132, 16, v149
	v_and_b32_e32 v133, 0xffff0000, v149
	v_rcp_f32_e32 v141, v129
	v_mul_f32_e32 v129, 0xbfb8aa3b, v121
	v_exp_f32_e32 v143, v143
	v_mul_f32_e32 v149, 0xbfb8aa3b, v123
	v_lshlrev_b32_e32 v138, 16, v151
	v_and_b32_e32 v139, 0xffff0000, v151
	v_exp_f32_e32 v129, v129
	v_exp_f32_e32 v151, v149
	v_lshlrev_b32_e32 v136, 16, v150
	v_and_b32_e32 v137, 0xffff0000, v150
	v_rcp_f32_e32 v150, v135
	v_add_f32_e32 v135, 1.0, v143
	v_add_f32_e32 v129, 1.0, v129
	v_rcp_f32_e32 v149, v135
	v_add_f32_e32 v135, 1.0, v151
	v_rcp_f32_e32 v151, v135
	v_rcp_f32_e32 v143, v129
	v_fmamk_f32 v128, v128, 0x3b000000, v198
	v_rsq_f32_e32 v128, v128
	v_pk_mul_f32 v[126:127], v[126:127], v[148:149]
	v_pk_mul_f32 v[124:125], v[124:125], v[140:141]
	v_pk_mul_f32 v[122:123], v[122:123], v[150:151]
	v_pk_mul_f32 v[120:121], v[120:121], v[142:143]
	v_pk_mul_f32 v[124:125], v[124:125], v[130:131]
	v_pk_mul_f32 v[126:127], v[126:127], v[132:133]
	v_pk_mul_f32 v[120:121], v[120:121], v[136:137]
	v_pk_mul_f32 v[122:123], v[122:123], v[138:139]
	v_pk_mul_f32 v[126:127], v[66:67], v[126:127]
	v_pk_mul_f32 v[124:125], v[64:65], v[124:125]
	v_pk_mul_f32 v[122:123], v[70:71], v[122:123]
	v_pk_mul_f32 v[120:121], v[68:69], v[120:121]
	v_pk_mul_f32 v[116:117], v[116:117], v[134:135] op_sel_hi:[1,0]
	v_pk_mul_f32 v[126:127], v[128:129], v[126:127] op_sel_hi:[0,1]
	v_pk_mul_f32 v[124:125], v[128:129], v[124:125] op_sel_hi:[0,1]
	v_pk_mul_f32 v[130:131], v[128:129], v[122:123] op_sel_hi:[0,1]
	v_pk_mul_f32 v[122:123], v[128:129], v[120:121] op_sel_hi:[0,1]
	v_mul_f32_e32 v129, 0xbfb8aa3b, v116
	v_pk_mul_f32 v[112:113], v[112:113], v[134:135] op_sel_hi:[1,0]
	v_exp_f32_e32 v129, v129
	v_pk_mul_f32 v[118:119], v[118:119], v[134:135] op_sel_hi:[1,0]
	v_pk_mul_f32 v[114:115], v[114:115], v[134:135] op_sel_hi:[1,0]
; __device__ __forceinline__ u32x4 pack8(f32x4 a, f32x4 b) { u32x4 w; w.x = pk2(a[0], a[1]); w.y = pk2(a[2], a[3]); w.z = pk2(b[0], b[1]); w.w = pk2(b[2], b[3]); return w; }
;     __device__ __forceinline__ void operator()(const Acc& acc, const pg8::Unit& u, int wid) const {
;     ...
;                 float scv[2]; f32x4 rq[2][4]; u32x4 ov[2][2];
; #pragma unroll
;                 for (int mm = 0; mm < 2; ++mm) { const int row = row0 + ai * 128 + (2 * mp + mm) * 16;
;                     scv[mm] = ssq[row];
;                     const f32x4* rp = (const f32x4*)(rssq + (size_t)row * 64 + head * 16);
; #pragma unroll
;                     for (int i = 0; i < 4; ++i) rq[mm][i] = rp[i];
; #pragma unroll
;                     for (int bj = 0; bj < 2; ++bj) ov[mm][bj] = *(const u32x4*)(Y + (size_t)row * 2048 + col0 + bj * 128); }
; #pragma unroll
;                 for (int mm = 0; mm < 2; ++mm) { const int m = 2 * mp + mm, row = row0 + ai * 128 + m * 16;
;                     const float sc = __builtin_amdgcn_rsqf(scv[mm] * (1.f / 1024.f) + EPS);
;                     const f32x4 pa = (rq[mm][0] + rq[mm][1]) + (rq[mm][2] + rq[mm][3]);
;                     const float rg = __builtin_amdgcn_rsqf(((pa[0] + pa[1]) + (pa[2] + pa[3])) * (1.f / 512.f) + EPS);
; #pragma unroll
;                     for (int bj = 0; bj < 2; ++bj) {
;                         const u32x4 w = ov[mm][bj];
;                         f32x4 o0 = (f32x4){bflo(w.x), bfhi(w.x), bflo(w.y), bfhi(w.y)}, o1 = (f32x4){bflo(w.z), bfhi(w.z), bflo(w.w), bfhi(w.w)};
;                         f32x4 a0 = acc[ai][bj][m][0] * sc, a1 = acc[ai][bj][m][1] * sc;
; #pragma unroll
;                         for (int e = 0; e < 4; ++e) { a0[e] = a0[e] * __builtin_amdgcn_rcpf(1.f + __builtin_amdgcn_exp2f(-1.4426950408889634f * a0[e])); a1[e] = a1[e] * __builtin_amdgcn_rcpf(1.f + __builtin_amdgcn_exp2f(-1.4426950408889634f * a1[e])); }
;                         o0 = a0 * o0 * g4[bj][0] * rg; o1 = a1 * o1 * g4[bj][1] * rg;
;                         *(u32x4*)(Y + (size_t)row * 2048 + col0 + bj * 128) = pack8(o0, o1);
;                     } }
	v_mul_f32_e32 v134, 0xbfb8aa3b, v112
	v_exp_f32_e32 v135, v134
	v_mul_f32_e32 v134, 0xbfb8aa3b, v117
	v_exp_f32_e32 v143, v134
	v_add_f32_e32 v129, 1.0, v129
	v_rcp_f32_e32 v134, v129
	v_add_f32_e32 v129, 1.0, v135
	v_rcp_f32_e32 v142, v129
	v_add_f32_e32 v129, 1.0, v143
	v_mul_f32_e32 v143, 0xbfb8aa3b, v118
	v_cvt_pk_bf16_f32 v121, v126, v127
	v_lshlrev_b32_e32 v126, 16, v144
	v_and_b32_e32 v127, 0xffff0000, v144
	v_exp_f32_e32 v143, v143
	v_mul_f32_e32 v144, 0xbfb8aa3b, v114
	v_lshlrev_b32_e32 v136, 16, v145
	v_and_b32_e32 v137, 0xffff0000, v145
	v_exp_f32_e32 v145, v144
	v_add_f32_e32 v143, 1.0, v143
	v_rcp_f32_e32 v144, v143
	v_lshlrev_b32_e32 v138, 16, v146
	v_add_f32_e32 v143, 1.0, v145
	v_mul_f32_e32 v145, 0xbfb8aa3b, v119
	v_and_b32_e32 v139, 0xffff0000, v146
	v_rcp_f32_e32 v135, v129
	v_mul_f32_e32 v129, 0xbfb8aa3b, v113
	v_exp_f32_e32 v145, v145
	v_mul_f32_e32 v146, 0xbfb8aa3b, v115
	v_lshlrev_b32_e32 v140, 16, v147
	v_and_b32_e32 v141, 0xffff0000, v147
	v_exp_f32_e32 v129, v129
	v_exp_f32_e32 v147, v146
	v_rcp_f32_e32 v146, v143
	v_add_f32_e32 v143, 1.0, v145
	v_add_f32_e32 v129, 1.0, v129
	v_rcp_f32_e32 v145, v143
	v_add_f32_e32 v143, 1.0, v147
	v_rcp_f32_e32 v147, v143
	v_rcp_f32_e32 v143, v129
	v_cvt_pk_bf16_f32 v120, v124, v125
	v_lshl_add_u64 v[124:125], s[36:37], 0, v[192:193]
	v_pk_mul_f32 v[118:119], v[118:119], v[144:145]
	v_pk_mul_f32 v[116:117], v[116:117], v[134:135]
	v_pk_mul_f32 v[114:115], v[114:115], v[146:147]
	v_pk_mul_f32 v[112:113], v[112:113], v[142:143]
	v_cvt_pk_bf16_f32 v122, v122, v123
	v_cvt_pk_bf16_f32 v123, v130, v131
	v_lshl_add_u64 v[124:125], v[124:125], 0, v[184:185]
	v_pk_mul_f32 v[116:117], v[116:117], v[126:127]
	v_pk_mul_f32 v[118:119], v[118:119], v[136:137]
	v_pk_mul_f32 v[112:113], v[112:113], v[138:139]
	v_pk_mul_f32 v[114:115], v[114:115], v[140:141]
	global_store_dwordx4 v[124:125], v[120:123], off
	v_pk_mul_f32 v[118:119], v[58:59], v[118:119]
	v_pk_mul_f32 v[116:117], v[56:57], v[116:117]
	v_or_b32_e32 v120, 32, v186
	v_pk_mul_f32 v[114:115], v[50:51], v[114:115]
	v_pk_mul_f32 v[112:113], v[48:49], v[112:113]
	v_ashrrev_i32_e32 v121, 31, v120
	v_pk_mul_f32 v[118:119], v[128:129], v[118:119] op_sel_hi:[0,1]
	v_pk_mul_f32 v[116:117], v[128:129], v[116:117] op_sel_hi:[0,1]
	v_pk_mul_f32 v[126:127], v[128:129], v[114:115] op_sel_hi:[0,1]
	v_pk_mul_f32 v[114:115], v[128:129], v[112:113] op_sel_hi:[0,1]
	v_lshlrev_b64 v[162:163], 12, v[120:121]
	v_cvt_pk_bf16_f32 v112, v116, v117
	v_cvt_pk_bf16_f32 v113, v118, v119
	v_cvt_pk_bf16_f32 v114, v114, v115
	v_cvt_pk_bf16_f32 v115, v126, v127
	v_lshl_add_u64 v[122:123], v[190:191], 0, v[162:163]
	global_store_dwordx4 v[124:125], v[112:115], off offset:256
	global_load_dwordx4 v[130:133], v[122:123], off
	s_nop 0
	v_lshlrev_b64 v[112:113], 8, v[120:121]
	v_lshl_add_u64 v[112:113], s[20:21], 0, v[112:113]
	global_load_dword v164, v[188:189], off offset:128
	global_load_dwordx4 v[134:137], v[112:113], off
	global_load_dwordx4 v[138:141], v[112:113], off offset:16
	global_load_dwordx4 v[142:145], v[112:113], off offset:32
	global_load_dwordx4 v[146:149], v[112:113], off offset:48
	global_load_dwordx4 v[150:153], v[122:123], off offset:256
	global_load_dword v165, v[188:189], off offset:192
	v_or_b32_e32 v112, 48, v186
	v_ashrrev_i32_e32 v113, 31, v112
	v_lshlrev_b64 v[114:115], 8, v[112:113]
	v_lshl_add_u64 v[114:115], s[20:21], 0, v[114:115]
	global_load_dwordx4 v[154:157], v[114:115], off
	global_load_dwordx4 v[158:161], v[114:115], off offset:16
	global_load_dwordx4 v[120:123], v[114:115], off offset:32
	global_load_dwordx4 v[124:127], v[114:115], off offset:48
	v_lshlrev_b64 v[128:129], 12, v[112:113]
	v_lshl_add_u64 v[112:113], v[190:191], 0, v[128:129]
	global_load_dwordx4 v[116:119], v[112:113], off
	s_nop 0
	global_load_dwordx4 v[112:115], v[112:113], off offset:256
	s_waitcnt vmcnt(0) lgkmcnt(0)
	v_fmamk_f32 v164, v164, 0x3a800000, v198
	v_rsq_f32_e32 v164, v164
	v_pk_add_f32 v[136:137], v[136:137], v[140:141]
	v_pk_add_f32 v[134:135], v[134:135], v[138:139]
	v_pk_add_f32 v[138:139], v[144:145], v[148:149]
	v_pk_add_f32 v[140:141], v[142:143], v[146:147]
	v_pk_add_f32 v[136:137], v[136:137], v[138:139]
	v_pk_add_f32 v[134:135], v[134:135], v[140:141]
	v_pk_mul_f32 v[108:109], v[108:109], v[164:165] op_sel_hi:[1,0]
	v_pk_mov_b32 v[138:139], v[134:135], v[136:137] op_sel:[1,0]
	v_mov_b32_e32 v135, v137
	v_pk_add_f32 v[134:135], v[138:139], v[134:135]
	v_pk_mul_f32 v[104:105], v[104:105], v[164:165] op_sel_hi:[1,0]
	v_add_f32_e32 v134, v134, v135
	v_mul_f32_e32 v135, 0xbfb8aa3b, v108
	v_exp_f32_e32 v135, v135
	v_mul_f32_e32 v140, 0xbfb8aa3b, v104
	v_exp_f32_e32 v141, v140
	v_mul_f32_e32 v140, 0xbfb8aa3b, v109
	v_exp_f32_e32 v143, v140
	v_add_f32_e32 v135, 1.0, v135
	v_pk_mul_f32 v[110:111], v[110:111], v[164:165] op_sel_hi:[1,0]
	v_rcp_f32_e32 v140, v135
	v_add_f32_e32 v135, 1.0, v141
	v_pk_mul_f32 v[106:107], v[106:107], v[164:165] op_sel_hi:[1,0]
	v_rcp_f32_e32 v142, v135
	v_add_f32_e32 v135, 1.0, v143
	v_mul_f32_e32 v143, 0xbfb8aa3b, v110
	v_exp_f32_e32 v143, v143
	v_mul_f32_e32 v144, 0xbfb8aa3b, v106
	v_exp_f32_e32 v145, v144
	v_rcp_f32_e32 v141, v135
	v_add_f32_e32 v143, 1.0, v143
	v_rcp_f32_e32 v144, v143
	v_add_f32_e32 v143, 1.0, v145
	v_mul_f32_e32 v145, 0xbfb8aa3b, v111
	v_mul_f32_e32 v135, 0xbfb8aa3b, v105
	v_exp_f32_e32 v145, v145
	v_mul_f32_e32 v146, 0xbfb8aa3b, v107
	v_exp_f32_e32 v135, v135
	v_exp_f32_e32 v147, v146
	v_rcp_f32_e32 v146, v143
	v_add_f32_e32 v143, 1.0, v145
	v_add_f32_e32 v135, 1.0, v135
	v_rcp_f32_e32 v145, v143
	v_add_f32_e32 v143, 1.0, v147
	v_rcp_f32_e32 v147, v143
	v_rcp_f32_e32 v143, v135
; __device__ __forceinline__ u32x4 pack8(f32x4 a, f32x4 b) { u32x4 w; w.x = pk2(a[0], a[1]); w.y = pk2(a[2], a[3]); w.z = pk2(b[0], b[1]); w.w = pk2(b[2], b[3]); return w; }
;     __device__ __forceinline__ void operator()(const Acc& acc, const pg8::Unit& u, int wid) const {
;     ...
;                 for (int mm = 0; mm < 2; ++mm) { const int m = 2 * mp + mm, row = row0 + ai * 128 + m * 16;
;                     const float sc = __builtin_amdgcn_rsqf(scv[mm] * (1.f / 1024.f) + EPS);
;                     const f32x4 pa = (rq[mm][0] + rq[mm][1]) + (rq[mm][2] + rq[mm][3]);
;                     const float rg = __builtin_amdgcn_rsqf(((pa[0] + pa[1]) + (pa[2] + pa[3])) * (1.f / 512.f) + EPS);
; #pragma unroll
;                     for (int bj = 0; bj < 2; ++bj) {
;                         const u32x4 w = ov[mm][bj];
;                         f32x4 o0 = (f32x4){bflo(w.x), bfhi(w.x), bflo(w.y), bfhi(w.y)}, o1 = (f32x4){bflo(w.z), bfhi(w.z), bflo(w.w), bfhi(w.w)};
;                         f32x4 a0 = acc[ai][bj][m][0] * sc, a1 = acc[ai][bj][m][1] * sc;
; #pragma unroll
;                         for (int e = 0; e < 4; ++e) { a0[e] = a0[e] * __builtin_amdgcn_rcpf(1.f + __builtin_amdgcn_exp2f(-1.4426950408889634f * a0[e])); a1[e] = a1[e] * __builtin_amdgcn_rcpf(1.f + __builtin_amdgcn_exp2f(-1.4426950408889634f * a1[e])); }
;                         o0 = a0 * o0 * g4[bj][0] * rg; o1 = a1 * o1 * g4[bj][1] * rg;
;                         *(u32x4*)(Y + (size_t)row * 2048 + col0 + bj * 128) = pack8(o0, o1);
;                     } }
	v_fmamk_f32 v134, v134, 0x3b000000, v198
	v_rsq_f32_e32 v134, v134
	v_lshlrev_b32_e32 v136, 16, v130
	v_and_b32_e32 v137, 0xffff0000, v130
	v_lshlrev_b32_e32 v130, 16, v131
	v_and_b32_e32 v131, 0xffff0000, v131
	v_lshlrev_b32_e32 v138, 16, v132
	v_and_b32_e32 v139, 0xffff0000, v132
	v_lshlrev_b32_e32 v132, 16, v133
	v_and_b32_e32 v133, 0xffff0000, v133
	v_pk_mul_f32 v[110:111], v[110:111], v[144:145]
	v_pk_mul_f32 v[108:109], v[108:109], v[140:141]
	v_pk_mul_f32 v[106:107], v[106:107], v[146:147]
	v_pk_mul_f32 v[104:105], v[104:105], v[142:143]
	v_pk_mul_f32 v[102:103], v[102:103], v[164:165] op_sel_hi:[1,0]
	v_pk_mul_f32 v[108:109], v[108:109], v[136:137]
	v_pk_mul_f32 v[110:111], v[110:111], v[130:131]
	v_pk_mul_f32 v[104:105], v[104:105], v[138:139]
	v_pk_mul_f32 v[106:107], v[106:107], v[132:133]
	v_pk_mul_f32 v[98:99], v[98:99], v[164:165] op_sel_hi:[1,0]
	v_pk_mul_f32 v[96:97], v[96:97], v[164:165] op_sel_hi:[1,0]
	v_mul_f32_e32 v137, 0xbfb8aa3b, v102
	v_pk_mul_f32 v[110:111], v[66:67], v[110:111]
	v_pk_mul_f32 v[108:109], v[64:65], v[108:109]
	v_pk_mul_f32 v[106:107], v[70:71], v[106:107]
	v_pk_mul_f32 v[104:105], v[68:69], v[104:105]
	v_pk_mul_f32 v[100:101], v[100:101], v[164:165] op_sel_hi:[1,0]
	v_mul_f32_e32 v133, 0xbfb8aa3b, v96
	v_exp_f32_e32 v137, v137
	v_mul_f32_e32 v138, 0xbfb8aa3b, v98
	v_pk_mul_f32 v[110:111], v[134:135], v[110:111] op_sel_hi:[0,1]
	v_pk_mul_f32 v[108:109], v[134:135], v[108:109] op_sel_hi:[0,1]
	v_pk_mul_f32 v[130:131], v[134:135], v[106:107] op_sel_hi:[0,1]
	v_pk_mul_f32 v[106:107], v[134:135], v[104:105] op_sel_hi:[0,1]
	v_exp_f32_e32 v133, v133
	v_mul_f32_e32 v135, 0xbfb8aa3b, v101
	v_exp_f32_e32 v139, v138
	v_exp_f32_e32 v135, v135
	v_add_f32_e32 v137, 1.0, v137
	v_add_f32_e32 v133, 1.0, v133
	v_rcp_f32_e32 v138, v137
	v_add_f32_e32 v137, 1.0, v139
	v_mul_f32_e32 v139, 0xbfb8aa3b, v103
	v_mul_f32_e32 v132, 0xbfb8aa3b, v100
	v_rcp_f32_e32 v136, v133
	v_add_f32_e32 v133, 1.0, v135
	v_mul_f32_e32 v135, 0xbfb8aa3b, v97
	v_exp_f32_e32 v139, v139
	v_mul_f32_e32 v140, 0xbfb8aa3b, v99
	v_exp_f32_e32 v132, v132
	v_exp_f32_e32 v135, v135
	v_exp_f32_e32 v141, v140
	v_rcp_f32_e32 v140, v137
	v_add_f32_e32 v137, 1.0, v139
	v_add_f32_e32 v132, 1.0, v132
	v_add_f32_e32 v135, 1.0, v135
	v_rcp_f32_e32 v139, v137
	v_add_f32_e32 v137, 1.0, v141
	v_rcp_f32_e32 v132, v132
	v_rcp_f32_e32 v133, v133
	v_rcp_f32_e32 v141, v137
	v_rcp_f32_e32 v137, v135
	v_cvt_pk_bf16_f32 v104, v108, v109
	v_lshl_add_u64 v[108:109], s[36:37], 0, v[162:163]
	v_cvt_pk_bf16_f32 v105, v110, v111
	v_cvt_pk_bf16_f32 v106, v106, v107
	v_cvt_pk_bf16_f32 v107, v130, v131
	v_lshl_add_u64 v[108:109], v[108:109], 0, v[184:185]
	global_store_dwordx4 v[108:109], v[104:107], off
	v_lshlrev_b32_e32 v110, 16, v152
	v_and_b32_e32 v111, 0xffff0000, v152
	v_lshlrev_b32_e32 v104, 16, v150
	v_and_b32_e32 v105, 0xffff0000, v150
	v_lshlrev_b32_e32 v106, 16, v151
	v_and_b32_e32 v107, 0xffff0000, v151
	v_lshlrev_b32_e32 v130, 16, v153
	v_and_b32_e32 v131, 0xffff0000, v153
	v_pk_mul_f32 v[102:103], v[102:103], v[138:139]
	v_pk_mul_f32 v[100:101], v[100:101], v[132:133]
	v_pk_mul_f32 v[98:99], v[98:99], v[140:141]
	v_pk_mul_f32 v[96:97], v[96:97], v[136:137]
	v_pk_mul_f32 v[100:101], v[100:101], v[104:105]
	v_pk_mul_f32 v[102:103], v[102:103], v[106:107]
	v_pk_mul_f32 v[96:97], v[96:97], v[110:111]
	v_pk_mul_f32 v[98:99], v[98:99], v[130:131]
	v_pk_mul_f32 v[102:103], v[58:59], v[102:103]
	v_pk_mul_f32 v[100:101], v[56:57], v[100:101]
	v_pk_mul_f32 v[98:99], v[50:51], v[98:99]
	v_pk_mul_f32 v[96:97], v[48:49], v[96:97]
	v_pk_mul_f32 v[102:103], v[134:135], v[102:103] op_sel_hi:[0,1]
	v_pk_mul_f32 v[100:101], v[134:135], v[100:101] op_sel_hi:[0,1]
	v_pk_mul_f32 v[104:105], v[134:135], v[98:99] op_sel_hi:[0,1]
	v_pk_mul_f32 v[98:99], v[134:135], v[96:97] op_sel_hi:[0,1]
	v_cvt_pk_bf16_f32 v96, v100, v101
	v_cvt_pk_bf16_f32 v97, v102, v103
	v_cvt_pk_bf16_f32 v98, v98, v99
	v_cvt_pk_bf16_f32 v99, v104, v105
	global_store_dwordx4 v[108:109], v[96:99], off offset:256
	v_pk_add_f32 v[100:101], v[154:155], v[158:159]
	v_pk_add_f32 v[102:103], v[122:123], v[126:127]
	v_pk_add_f32 v[98:99], v[156:157], v[160:161]
	v_pk_add_f32 v[104:105], v[120:121], v[124:125]
	v_fmamk_f32 v96, v165, 0x3a800000, v198
	v_pk_add_f32 v[98:99], v[98:99], v[102:103]
	v_pk_add_f32 v[100:101], v[100:101], v[104:105]
	v_rsq_f32_e32 v96, v96
	v_pk_mov_b32 v[102:103], v[100:101], v[98:99] op_sel:[1,0]
	v_mov_b32_e32 v101, v99
	v_pk_add_f32 v[98:99], v[102:103], v[100:101]
	v_lshlrev_b32_e32 v100, 16, v116
	v_add_f32_e32 v97, v98, v99
	v_fmamk_f32 v97, v97, 0x3b000000, v198
	v_pk_mul_f32 v[92:93], v[92:93], v[96:97] op_sel_hi:[1,0]
	v_rsq_f32_e32 v98, v97
	v_mul_f32_e32 v97, 0xbfb8aa3b, v92
	v_exp_f32_e32 v97, v97
	v_mul_f32_e32 v108, 0xbfb8aa3b, v93
	v_exp_f32_e32 v109, v108
	v_and_b32_e32 v101, 0xffff0000, v116
	v_pk_mul_f32 v[88:89], v[88:89], v[96:97] op_sel_hi:[1,0]
	v_pk_mul_f32 v[94:95], v[94:95], v[96:97] op_sel_hi:[1,0]
	v_mul_f32_e32 v99, 0xbfb8aa3b, v88
	v_exp_f32_e32 v99, v99
	v_pk_mul_f32 v[90:91], v[90:91], v[96:97] op_sel_hi:[1,0]
	v_add_f32_e32 v97, 1.0, v97
	v_rcp_f32_e32 v108, v97
	v_add_f32_e32 v97, 1.0, v99
	v_mul_f32_e32 v99, 0xbfb8aa3b, v94
	v_exp_f32_e32 v99, v99
	v_mul_f32_e32 v111, 0xbfb8aa3b, v90
	v_exp_f32_e32 v111, v111
	v_rcp_f32_e32 v110, v97
	v_add_f32_e32 v97, 1.0, v109
	v_rcp_f32_e32 v109, v97
	v_mul_f32_e32 v97, 0xbfb8aa3b, v89
	v_add_f32_e32 v99, 1.0, v99
	v_exp_f32_e32 v97, v97
	v_rcp_f32_e32 v116, v99
	v_add_f32_e32 v99, 1.0, v111
	v_mul_f32_e32 v111, 0xbfb8aa3b, v95
	v_lshlrev_b32_e32 v102, 16, v117
	v_and_b32_e32 v103, 0xffff0000, v117
	v_exp_f32_e32 v111, v111
; __device__ __forceinline__ u32x4 pack8(f32x4 a, f32x4 b) { u32x4 w; w.x = pk2(a[0], a[1]); w.y = pk2(a[2], a[3]); w.z = pk2(b[0], b[1]); w.w = pk2(b[2], b[3]); return w; }
;     __device__ __forceinline__ void operator()(const Acc& acc, const pg8::Unit& u, int wid) const {
;     ...
;                 float scv[2]; f32x4 rq[2][4]; u32x4 ov[2][2];
; #pragma unroll
;                 for (int mm = 0; mm < 2; ++mm) { const int row = row0 + ai * 128 + (2 * mp + mm) * 16;
;                     scv[mm] = ssq[row];
;                     const f32x4* rp = (const f32x4*)(rssq + (size_t)row * 64 + head * 16);
; #pragma unroll
;                     for (int i = 0; i < 4; ++i) rq[mm][i] = rp[i];
; #pragma unroll
;                     for (int bj = 0; bj < 2; ++bj) ov[mm][bj] = *(const u32x4*)(Y + (size_t)row * 2048 + col0 + bj * 128); }
; #pragma unroll
;                 for (int mm = 0; mm < 2; ++mm) { const int m = 2 * mp + mm, row = row0 + ai * 128 + m * 16;
;                     const float sc = __builtin_amdgcn_rsqf(scv[mm] * (1.f / 1024.f) + EPS);
;                     const f32x4 pa = (rq[mm][0] + rq[mm][1]) + (rq[mm][2] + rq[mm][3]);
;                     const float rg = __builtin_amdgcn_rsqf(((pa[0] + pa[1]) + (pa[2] + pa[3])) * (1.f / 512.f) + EPS);
; #pragma unroll
;                     for (int bj = 0; bj < 2; ++bj) {
;                         const u32x4 w = ov[mm][bj];
;                         f32x4 o0 = (f32x4){bflo(w.x), bfhi(w.x), bflo(w.y), bfhi(w.y)}, o1 = (f32x4){bflo(w.z), bfhi(w.z), bflo(w.w), bfhi(w.w)};
;                         f32x4 a0 = acc[ai][bj][m][0] * sc, a1 = acc[ai][bj][m][1] * sc;
; #pragma unroll
;                         for (int e = 0; e < 4; ++e) { a0[e] = a0[e] * __builtin_amdgcn_rcpf(1.f + __builtin_amdgcn_exp2f(-1.4426950408889634f * a0[e])); a1[e] = a1[e] * __builtin_amdgcn_rcpf(1.f + __builtin_amdgcn_exp2f(-1.4426950408889634f * a1[e])); }
;                         o0 = a0 * o0 * g4[bj][0] * rg; o1 = a1 * o1 * g4[bj][1] * rg;
;                         *(u32x4*)(Y + (size_t)row * 2048 + col0 + bj * 128) = pack8(o0, o1);
;                     } }
	v_mul_f32_e32 v117, 0xbfb8aa3b, v91
	v_lshlrev_b32_e32 v106, 16, v119
	v_and_b32_e32 v107, 0xffff0000, v119
	v_exp_f32_e32 v119, v117
	v_add_f32_e32 v97, 1.0, v97
	v_lshlrev_b32_e32 v104, 16, v118
	v_and_b32_e32 v105, 0xffff0000, v118
	v_rcp_f32_e32 v118, v99
	v_add_f32_e32 v99, 1.0, v111
	v_pk_mul_f32 v[84:85], v[84:85], v[96:97] op_sel_hi:[1,0]
	v_rcp_f32_e32 v117, v99
	v_add_f32_e32 v99, 1.0, v119
	v_rcp_f32_e32 v111, v97
	v_mul_f32_e32 v97, 0xbfb8aa3b, v84
	v_rcp_f32_e32 v119, v99
	v_exp_f32_e32 v97, v97
	v_pk_mul_f32 v[94:95], v[94:95], v[116:117]
	v_pk_mul_f32 v[92:93], v[92:93], v[108:109]
	v_pk_mul_f32 v[90:91], v[90:91], v[118:119]
	v_pk_mul_f32 v[88:89], v[88:89], v[110:111]
	v_pk_mul_f32 v[86:87], v[86:87], v[96:97] op_sel_hi:[1,0]
	v_pk_mul_f32 v[92:93], v[92:93], v[100:101]
	v_pk_mul_f32 v[94:95], v[94:95], v[102:103]
	v_pk_mul_f32 v[88:89], v[88:89], v[104:105]
	v_pk_mul_f32 v[90:91], v[90:91], v[106:107]
	v_pk_mul_f32 v[82:83], v[82:83], v[96:97] op_sel_hi:[1,0]
	v_pk_mul_f32 v[80:81], v[80:81], v[96:97] op_sel_hi:[1,0]
	v_mul_f32_e32 v103, 0xbfb8aa3b, v86
	v_pk_mul_f32 v[94:95], v[66:67], v[94:95]
	v_pk_mul_f32 v[92:93], v[64:65], v[92:93]
	v_pk_mul_f32 v[90:91], v[70:71], v[90:91]
	v_pk_mul_f32 v[88:89], v[68:69], v[88:89]
	v_add_f32_e32 v96, 1.0, v97
	v_mul_f32_e32 v97, 0xbfb8aa3b, v80
	v_exp_f32_e32 v103, v103
	v_mul_f32_e32 v104, 0xbfb8aa3b, v82
	v_pk_mul_f32 v[94:95], v[98:99], v[94:95] op_sel_hi:[0,1]
	v_pk_mul_f32 v[92:93], v[98:99], v[92:93] op_sel_hi:[0,1]
	v_pk_mul_f32 v[100:101], v[98:99], v[90:91] op_sel_hi:[0,1]
	v_pk_mul_f32 v[90:91], v[98:99], v[88:89] op_sel_hi:[0,1]
	v_exp_f32_e32 v97, v97
	v_mul_f32_e32 v99, 0xbfb8aa3b, v85
	v_exp_f32_e32 v105, v104
	v_exp_f32_e32 v99, v99
	v_add_f32_e32 v103, 1.0, v103
	v_add_f32_e32 v97, 1.0, v97
	v_rcp_f32_e32 v104, v103
	v_add_f32_e32 v103, 1.0, v105
	v_mul_f32_e32 v105, 0xbfb8aa3b, v87
	v_rcp_f32_e32 v102, v97
	v_add_f32_e32 v97, 1.0, v99
	v_mul_f32_e32 v99, 0xbfb8aa3b, v81
	v_exp_f32_e32 v105, v105
	v_mul_f32_e32 v106, 0xbfb8aa3b, v83
	v_exp_f32_e32 v99, v99
	v_exp_f32_e32 v107, v106
	v_rcp_f32_e32 v106, v103
	v_add_f32_e32 v103, 1.0, v105
	v_add_f32_e32 v99, 1.0, v99
	v_rcp_f32_e32 v105, v103
	v_add_f32_e32 v103, 1.0, v107
	v_rcp_f32_e32 v96, v96
	v_rcp_f32_e32 v97, v97
	v_rcp_f32_e32 v107, v103
	v_rcp_f32_e32 v103, v99
	v_cvt_pk_bf16_f32 v88, v92, v93
	v_lshl_add_u64 v[92:93], s[36:37], 0, v[128:129]
	v_cvt_pk_bf16_f32 v89, v94, v95
	v_cvt_pk_bf16_f32 v90, v90, v91
	v_cvt_pk_bf16_f32 v91, v100, v101
	v_lshl_add_u64 v[92:93], v[92:93], 0, v[184:185]
	global_store_dwordx4 v[92:93], v[88:91], off
	v_lshlrev_b32_e32 v94, 16, v114
	v_and_b32_e32 v95, 0xffff0000, v114
	v_lshlrev_b32_e32 v88, 16, v112
	v_and_b32_e32 v89, 0xffff0000, v112
	v_lshlrev_b32_e32 v90, 16, v113
	v_and_b32_e32 v91, 0xffff0000, v113
	v_lshlrev_b32_e32 v100, 16, v115
	v_and_b32_e32 v101, 0xffff0000, v115
	v_pk_mul_f32 v[86:87], v[86:87], v[104:105]
	v_pk_mul_f32 v[84:85], v[84:85], v[96:97]
	v_pk_mul_f32 v[82:83], v[82:83], v[106:107]
	v_pk_mul_f32 v[80:81], v[80:81], v[102:103]
	v_pk_mul_f32 v[84:85], v[84:85], v[88:89]
	v_pk_mul_f32 v[86:87], v[86:87], v[90:91]
	v_pk_mul_f32 v[80:81], v[80:81], v[94:95]
	v_pk_mul_f32 v[82:83], v[82:83], v[100:101]
	v_pk_mul_f32 v[86:87], v[58:59], v[86:87]
	v_pk_mul_f32 v[84:85], v[56:57], v[84:85]
	v_pk_mul_f32 v[82:83], v[50:51], v[82:83]
	v_pk_mul_f32 v[80:81], v[48:49], v[80:81]
	v_pk_mul_f32 v[86:87], v[98:99], v[86:87] op_sel_hi:[0,1]
	v_pk_mul_f32 v[84:85], v[98:99], v[84:85] op_sel_hi:[0,1]
	v_pk_mul_f32 v[88:89], v[98:99], v[82:83] op_sel_hi:[0,1]
	v_pk_mul_f32 v[82:83], v[98:99], v[80:81] op_sel_hi:[0,1]
	v_cvt_pk_bf16_f32 v80, v84, v85
	v_cvt_pk_bf16_f32 v81, v86, v87
	v_cvt_pk_bf16_f32 v82, v82, v83
	v_cvt_pk_bf16_f32 v83, v88, v89
	global_store_dwordx4 v[92:93], v[80:83], off offset:256
	s_nop 1
	v_add_u32_e32 v80, 0x80, v186
	v_ashrrev_i32_e32 v81, 31, v80
	v_lshlrev_b64 v[82:83], 8, v[80:81]
	v_lshl_add_u64 v[82:83], s[20:21], 0, v[82:83]
	global_load_dword v132, v[188:189], off offset:512
	global_load_dwordx4 v[94:97], v[82:83], off
	global_load_dwordx4 v[98:101], v[82:83], off offset:16
	global_load_dwordx4 v[102:105], v[82:83], off offset:32
	global_load_dwordx4 v[106:109], v[82:83], off offset:48
	v_lshlrev_b64 v[130:131], 12, v[80:81]
	v_lshl_add_u64 v[80:81], v[190:191], 0, v[130:131]
	global_load_dwordx4 v[110:113], v[80:81], off
	global_load_dword v133, v[188:189], off offset:576
	v_add_u32_e32 v82, 0x90, v186
	v_ashrrev_i32_e32 v83, 31, v82
	v_lshlrev_b64 v[84:85], 8, v[82:83]
	v_lshl_add_u64 v[84:85], s[20:21], 0, v[84:85]
	global_load_dwordx4 v[114:117], v[80:81], off offset:256
	global_load_dwordx4 v[118:121], v[84:85], off
	global_load_dwordx4 v[122:125], v[84:85], off offset:16
	global_load_dwordx4 v[88:91], v[84:85], off offset:32
	v_lshlrev_b64 v[92:93], 12, v[82:83]
	v_lshl_add_u64 v[80:81], v[190:191], 0, v[92:93]
	global_load_dwordx4 v[126:129], v[84:85], off offset:48
	s_nop 0
	global_load_dwordx4 v[84:87], v[80:81], off
	s_nop 0
	global_load_dwordx4 v[80:83], v[80:81], off offset:256
	s_waitcnt vmcnt(0) lgkmcnt(0)
; __device__ __forceinline__ u32x4 pack8(f32x4 a, f32x4 b) { u32x4 w; w.x = pk2(a[0], a[1]); w.y = pk2(a[2], a[3]); w.z = pk2(b[0], b[1]); w.w = pk2(b[2], b[3]); return w; }
;     __device__ __forceinline__ void operator()(const Acc& acc, const pg8::Unit& u, int wid) const {
;     ...
;                 for (int mm = 0; mm < 2; ++mm) { const int m = 2 * mp + mm, row = row0 + ai * 128 + m * 16;
;                     const float sc = __builtin_amdgcn_rsqf(scv[mm] * (1.f / 1024.f) + EPS);
;                     const f32x4 pa = (rq[mm][0] + rq[mm][1]) + (rq[mm][2] + rq[mm][3]);
;                     const float rg = __builtin_amdgcn_rsqf(((pa[0] + pa[1]) + (pa[2] + pa[3])) * (1.f / 512.f) + EPS);
; #pragma unroll
;                     for (int bj = 0; bj < 2; ++bj) {
;                         const u32x4 w = ov[mm][bj];
;                         f32x4 o0 = (f32x4){bflo(w.x), bfhi(w.x), bflo(w.y), bfhi(w.y)}, o1 = (f32x4){bflo(w.z), bfhi(w.z), bflo(w.w), bfhi(w.w)};
;                         f32x4 a0 = acc[ai][bj][m][0] * sc, a1 = acc[ai][bj][m][1] * sc;
; #pragma unroll
;                         for (int e = 0; e < 4; ++e) { a0[e] = a0[e] * __builtin_amdgcn_rcpf(1.f + __builtin_amdgcn_exp2f(-1.4426950408889634f * a0[e])); a1[e] = a1[e] * __builtin_amdgcn_rcpf(1.f + __builtin_amdgcn_exp2f(-1.4426950408889634f * a1[e])); }
;                         o0 = a0 * o0 * g4[bj][0] * rg; o1 = a1 * o1 * g4[bj][1] * rg;
;                         *(u32x4*)(Y + (size_t)row * 2048 + col0 + bj * 128) = pack8(o0, o1);
;                     } }
	v_fmamk_f32 v132, v132, 0x3a800000, v198
	v_rsq_f32_e32 v132, v132
	v_pk_add_f32 v[96:97], v[96:97], v[100:101]
	v_pk_add_f32 v[94:95], v[94:95], v[98:99]
	v_pk_add_f32 v[98:99], v[104:105], v[108:109]
	v_pk_add_f32 v[100:101], v[102:103], v[106:107]
	v_pk_add_f32 v[96:97], v[96:97], v[98:99]
	v_pk_add_f32 v[94:95], v[94:95], v[100:101]
	v_pk_mul_f32 v[76:77], v[76:77], v[132:133] op_sel_hi:[1,0]
	v_pk_mov_b32 v[98:99], v[94:95], v[96:97] op_sel:[1,0]
	v_mov_b32_e32 v95, v97
	v_pk_add_f32 v[94:95], v[98:99], v[94:95]
	v_pk_mul_f32 v[72:73], v[72:73], v[132:133] op_sel_hi:[1,0]
	v_add_f32_e32 v94, v94, v95
	v_mul_f32_e32 v95, 0xbfb8aa3b, v76
	v_exp_f32_e32 v95, v95
	v_mul_f32_e32 v104, 0xbfb8aa3b, v72
	v_exp_f32_e32 v105, v104
	v_mul_f32_e32 v104, 0xbfb8aa3b, v77
	v_exp_f32_e32 v107, v104
	v_add_f32_e32 v95, 1.0, v95
	v_pk_mul_f32 v[78:79], v[78:79], v[132:133] op_sel_hi:[1,0]
	v_rcp_f32_e32 v104, v95
	v_add_f32_e32 v95, 1.0, v105
	v_pk_mul_f32 v[74:75], v[74:75], v[132:133] op_sel_hi:[1,0]
	v_rcp_f32_e32 v106, v95
	v_add_f32_e32 v95, 1.0, v107
	v_mul_f32_e32 v107, 0xbfb8aa3b, v78
	v_exp_f32_e32 v107, v107
	v_mul_f32_e32 v108, 0xbfb8aa3b, v74
	v_exp_f32_e32 v109, v108
	v_lshlrev_b32_e32 v96, 16, v110
	v_add_f32_e32 v107, 1.0, v107
	v_rcp_f32_e32 v108, v107
	v_add_f32_e32 v107, 1.0, v109
	v_mul_f32_e32 v109, 0xbfb8aa3b, v79
	v_and_b32_e32 v97, 0xffff0000, v110
	v_rcp_f32_e32 v105, v95
	v_mul_f32_e32 v95, 0xbfb8aa3b, v73
	v_exp_f32_e32 v109, v109
	v_mul_f32_e32 v110, 0xbfb8aa3b, v75
	v_lshlrev_b32_e32 v98, 16, v111
	v_and_b32_e32 v99, 0xffff0000, v111
	v_exp_f32_e32 v95, v95
	v_exp_f32_e32 v111, v110
	v_rcp_f32_e32 v110, v107
	v_add_f32_e32 v107, 1.0, v109
	v_add_f32_e32 v95, 1.0, v95
	v_rcp_f32_e32 v109, v107
	v_add_f32_e32 v107, 1.0, v111
	v_rcp_f32_e32 v111, v107
	v_rcp_f32_e32 v107, v95
	v_fmamk_f32 v94, v94, 0x3b000000, v198
	v_rsq_f32_e32 v94, v94
	v_lshlrev_b32_e32 v100, 16, v112
	v_and_b32_e32 v101, 0xffff0000, v112
	v_lshlrev_b32_e32 v102, 16, v113
	v_and_b32_e32 v103, 0xffff0000, v113
	v_pk_mul_f32 v[78:79], v[78:79], v[108:109]
	v_pk_mul_f32 v[76:77], v[76:77], v[104:105]
	v_pk_mul_f32 v[74:75], v[74:75], v[110:111]
	v_pk_mul_f32 v[72:73], v[72:73], v[106:107]
	v_pk_mul_f32 v[76:77], v[76:77], v[96:97]
	v_pk_mul_f32 v[78:79], v[78:79], v[98:99]
	v_pk_mul_f32 v[72:73], v[72:73], v[100:101]
	v_pk_mul_f32 v[74:75], v[74:75], v[102:103]
	v_pk_mul_f32 v[78:79], v[66:67], v[78:79]
	v_pk_mul_f32 v[76:77], v[64:65], v[76:77]
	v_pk_mul_f32 v[74:75], v[70:71], v[74:75]
	v_pk_mul_f32 v[72:73], v[68:69], v[72:73]
	v_pk_mul_f32 v[60:61], v[60:61], v[132:133] op_sel_hi:[1,0]
	v_pk_mul_f32 v[78:79], v[94:95], v[78:79] op_sel_hi:[0,1]
	v_pk_mul_f32 v[76:77], v[94:95], v[76:77] op_sel_hi:[0,1]
	v_pk_mul_f32 v[96:97], v[94:95], v[74:75] op_sel_hi:[0,1]
	v_pk_mul_f32 v[74:75], v[94:95], v[72:73] op_sel_hi:[0,1]
	v_mul_f32_e32 v95, 0xbfb8aa3b, v60
	v_pk_mul_f32 v[52:53], v[52:53], v[132:133] op_sel_hi:[1,0]
	v_exp_f32_e32 v95, v95
	v_mul_f32_e32 v98, 0xbfb8aa3b, v52
	v_exp_f32_e32 v99, v98
	v_mul_f32_e32 v98, 0xbfb8aa3b, v61
	v_exp_f32_e32 v101, v98
	v_add_f32_e32 v95, 1.0, v95
	v_pk_mul_f32 v[62:63], v[62:63], v[132:133] op_sel_hi:[1,0]
	v_rcp_f32_e32 v98, v95
	v_add_f32_e32 v95, 1.0, v99
	v_pk_mul_f32 v[54:55], v[54:55], v[132:133] op_sel_hi:[1,0]
	v_rcp_f32_e32 v100, v95
	v_add_f32_e32 v95, 1.0, v101
	v_mul_f32_e32 v101, 0xbfb8aa3b, v62
	v_exp_f32_e32 v101, v101
	v_mul_f32_e32 v102, 0xbfb8aa3b, v54
	v_exp_f32_e32 v103, v102
	v_rcp_f32_e32 v99, v95
	v_add_f32_e32 v101, 1.0, v101
	v_rcp_f32_e32 v102, v101
	v_add_f32_e32 v101, 1.0, v103
	v_mul_f32_e32 v103, 0xbfb8aa3b, v63
	v_mul_f32_e32 v95, 0xbfb8aa3b, v53
	v_exp_f32_e32 v103, v103
	v_mul_f32_e32 v104, 0xbfb8aa3b, v55
	v_exp_f32_e32 v95, v95
	v_exp_f32_e32 v105, v104
	v_rcp_f32_e32 v104, v101
	v_add_f32_e32 v101, 1.0, v103
	v_add_f32_e32 v95, 1.0, v95
	v_rcp_f32_e32 v103, v101
	v_add_f32_e32 v101, 1.0, v105
	v_rcp_f32_e32 v105, v101
	v_rcp_f32_e32 v101, v95
	v_cvt_pk_bf16_f32 v72, v76, v77
	v_lshl_add_u64 v[76:77], s[36:37], 0, v[130:131]
	v_cvt_pk_bf16_f32 v73, v78, v79
	v_cvt_pk_bf16_f32 v74, v74, v75
	v_cvt_pk_bf16_f32 v75, v96, v97
	v_lshl_add_u64 v[76:77], v[76:77], 0, v[184:185]
	global_store_dwordx4 v[76:77], v[72:75], off
	v_lshlrev_b32_e32 v78, 16, v116
	v_and_b32_e32 v79, 0xffff0000, v116
	v_lshlrev_b32_e32 v72, 16, v114
	v_and_b32_e32 v73, 0xffff0000, v114
	v_lshlrev_b32_e32 v74, 16, v115
	v_and_b32_e32 v75, 0xffff0000, v115
	v_lshlrev_b32_e32 v96, 16, v117
	v_and_b32_e32 v97, 0xffff0000, v117
	v_pk_mul_f32 v[62:63], v[62:63], v[102:103]
	v_pk_mul_f32 v[60:61], v[60:61], v[98:99]
	v_pk_mul_f32 v[54:55], v[54:55], v[104:105]
	v_pk_mul_f32 v[52:53], v[52:53], v[100:101]
	v_pk_mul_f32 v[60:61], v[60:61], v[72:73]
	v_pk_mul_f32 v[62:63], v[62:63], v[74:75]
	v_pk_mul_f32 v[52:53], v[52:53], v[78:79]
	v_pk_mul_f32 v[54:55], v[54:55], v[96:97]
	v_pk_mul_f32 v[62:63], v[58:59], v[62:63]
	v_pk_mul_f32 v[60:61], v[56:57], v[60:61]
	v_pk_mul_f32 v[54:55], v[50:51], v[54:55]
	v_pk_mul_f32 v[52:53], v[48:49], v[52:53]
	v_pk_mul_f32 v[62:63], v[94:95], v[62:63] op_sel_hi:[0,1]
	v_pk_mul_f32 v[60:61], v[94:95], v[60:61] op_sel_hi:[0,1]
	v_pk_mul_f32 v[72:73], v[94:95], v[54:55] op_sel_hi:[0,1]
	v_pk_mul_f32 v[54:55], v[94:95], v[52:53] op_sel_hi:[0,1]
	v_cvt_pk_bf16_f32 v52, v60, v61
	v_cvt_pk_bf16_f32 v53, v62, v63
	v_cvt_pk_bf16_f32 v54, v54, v55
	v_cvt_pk_bf16_f32 v55, v72, v73
	global_store_dwordx4 v[76:77], v[52:55], off offset:256
	v_pk_add_f32 v[60:61], v[118:119], v[122:123]
	v_pk_add_f32 v[62:63], v[90:91], v[128:129]
	v_fmamk_f32 v52, v133, 0x3a800000, v198
	v_rsq_f32_e32 v54, v52
; __device__ __forceinline__ u32x4 pack8(f32x4 a, f32x4 b) { u32x4 w; w.x = pk2(a[0], a[1]); w.y = pk2(a[2], a[3]); w.z = pk2(b[0], b[1]); w.w = pk2(b[2], b[3]); return w; }
;     __device__ __forceinline__ void operator()(const Acc& acc, const pg8::Unit& u, int wid) const {
;     ...
;                 float scv[2]; f32x4 rq[2][4]; u32x4 ov[2][2];
; #pragma unroll
;                 for (int mm = 0; mm < 2; ++mm) { const int row = row0 + ai * 128 + (2 * mp + mm) * 16;
;                     scv[mm] = ssq[row];
;                     const f32x4* rp = (const f32x4*)(rssq + (size_t)row * 64 + head * 16);
; #pragma unroll
;                     for (int i = 0; i < 4; ++i) rq[mm][i] = rp[i];
; #pragma unroll
;                     for (int bj = 0; bj < 2; ++bj) ov[mm][bj] = *(const u32x4*)(Y + (size_t)row * 2048 + col0 + bj * 128); }
; #pragma unroll
;                 for (int mm = 0; mm < 2; ++mm) { const int m = 2 * mp + mm, row = row0 + ai * 128 + m * 16;
;                     const float sc = __builtin_amdgcn_rsqf(scv[mm] * (1.f / 1024.f) + EPS);
;                     const f32x4 pa = (rq[mm][0] + rq[mm][1]) + (rq[mm][2] + rq[mm][3]);
;                     const float rg = __builtin_amdgcn_rsqf(((pa[0] + pa[1]) + (pa[2] + pa[3])) * (1.f / 512.f) + EPS);
; #pragma unroll
;                     for (int bj = 0; bj < 2; ++bj) {
;                         const u32x4 w = ov[mm][bj];
;                         f32x4 o0 = (f32x4){bflo(w.x), bfhi(w.x), bflo(w.y), bfhi(w.y)}, o1 = (f32x4){bflo(w.z), bfhi(w.z), bflo(w.w), bfhi(w.w)};
;                         f32x4 a0 = acc[ai][bj][m][0] * sc, a1 = acc[ai][bj][m][1] * sc;
; #pragma unroll
;                         for (int e = 0; e < 4; ++e) { a0[e] = a0[e] * __builtin_amdgcn_rcpf(1.f + __builtin_amdgcn_exp2f(-1.4426950408889634f * a0[e])); a1[e] = a1[e] * __builtin_amdgcn_rcpf(1.f + __builtin_amdgcn_exp2f(-1.4426950408889634f * a1[e])); }
;                         o0 = a0 * o0 * g4[bj][0] * rg; o1 = a1 * o1 * g4[bj][1] * rg;
;                         *(u32x4*)(Y + (size_t)row * 2048 + col0 + bj * 128) = pack8(o0, o1);
;                     } }
	v_pk_add_f32 v[52:53], v[120:121], v[124:125]
	v_pk_add_f32 v[72:73], v[88:89], v[126:127]
	v_pk_add_f32 v[52:53], v[52:53], v[62:63]
	v_pk_add_f32 v[60:61], v[60:61], v[72:73]
	v_pk_mul_f32 v[44:45], v[44:45], v[54:55] op_sel_hi:[1,0]
	v_pk_mov_b32 v[62:63], v[60:61], v[52:53] op_sel:[1,0]
	v_mov_b32_e32 v61, v53
	v_pk_add_f32 v[52:53], v[62:63], v[60:61]
	v_pk_mul_f32 v[40:41], v[40:41], v[54:55] op_sel_hi:[1,0]
	v_add_f32_e32 v52, v52, v53
	v_mul_f32_e32 v53, 0xbfb8aa3b, v44
	v_exp_f32_e32 v53, v53
	v_pk_mul_f32 v[46:47], v[46:47], v[54:55] op_sel_hi:[1,0]
	v_pk_mul_f32 v[42:43], v[42:43], v[54:55] op_sel_hi:[1,0]
	v_mul_f32_e32 v55, 0xbfb8aa3b, v40
	v_exp_f32_e32 v55, v55
	v_add_f32_e32 v53, 1.0, v53
	v_mul_f32_e32 v76, 0xbfb8aa3b, v45
	v_exp_f32_e32 v77, v76
	v_rcp_f32_e32 v76, v53
	v_add_f32_e32 v53, 1.0, v55
	v_mul_f32_e32 v55, 0xbfb8aa3b, v46
	v_exp_f32_e32 v55, v55
	v_mul_f32_e32 v79, 0xbfb8aa3b, v42
	v_exp_f32_e32 v79, v79
	v_lshlrev_b32_e32 v60, 16, v84
	v_add_f32_e32 v55, 1.0, v55
	v_and_b32_e32 v61, 0xffff0000, v84
	v_rcp_f32_e32 v78, v53
	v_add_f32_e32 v53, 1.0, v77
	v_rcp_f32_e32 v84, v55
	v_add_f32_e32 v55, 1.0, v79
	v_mul_f32_e32 v79, 0xbfb8aa3b, v47
	v_lshlrev_b32_e32 v62, 16, v85
	v_and_b32_e32 v63, 0xffff0000, v85
	v_rcp_f32_e32 v77, v53
	v_mul_f32_e32 v53, 0xbfb8aa3b, v41
	v_exp_f32_e32 v79, v79
	v_mul_f32_e32 v85, 0xbfb8aa3b, v43
	v_lshlrev_b32_e32 v74, 16, v87
	v_and_b32_e32 v75, 0xffff0000, v87
	v_exp_f32_e32 v53, v53
	v_exp_f32_e32 v87, v85
	v_lshlrev_b32_e32 v72, 16, v86
	v_and_b32_e32 v73, 0xffff0000, v86
	v_rcp_f32_e32 v86, v55
	v_add_f32_e32 v55, 1.0, v79
	v_add_f32_e32 v53, 1.0, v53
	v_rcp_f32_e32 v85, v55
	v_add_f32_e32 v55, 1.0, v87
	v_rcp_f32_e32 v87, v55
	v_rcp_f32_e32 v79, v53
	v_fmamk_f32 v52, v52, 0x3b000000, v198
	v_rsq_f32_e32 v52, v52
	v_pk_mul_f32 v[46:47], v[46:47], v[84:85]
	v_pk_mul_f32 v[44:45], v[44:45], v[76:77]
	v_pk_mul_f32 v[42:43], v[42:43], v[86:87]
	v_pk_mul_f32 v[40:41], v[40:41], v[78:79]
	v_pk_mul_f32 v[44:45], v[44:45], v[60:61]
	v_pk_mul_f32 v[46:47], v[46:47], v[62:63]
	v_pk_mul_f32 v[40:41], v[40:41], v[72:73]
	v_pk_mul_f32 v[42:43], v[42:43], v[74:75]
	v_pk_mul_f32 v[46:47], v[66:67], v[46:47]
	v_pk_mul_f32 v[44:45], v[64:65], v[44:45]
	v_pk_mul_f32 v[42:43], v[70:71], v[42:43]
	v_pk_mul_f32 v[40:41], v[68:69], v[40:41]
	v_pk_mul_f32 v[36:37], v[36:37], v[54:55] op_sel_hi:[1,0]
	v_pk_mul_f32 v[46:47], v[52:53], v[46:47] op_sel_hi:[0,1]
	v_pk_mul_f32 v[44:45], v[52:53], v[44:45] op_sel_hi:[0,1]
	v_pk_mul_f32 v[60:61], v[52:53], v[42:43] op_sel_hi:[0,1]
	v_pk_mul_f32 v[42:43], v[52:53], v[40:41] op_sel_hi:[0,1]
	v_mul_f32_e32 v53, 0xbfb8aa3b, v36
	v_pk_mul_f32 v[32:33], v[32:33], v[54:55] op_sel_hi:[1,0]
	v_exp_f32_e32 v53, v53
	v_pk_mul_f32 v[38:39], v[38:39], v[54:55] op_sel_hi:[1,0]
	v_pk_mul_f32 v[34:35], v[34:35], v[54:55] op_sel_hi:[1,0]
	v_mul_f32_e32 v54, 0xbfb8aa3b, v32
	v_exp_f32_e32 v55, v54
	v_mul_f32_e32 v54, 0xbfb8aa3b, v37
	v_exp_f32_e32 v79, v54
	v_add_f32_e32 v53, 1.0, v53
	v_rcp_f32_e32 v54, v53
	v_add_f32_e32 v53, 1.0, v55
	v_rcp_f32_e32 v78, v53
	v_add_f32_e32 v53, 1.0, v79
	v_mul_f32_e32 v79, 0xbfb8aa3b, v38
	v_cvt_pk_bf16_f32 v41, v46, v47
	v_lshlrev_b32_e32 v46, 16, v80
	v_and_b32_e32 v47, 0xffff0000, v80
	v_exp_f32_e32 v79, v79
	v_mul_f32_e32 v80, 0xbfb8aa3b, v34
	v_lshlrev_b32_e32 v72, 16, v81
	v_and_b32_e32 v73, 0xffff0000, v81
	v_exp_f32_e32 v81, v80
	v_add_f32_e32 v79, 1.0, v79
	v_rcp_f32_e32 v80, v79
	v_lshlrev_b32_e32 v74, 16, v82
	v_add_f32_e32 v79, 1.0, v81
	v_mul_f32_e32 v81, 0xbfb8aa3b, v39
	v_and_b32_e32 v75, 0xffff0000, v82
	v_rcp_f32_e32 v55, v53
	v_mul_f32_e32 v53, 0xbfb8aa3b, v33
	v_exp_f32_e32 v81, v81
	v_mul_f32_e32 v82, 0xbfb8aa3b, v35
	v_lshlrev_b32_e32 v76, 16, v83
	v_and_b32_e32 v77, 0xffff0000, v83
	v_exp_f32_e32 v53, v53
	v_exp_f32_e32 v83, v82
	v_rcp_f32_e32 v82, v79
	v_add_f32_e32 v79, 1.0, v81
	v_add_f32_e32 v53, 1.0, v53
	v_rcp_f32_e32 v81, v79
	v_add_f32_e32 v79, 1.0, v83
	v_rcp_f32_e32 v83, v79
	v_rcp_f32_e32 v79, v53
	v_cvt_pk_bf16_f32 v40, v44, v45
	v_lshl_add_u64 v[44:45], s[36:37], 0, v[92:93]
	v_pk_mul_f32 v[38:39], v[38:39], v[80:81]
	v_pk_mul_f32 v[36:37], v[36:37], v[54:55]
	v_pk_mul_f32 v[34:35], v[34:35], v[82:83]
	v_pk_mul_f32 v[32:33], v[32:33], v[78:79]
	v_cvt_pk_bf16_f32 v42, v42, v43
	v_cvt_pk_bf16_f32 v43, v60, v61
	v_lshl_add_u64 v[44:45], v[44:45], 0, v[184:185]
	v_pk_mul_f32 v[36:37], v[36:37], v[46:47]
	v_pk_mul_f32 v[38:39], v[38:39], v[72:73]
	v_pk_mul_f32 v[32:33], v[32:33], v[74:75]
	v_pk_mul_f32 v[34:35], v[34:35], v[76:77]
	global_store_dwordx4 v[44:45], v[40:43], off
	v_pk_mul_f32 v[38:39], v[58:59], v[38:39]
	v_pk_mul_f32 v[36:37], v[56:57], v[36:37]
	v_add_u32_e32 v40, 0xa0, v186
	v_pk_mul_f32 v[34:35], v[50:51], v[34:35]
	v_pk_mul_f32 v[32:33], v[48:49], v[32:33]
	v_ashrrev_i32_e32 v41, 31, v40
	v_pk_mul_f32 v[38:39], v[52:53], v[38:39] op_sel_hi:[0,1]
	v_pk_mul_f32 v[36:37], v[52:53], v[36:37] op_sel_hi:[0,1]
	v_pk_mul_f32 v[46:47], v[52:53], v[34:35] op_sel_hi:[0,1]
	v_pk_mul_f32 v[34:35], v[52:53], v[32:33] op_sel_hi:[0,1]
	v_lshlrev_b64 v[100:101], 12, v[40:41]
	v_cvt_pk_bf16_f32 v32, v36, v37
	v_cvt_pk_bf16_f32 v33, v38, v39
	v_cvt_pk_bf16_f32 v34, v34, v35
	v_cvt_pk_bf16_f32 v35, v46, v47
	v_lshl_add_u64 v[42:43], v[190:191], 0, v[100:101]
	global_store_dwordx4 v[44:45], v[32:35], off offset:256
	global_load_dwordx4 v[60:63], v[42:43], off
	s_nop 0
	v_lshlrev_b64 v[32:33], 8, v[40:41]
	v_lshl_add_u64 v[32:33], s[20:21], 0, v[32:33]
	global_load_dword v54, v[188:189], off offset:640
	global_load_dwordx4 v[72:75], v[32:33], off
	global_load_dwordx4 v[76:79], v[32:33], off offset:16
	global_load_dwordx4 v[80:83], v[32:33], off offset:32
	global_load_dwordx4 v[84:87], v[32:33], off offset:48
	global_load_dwordx4 v[88:91], v[42:43], off offset:256
	v_add_u32_e32 v32, 0xb0, v186
	v_ashrrev_i32_e32 v33, 31, v32
	v_lshlrev_b64 v[34:35], 8, v[32:33]
	v_lshl_add_u64 v[34:35], s[20:21], 0, v[34:35]
	global_load_dword v102, v[188:189], off offset:704
	global_load_dwordx4 v[92:95], v[34:35], off
	global_load_dwordx4 v[96:99], v[34:35], off offset:16
	global_load_dwordx4 v[40:43], v[34:35], off offset:32
	global_load_dwordx4 v[44:47], v[34:35], off offset:48
	v_lshlrev_b64 v[52:53], 12, v[32:33]
	v_lshl_add_u64 v[32:33], v[190:191], 0, v[52:53]
	global_load_dwordx4 v[36:39], v[32:33], off
	s_nop 0
	global_load_dwordx4 v[32:35], v[32:33], off offset:256
	s_waitcnt vmcnt(0) lgkmcnt(0)
; __device__ __forceinline__ u32x4 pack8(f32x4 a, f32x4 b) { u32x4 w; w.x = pk2(a[0], a[1]); w.y = pk2(a[2], a[3]); w.z = pk2(b[0], b[1]); w.w = pk2(b[2], b[3]); return w; }
;     __device__ __forceinline__ void operator()(const Acc& acc, const pg8::Unit& u, int wid) const {
;     ...
;                 for (int mm = 0; mm < 2; ++mm) { const int m = 2 * mp + mm, row = row0 + ai * 128 + m * 16;
;                     const float sc = __builtin_amdgcn_rsqf(scv[mm] * (1.f / 1024.f) + EPS);
;                     const f32x4 pa = (rq[mm][0] + rq[mm][1]) + (rq[mm][2] + rq[mm][3]);
;                     const float rg = __builtin_amdgcn_rsqf(((pa[0] + pa[1]) + (pa[2] + pa[3])) * (1.f / 512.f) + EPS);
; #pragma unroll
;                     for (int bj = 0; bj < 2; ++bj) {
;                         const u32x4 w = ov[mm][bj];
;                         f32x4 o0 = (f32x4){bflo(w.x), bfhi(w.x), bflo(w.y), bfhi(w.y)}, o1 = (f32x4){bflo(w.z), bfhi(w.z), bflo(w.w), bfhi(w.w)};
;                         f32x4 a0 = acc[ai][bj][m][0] * sc, a1 = acc[ai][bj][m][1] * sc;
; #pragma unroll
;                         for (int e = 0; e < 4; ++e) { a0[e] = a0[e] * __builtin_amdgcn_rcpf(1.f + __builtin_amdgcn_exp2f(-1.4426950408889634f * a0[e])); a1[e] = a1[e] * __builtin_amdgcn_rcpf(1.f + __builtin_amdgcn_exp2f(-1.4426950408889634f * a1[e])); }
;                         o0 = a0 * o0 * g4[bj][0] * rg; o1 = a1 * o1 * g4[bj][1] * rg;
;                         *(u32x4*)(Y + (size_t)row * 2048 + col0 + bj * 128) = pack8(o0, o1);
;                     } }
	v_fmamk_f32 v54, v54, 0x3a800000, v198
	v_rsq_f32_e32 v54, v54
	v_pk_add_f32 v[74:75], v[74:75], v[78:79]
	v_pk_add_f32 v[72:73], v[72:73], v[76:77]
	v_pk_add_f32 v[76:77], v[82:83], v[86:87]
	v_pk_add_f32 v[78:79], v[80:81], v[84:85]
	v_pk_add_f32 v[74:75], v[74:75], v[76:77]
	v_pk_add_f32 v[72:73], v[72:73], v[78:79]
	s_nop 0
	v_pk_mov_b32 v[76:77], v[72:73], v[74:75] op_sel:[1,0]
	v_mov_b32_e32 v73, v75
	v_pk_add_f32 v[72:73], v[76:77], v[72:73]
	v_lshlrev_b32_e32 v74, 16, v60
	v_add_f32_e32 v55, v72, v73
	v_fmamk_f32 v55, v55, 0x3b000000, v198
	v_pk_mul_f32 v[28:29], v[28:29], v[54:55] op_sel_hi:[1,0]
	v_rsq_f32_e32 v72, v55
	v_mul_f32_e32 v55, 0xbfb8aa3b, v28
	v_exp_f32_e32 v55, v55
	v_mul_f32_e32 v78, 0xbfb8aa3b, v29
	v_exp_f32_e32 v79, v78
	v_and_b32_e32 v75, 0xffff0000, v60
	v_pk_mul_f32 v[24:25], v[24:25], v[54:55] op_sel_hi:[1,0]
	v_pk_mul_f32 v[30:31], v[30:31], v[54:55] op_sel_hi:[1,0]
	v_mul_f32_e32 v73, 0xbfb8aa3b, v24
	v_exp_f32_e32 v73, v73
	v_pk_mul_f32 v[26:27], v[26:27], v[54:55] op_sel_hi:[1,0]
	v_add_f32_e32 v55, 1.0, v55
	v_rcp_f32_e32 v78, v55
	v_add_f32_e32 v55, 1.0, v73
	v_mul_f32_e32 v73, 0xbfb8aa3b, v30
	v_exp_f32_e32 v73, v73
	v_mul_f32_e32 v81, 0xbfb8aa3b, v26
	v_exp_f32_e32 v81, v81
	v_rcp_f32_e32 v80, v55
	v_add_f32_e32 v73, 1.0, v73
	v_add_f32_e32 v55, 1.0, v79
	v_rcp_f32_e32 v82, v73
	v_add_f32_e32 v73, 1.0, v81
	v_mul_f32_e32 v81, 0xbfb8aa3b, v31
	v_rcp_f32_e32 v79, v55
	v_mul_f32_e32 v55, 0xbfb8aa3b, v25
	v_exp_f32_e32 v81, v81
	v_mul_f32_e32 v83, 0xbfb8aa3b, v27
	v_exp_f32_e32 v55, v55
	v_exp_f32_e32 v85, v83
	v_rcp_f32_e32 v84, v73
	v_add_f32_e32 v73, 1.0, v81
	v_add_f32_e32 v55, 1.0, v55
	v_rcp_f32_e32 v83, v73
	v_add_f32_e32 v73, 1.0, v85
	v_rcp_f32_e32 v85, v73
	v_rcp_f32_e32 v81, v55
	v_pk_mul_f32 v[20:21], v[20:21], v[54:55] op_sel_hi:[1,0]
	v_lshlrev_b32_e32 v60, 16, v61
	v_mul_f32_e32 v55, 0xbfb8aa3b, v20
	v_exp_f32_e32 v55, v55
	v_and_b32_e32 v61, 0xffff0000, v61
	v_lshlrev_b32_e32 v76, 16, v62
	v_and_b32_e32 v77, 0xffff0000, v62
	v_lshlrev_b32_e32 v62, 16, v63
	v_and_b32_e32 v63, 0xffff0000, v63
	v_pk_mul_f32 v[30:31], v[30:31], v[82:83]
	v_pk_mul_f32 v[28:29], v[28:29], v[78:79]
	v_pk_mul_f32 v[26:27], v[26:27], v[84:85]
	v_pk_mul_f32 v[24:25], v[24:25], v[80:81]
	v_pk_mul_f32 v[28:29], v[28:29], v[74:75]
	v_pk_mul_f32 v[30:31], v[30:31], v[60:61]
	v_pk_mul_f32 v[24:25], v[24:25], v[76:77]
	v_pk_mul_f32 v[26:27], v[26:27], v[62:63]
	v_pk_mul_f32 v[30:31], v[66:67], v[30:31]
	v_pk_mul_f32 v[28:29], v[64:65], v[28:29]
	v_pk_mul_f32 v[26:27], v[70:71], v[26:27]
	v_pk_mul_f32 v[24:25], v[68:69], v[24:25]
	v_pk_mul_f32 v[22:23], v[22:23], v[54:55] op_sel_hi:[1,0]
	v_pk_mul_f32 v[30:31], v[72:73], v[30:31] op_sel_hi:[0,1]
	v_pk_mul_f32 v[28:29], v[72:73], v[28:29] op_sel_hi:[0,1]
	v_pk_mul_f32 v[60:61], v[72:73], v[26:27] op_sel_hi:[0,1]
	v_pk_mul_f32 v[26:27], v[72:73], v[24:25] op_sel_hi:[0,1]
	v_pk_mul_f32 v[18:19], v[18:19], v[54:55] op_sel_hi:[1,0]
	v_pk_mul_f32 v[16:17], v[16:17], v[54:55] op_sel_hi:[1,0]
	v_mul_f32_e32 v73, 0xbfb8aa3b, v22
	v_add_f32_e32 v54, 1.0, v55
	v_mul_f32_e32 v55, 0xbfb8aa3b, v16
	v_exp_f32_e32 v73, v73
	v_mul_f32_e32 v74, 0xbfb8aa3b, v18
	v_exp_f32_e32 v55, v55
	v_mul_f32_e32 v62, 0xbfb8aa3b, v21
	v_exp_f32_e32 v75, v74
	v_exp_f32_e32 v63, v62
	v_add_f32_e32 v73, 1.0, v73
	v_add_f32_e32 v55, 1.0, v55
	v_rcp_f32_e32 v74, v73
	v_add_f32_e32 v73, 1.0, v75
	v_mul_f32_e32 v75, 0xbfb8aa3b, v23
	v_rcp_f32_e32 v62, v55
	v_add_f32_e32 v55, 1.0, v63
	v_mul_f32_e32 v63, 0xbfb8aa3b, v17
	v_exp_f32_e32 v75, v75
	v_mul_f32_e32 v76, 0xbfb8aa3b, v19
	v_exp_f32_e32 v63, v63
	v_exp_f32_e32 v77, v76
	v_rcp_f32_e32 v76, v73
	v_add_f32_e32 v73, 1.0, v75
	v_add_f32_e32 v63, 1.0, v63
	v_rcp_f32_e32 v75, v73
	v_add_f32_e32 v73, 1.0, v77
	v_rcp_f32_e32 v54, v54
	v_rcp_f32_e32 v55, v55
	v_rcp_f32_e32 v77, v73
	v_rcp_f32_e32 v63, v63
	v_cvt_pk_bf16_f32 v24, v28, v29
	v_lshl_add_u64 v[28:29], s[36:37], 0, v[100:101]
	v_cvt_pk_bf16_f32 v25, v30, v31
	v_cvt_pk_bf16_f32 v26, v26, v27
	v_cvt_pk_bf16_f32 v27, v60, v61
	v_lshl_add_u64 v[28:29], v[28:29], 0, v[184:185]
	global_store_dwordx4 v[28:29], v[24:27], off
	v_lshlrev_b32_e32 v30, 16, v90
	v_and_b32_e32 v31, 0xffff0000, v90
	v_lshlrev_b32_e32 v24, 16, v88
	v_and_b32_e32 v25, 0xffff0000, v88
	v_lshlrev_b32_e32 v26, 16, v89
	v_and_b32_e32 v27, 0xffff0000, v89
	v_lshlrev_b32_e32 v60, 16, v91
	v_and_b32_e32 v61, 0xffff0000, v91
	v_pk_mul_f32 v[22:23], v[22:23], v[74:75]
	v_pk_mul_f32 v[20:21], v[20:21], v[54:55]
	v_pk_mul_f32 v[18:19], v[18:19], v[76:77]
	v_pk_mul_f32 v[16:17], v[16:17], v[62:63]
	v_pk_mul_f32 v[20:21], v[20:21], v[24:25]
	v_pk_mul_f32 v[22:23], v[22:23], v[26:27]
	v_pk_mul_f32 v[16:17], v[16:17], v[30:31]
	v_pk_mul_f32 v[18:19], v[18:19], v[60:61]
	v_pk_mul_f32 v[22:23], v[58:59], v[22:23]
	v_pk_mul_f32 v[20:21], v[56:57], v[20:21]
	v_pk_mul_f32 v[18:19], v[50:51], v[18:19]
	v_pk_mul_f32 v[16:17], v[48:49], v[16:17]
	v_pk_mul_f32 v[22:23], v[72:73], v[22:23] op_sel_hi:[0,1]
	v_pk_mul_f32 v[20:21], v[72:73], v[20:21] op_sel_hi:[0,1]
	v_pk_mul_f32 v[24:25], v[72:73], v[18:19] op_sel_hi:[0,1]
	v_pk_mul_f32 v[18:19], v[72:73], v[16:17] op_sel_hi:[0,1]
	v_cvt_pk_bf16_f32 v16, v20, v21
	v_cvt_pk_bf16_f32 v17, v22, v23
	v_cvt_pk_bf16_f32 v18, v18, v19
	v_cvt_pk_bf16_f32 v19, v24, v25
	global_store_dwordx4 v[28:29], v[16:19], off offset:256
; __device__ __forceinline__ u32x4 pack8(f32x4 a, f32x4 b) { u32x4 w; w.x = pk2(a[0], a[1]); w.y = pk2(a[2], a[3]); w.z = pk2(b[0], b[1]); w.w = pk2(b[2], b[3]); return w; }
;     __device__ __forceinline__ void operator()(const Acc& acc, const pg8::Unit& u, int wid) const {
;     ...
;                 for (int mm = 0; mm < 2; ++mm) { const int m = 2 * mp + mm, row = row0 + ai * 128 + m * 16;
;                     const float sc = __builtin_amdgcn_rsqf(scv[mm] * (1.f / 1024.f) + EPS);
;                     const f32x4 pa = (rq[mm][0] + rq[mm][1]) + (rq[mm][2] + rq[mm][3]);
;                     const float rg = __builtin_amdgcn_rsqf(((pa[0] + pa[1]) + (pa[2] + pa[3])) * (1.f / 512.f) + EPS);
; #pragma unroll
;                     for (int bj = 0; bj < 2; ++bj) {
;                         const u32x4 w = ov[mm][bj];
;                         f32x4 o0 = (f32x4){bflo(w.x), bfhi(w.x), bflo(w.y), bfhi(w.y)}, o1 = (f32x4){bflo(w.z), bfhi(w.z), bflo(w.w), bfhi(w.w)};
;                         f32x4 a0 = acc[ai][bj][m][0] * sc, a1 = acc[ai][bj][m][1] * sc;
; #pragma unroll
;                         for (int e = 0; e < 4; ++e) { a0[e] = a0[e] * __builtin_amdgcn_rcpf(1.f + __builtin_amdgcn_exp2f(-1.4426950408889634f * a0[e])); a1[e] = a1[e] * __builtin_amdgcn_rcpf(1.f + __builtin_amdgcn_exp2f(-1.4426950408889634f * a1[e])); }
;                         o0 = a0 * o0 * g4[bj][0] * rg; o1 = a1 * o1 * g4[bj][1] * rg;
;                         *(u32x4*)(Y + (size_t)row * 2048 + col0 + bj * 128) = pack8(o0, o1);
;                     } }
	v_pk_add_f32 v[20:21], v[92:93], v[96:97]
	v_pk_add_f32 v[22:23], v[42:43], v[46:47]
	v_pk_add_f32 v[18:19], v[94:95], v[98:99]
	v_pk_add_f32 v[24:25], v[40:41], v[44:45]
	v_fmamk_f32 v16, v102, 0x3a800000, v198
	v_pk_add_f32 v[18:19], v[18:19], v[22:23]
	v_pk_add_f32 v[20:21], v[20:21], v[24:25]
	v_rsq_f32_e32 v16, v16
	v_pk_mov_b32 v[22:23], v[20:21], v[18:19] op_sel:[1,0]
	v_mov_b32_e32 v21, v19
	v_pk_add_f32 v[18:19], v[22:23], v[20:21]
	v_lshlrev_b32_e32 v20, 16, v36
	v_add_f32_e32 v17, v18, v19
	v_fmamk_f32 v17, v17, 0x3b000000, v198
	v_pk_mul_f32 v[12:13], v[12:13], v[16:17] op_sel_hi:[1,0]
	v_rsq_f32_e32 v18, v17
	v_mul_f32_e32 v17, 0xbfb8aa3b, v12
	v_exp_f32_e32 v17, v17
	v_mul_f32_e32 v28, 0xbfb8aa3b, v13
	v_exp_f32_e32 v29, v28
	v_and_b32_e32 v21, 0xffff0000, v36
	v_pk_mul_f32 v[8:9], v[8:9], v[16:17] op_sel_hi:[1,0]
	v_pk_mul_f32 v[14:15], v[14:15], v[16:17] op_sel_hi:[1,0]
	v_mul_f32_e32 v19, 0xbfb8aa3b, v8
	v_exp_f32_e32 v19, v19
	v_pk_mul_f32 v[10:11], v[10:11], v[16:17] op_sel_hi:[1,0]
	v_add_f32_e32 v17, 1.0, v17
	v_rcp_f32_e32 v28, v17
	v_add_f32_e32 v17, 1.0, v19
	v_mul_f32_e32 v19, 0xbfb8aa3b, v14
	v_exp_f32_e32 v19, v19
	v_mul_f32_e32 v31, 0xbfb8aa3b, v10
	v_exp_f32_e32 v31, v31
	v_rcp_f32_e32 v30, v17
	v_add_f32_e32 v17, 1.0, v29
	v_rcp_f32_e32 v29, v17
	v_mul_f32_e32 v17, 0xbfb8aa3b, v9
	v_add_f32_e32 v19, 1.0, v19
	v_exp_f32_e32 v17, v17
	v_rcp_f32_e32 v36, v19
	v_add_f32_e32 v19, 1.0, v31
	v_mul_f32_e32 v31, 0xbfb8aa3b, v15
	v_lshlrev_b32_e32 v22, 16, v37
	v_and_b32_e32 v23, 0xffff0000, v37
	v_exp_f32_e32 v31, v31
	v_mul_f32_e32 v37, 0xbfb8aa3b, v11
	v_lshlrev_b32_e32 v26, 16, v39
	v_and_b32_e32 v27, 0xffff0000, v39
	v_exp_f32_e32 v39, v37
	v_add_f32_e32 v17, 1.0, v17
	v_lshlrev_b32_e32 v24, 16, v38
	v_and_b32_e32 v25, 0xffff0000, v38
	v_rcp_f32_e32 v38, v19
	v_add_f32_e32 v19, 1.0, v31
	v_pk_mul_f32 v[4:5], v[4:5], v[16:17] op_sel_hi:[1,0]
	v_rcp_f32_e32 v37, v19
	v_add_f32_e32 v19, 1.0, v39
	v_rcp_f32_e32 v31, v17
	v_mul_f32_e32 v17, 0xbfb8aa3b, v4
	v_rcp_f32_e32 v39, v19
	v_exp_f32_e32 v17, v17
	v_pk_mul_f32 v[14:15], v[14:15], v[36:37]
	v_pk_mul_f32 v[12:13], v[12:13], v[28:29]
	v_pk_mul_f32 v[10:11], v[10:11], v[38:39]
	v_pk_mul_f32 v[8:9], v[8:9], v[30:31]
	v_pk_mul_f32 v[6:7], v[6:7], v[16:17] op_sel_hi:[1,0]
	v_pk_mul_f32 v[12:13], v[12:13], v[20:21]
	v_pk_mul_f32 v[14:15], v[14:15], v[22:23]
	v_pk_mul_f32 v[8:9], v[8:9], v[24:25]
	v_pk_mul_f32 v[10:11], v[10:11], v[26:27]
	v_pk_mul_f32 v[2:3], v[2:3], v[16:17] op_sel_hi:[1,0]
	v_pk_mul_f32 v[0:1], v[0:1], v[16:17] op_sel_hi:[1,0]
	v_mul_f32_e32 v23, 0xbfb8aa3b, v6
	v_pk_mul_f32 v[14:15], v[66:67], v[14:15]
	v_pk_mul_f32 v[12:13], v[64:65], v[12:13]
	v_pk_mul_f32 v[10:11], v[70:71], v[10:11]
	v_pk_mul_f32 v[8:9], v[68:69], v[8:9]
	v_add_f32_e32 v16, 1.0, v17
	v_mul_f32_e32 v17, 0xbfb8aa3b, v0
	v_exp_f32_e32 v23, v23
	v_mul_f32_e32 v24, 0xbfb8aa3b, v2
	v_pk_mul_f32 v[14:15], v[18:19], v[14:15] op_sel_hi:[0,1]
	v_pk_mul_f32 v[12:13], v[18:19], v[12:13] op_sel_hi:[0,1]
	v_pk_mul_f32 v[20:21], v[18:19], v[10:11] op_sel_hi:[0,1]
	v_pk_mul_f32 v[10:11], v[18:19], v[8:9] op_sel_hi:[0,1]
	v_exp_f32_e32 v17, v17
	v_mul_f32_e32 v19, 0xbfb8aa3b, v5
	v_exp_f32_e32 v25, v24
	v_exp_f32_e32 v19, v19
	v_add_f32_e32 v23, 1.0, v23
	v_add_f32_e32 v17, 1.0, v17
	v_rcp_f32_e32 v24, v23
	v_add_f32_e32 v23, 1.0, v25
	v_mul_f32_e32 v25, 0xbfb8aa3b, v7
	v_rcp_f32_e32 v22, v17
	v_add_f32_e32 v17, 1.0, v19
	v_mul_f32_e32 v19, 0xbfb8aa3b, v1
	v_exp_f32_e32 v25, v25
	v_mul_f32_e32 v26, 0xbfb8aa3b, v3
	v_exp_f32_e32 v19, v19
	v_exp_f32_e32 v27, v26
	v_rcp_f32_e32 v26, v23
	v_add_f32_e32 v23, 1.0, v25
	v_add_f32_e32 v19, 1.0, v19
	v_rcp_f32_e32 v25, v23
	v_add_f32_e32 v23, 1.0, v27
	v_rcp_f32_e32 v16, v16
	v_rcp_f32_e32 v17, v17
	v_rcp_f32_e32 v27, v23
	v_rcp_f32_e32 v23, v19
	v_cvt_pk_bf16_f32 v8, v12, v13
	v_lshl_add_u64 v[12:13], s[36:37], 0, v[52:53]
	v_cvt_pk_bf16_f32 v9, v14, v15
	v_cvt_pk_bf16_f32 v10, v10, v11
	v_cvt_pk_bf16_f32 v11, v20, v21
	v_lshl_add_u64 v[12:13], v[12:13], 0, v[184:185]
	global_store_dwordx4 v[12:13], v[8:11], off
	v_lshlrev_b32_e32 v14, 16, v34
	v_and_b32_e32 v15, 0xffff0000, v34
	v_lshlrev_b32_e32 v8, 16, v32
	v_and_b32_e32 v9, 0xffff0000, v32
	v_lshlrev_b32_e32 v10, 16, v33
	v_and_b32_e32 v11, 0xffff0000, v33
	v_lshlrev_b32_e32 v20, 16, v35
	v_and_b32_e32 v21, 0xffff0000, v35
	v_pk_mul_f32 v[6:7], v[6:7], v[24:25]
	v_pk_mul_f32 v[4:5], v[4:5], v[16:17]
	v_pk_mul_f32 v[2:3], v[2:3], v[26:27]
	v_pk_mul_f32 v[0:1], v[0:1], v[22:23]
	v_pk_mul_f32 v[4:5], v[4:5], v[8:9]
	v_pk_mul_f32 v[6:7], v[6:7], v[10:11]
	v_pk_mul_f32 v[0:1], v[0:1], v[14:15]
	v_pk_mul_f32 v[2:3], v[2:3], v[20:21]
	v_pk_mul_f32 v[6:7], v[58:59], v[6:7]
	v_pk_mul_f32 v[4:5], v[56:57], v[4:5]
	v_pk_mul_f32 v[2:3], v[50:51], v[2:3]
	v_pk_mul_f32 v[0:1], v[48:49], v[0:1]
	v_pk_mul_f32 v[6:7], v[18:19], v[6:7] op_sel_hi:[0,1]
	v_pk_mul_f32 v[4:5], v[18:19], v[4:5] op_sel_hi:[0,1]
	v_pk_mul_f32 v[8:9], v[18:19], v[2:3] op_sel_hi:[0,1]
	v_pk_mul_f32 v[2:3], v[18:19], v[0:1] op_sel_hi:[0,1]
	v_cvt_pk_bf16_f32 v0, v4, v5
	v_cvt_pk_bf16_f32 v1, v6, v7
	v_cvt_pk_bf16_f32 v2, v2, v3
	v_cvt_pk_bf16_f32 v3, v8, v9
	global_store_dwordx4 v[12:13], v[0:3], off offset:256
	s_cbranch_vccnz .LBB0_323
	s_andn2_b64 vcc, exec, s[4:5]
	s_cbranch_vccnz .LBB0_322
	s_barrier
	s_branch .LBB0_322

; __device__ __forceinline__ u32x4 pack8(f32x4 a, f32x4 b) { u32x4 w; w.x = pk2(a[0], a[1]); w.y = pk2(a[2], a[3]); w.z = pk2(b[0], b[1]); w.w = pk2(b[2], b[3]); return w; }
;     __device__ __forceinline__ void operator()(const Acc& acc, const pg8::Unit& u, int wid) const {
;     ...
;         const int row0 = u.pm * 256 + wr * 64 + fr, col0 = u.pn * 256 + wc * 32 + 8 * fq;
;         float scv[8];
; #pragma unroll
;         for (int i = 0; i < 8; ++i) scv[i] = ssq ? ssq[row0 + (i >> 2) * 128 + (i & 3) * 16] : 0.f;
; #pragma unroll
;         for (int ai = 0; ai < 2; ++ai)
; #pragma unroll
;             for (int m = 0; m < 4; ++m) {
;                 const int row = row0 + ai * 128 + m * 16;
;                 const float sc = ssq ? __builtin_amdgcn_rsqf(scv[ai * 4 + m] * inv_n + EPS) : 1.f;
; #pragma unroll
;                 for (int bj = 0; bj < 2; ++bj) {
;                     f32x4 v0 = acc[ai][bj][m][0] * sc, v1 = acc[ai][bj][m][1] * sc;
;                     if (ACT == 1) {
; #pragma unroll
;                         for (int e = 0; e < 4; ++e) { float a = fmaxf(v0[e], 0.f), b = fmaxf(v1[e], 0.f); v0[e] = a * a; v1[e] = b * b; }
;                     }
;                     *(u32x4*)(O + (size_t)row * ldc + col0 + bj * 128) = pack8(v0, v1);
.LBB0_488:
	s_lshl_b32 s4, s34, 8
	v_mbcnt_lo_u32_b32 v149, -1, 0
	v_mbcnt_hi_u32_b32 v149, -1, v149
	s_add_i32 s4, s4, s77
	v_and_or_b32 v148, v149, 15, s4
	v_ashrrev_i32_e32 v149, 1, v149
	s_lshl_b32 s4, s89, 8
	v_and_b32_e32 v149, -8, v149
	s_or_b32 s4, s4, s69
	v_add_u32_e32 v150, s4, v149
	v_mov_b32_e32 v149, 0
	v_mov_b32_e32 v151, 0
	v_lshlrev_b64 v[152:153], 13, v[148:149]
	v_lshl_add_u64 v[152:153], s[44:45], 0, v[152:153]
	v_lshlrev_b64 v[150:151], 1, v[150:151]
	v_lshl_add_u64 v[152:153], v[152:153], 0, v[150:151]
	v_max_f32_e32 v124, 0, v124
	v_max_f32_e32 v125, 0, v125
	v_max_f32_e32 v126, 0, v126
	v_max_f32_e32 v127, 0, v127
	v_max_f32_e32 v120, 0, v120
	v_max_f32_e32 v121, 0, v121
	v_max_f32_e32 v122, 0, v122
	v_max_f32_e32 v123, 0, v123
	v_pk_mul_f32 v[124:125], v[124:125], v[124:125]
	v_pk_mul_f32 v[126:127], v[126:127], v[126:127]
	v_pk_mul_f32 v[120:121], v[120:121], v[120:121]
	v_pk_mul_f32 v[122:123], v[122:123], v[122:123]
	v_cvt_pk_bf16_f32 v124, v124, v125
	v_cvt_pk_bf16_f32 v125, v126, v127
	v_cvt_pk_bf16_f32 v126, v120, v121
	v_cvt_pk_bf16_f32 v127, v122, v123
	global_store_dwordx4 v[152:153], v[124:127], off
	v_max_f32_e32 v116, 0, v116
	v_max_f32_e32 v117, 0, v117
	v_max_f32_e32 v118, 0, v118
	v_max_f32_e32 v119, 0, v119
	v_max_f32_e32 v112, 0, v112
	v_max_f32_e32 v113, 0, v113
	v_max_f32_e32 v114, 0, v114
	v_max_f32_e32 v115, 0, v115
	v_pk_mul_f32 v[116:117], v[116:117], v[116:117]
	v_pk_mul_f32 v[118:119], v[118:119], v[118:119]
	v_pk_mul_f32 v[112:113], v[112:113], v[112:113]
	v_pk_mul_f32 v[114:115], v[114:115], v[114:115]
	v_cvt_pk_bf16_f32 v116, v116, v117
	v_cvt_pk_bf16_f32 v117, v118, v119
	v_cvt_pk_bf16_f32 v118, v112, v113
	v_cvt_pk_bf16_f32 v119, v114, v115
	global_store_dwordx4 v[152:153], v[116:119], off offset:256
	v_add_co_u32_e32 v150, vcc, 0x20000, v152
	s_nop 1
	v_addc_co_u32_e32 v151, vcc, 0, v153, vcc
	v_max_f32_e32 v108, 0, v108
	v_max_f32_e32 v109, 0, v109
	v_max_f32_e32 v110, 0, v110
	v_max_f32_e32 v111, 0, v111
	v_max_f32_e32 v104, 0, v104
	v_max_f32_e32 v105, 0, v105
	v_max_f32_e32 v106, 0, v106
	v_max_f32_e32 v107, 0, v107
	v_pk_mul_f32 v[108:109], v[108:109], v[108:109]
	v_pk_mul_f32 v[110:111], v[110:111], v[110:111]
	v_pk_mul_f32 v[104:105], v[104:105], v[104:105]
	v_pk_mul_f32 v[106:107], v[106:107], v[106:107]
	v_cvt_pk_bf16_f32 v108, v108, v109
	v_cvt_pk_bf16_f32 v109, v110, v111
	v_cvt_pk_bf16_f32 v110, v104, v105
	v_cvt_pk_bf16_f32 v111, v106, v107
	global_store_dwordx4 v[150:151], v[108:111], off
	v_max_f32_e32 v100, 0, v100
	v_max_f32_e32 v101, 0, v101
	v_max_f32_e32 v102, 0, v102
	v_max_f32_e32 v103, 0, v103
	v_max_f32_e32 v96, 0, v96
	v_max_f32_e32 v97, 0, v97
	v_max_f32_e32 v98, 0, v98
	v_max_f32_e32 v99, 0, v99
	v_pk_mul_f32 v[100:101], v[100:101], v[100:101]
	v_pk_mul_f32 v[102:103], v[102:103], v[102:103]
	v_pk_mul_f32 v[96:97], v[96:97], v[96:97]
	v_pk_mul_f32 v[98:99], v[98:99], v[98:99]
	v_cvt_pk_bf16_f32 v100, v100, v101
	v_cvt_pk_bf16_f32 v101, v102, v103
	v_cvt_pk_bf16_f32 v102, v96, v97
	v_cvt_pk_bf16_f32 v103, v98, v99
	global_store_dwordx4 v[150:151], v[100:103], off offset:256
	v_add_co_u32_e32 v150, vcc, 0x40000, v152
	s_nop 1
	v_addc_co_u32_e32 v151, vcc, 0, v153, vcc
	v_max_f32_e32 v92, 0, v92
	v_max_f32_e32 v93, 0, v93
	v_max_f32_e32 v94, 0, v94
	v_max_f32_e32 v95, 0, v95
	v_max_f32_e32 v88, 0, v88
	v_max_f32_e32 v89, 0, v89
	v_max_f32_e32 v90, 0, v90
	v_max_f32_e32 v91, 0, v91
	v_pk_mul_f32 v[92:93], v[92:93], v[92:93]
	v_pk_mul_f32 v[94:95], v[94:95], v[94:95]
	v_pk_mul_f32 v[88:89], v[88:89], v[88:89]
	v_pk_mul_f32 v[90:91], v[90:91], v[90:91]
	v_cvt_pk_bf16_f32 v92, v92, v93
	v_cvt_pk_bf16_f32 v93, v94, v95
	v_cvt_pk_bf16_f32 v94, v88, v89
	v_cvt_pk_bf16_f32 v95, v90, v91
	global_store_dwordx4 v[150:151], v[92:95], off
	v_max_f32_e32 v84, 0, v84
	v_max_f32_e32 v85, 0, v85
	v_max_f32_e32 v86, 0, v86
	v_max_f32_e32 v87, 0, v87
	v_max_f32_e32 v80, 0, v80
	v_max_f32_e32 v81, 0, v81
	v_max_f32_e32 v82, 0, v82
	v_max_f32_e32 v83, 0, v83
	v_pk_mul_f32 v[84:85], v[84:85], v[84:85]
	v_pk_mul_f32 v[86:87], v[86:87], v[86:87]
	v_pk_mul_f32 v[80:81], v[80:81], v[80:81]
	v_pk_mul_f32 v[82:83], v[82:83], v[82:83]
	v_cvt_pk_bf16_f32 v84, v84, v85
	v_cvt_pk_bf16_f32 v85, v86, v87
	v_cvt_pk_bf16_f32 v86, v80, v81
	v_cvt_pk_bf16_f32 v87, v82, v83
	global_store_dwordx4 v[150:151], v[84:87], off offset:256
	v_add_co_u32_e32 v150, vcc, 0x60000, v152
	s_nop 1
	v_addc_co_u32_e32 v151, vcc, 0, v153, vcc
	v_max_f32_e32 v76, 0, v76
	v_max_f32_e32 v77, 0, v77
	v_max_f32_e32 v78, 0, v78
	v_max_f32_e32 v79, 0, v79
	v_max_f32_e32 v72, 0, v72
	v_max_f32_e32 v73, 0, v73
	v_max_f32_e32 v74, 0, v74
	v_max_f32_e32 v75, 0, v75
	v_pk_mul_f32 v[76:77], v[76:77], v[76:77]
	v_pk_mul_f32 v[78:79], v[78:79], v[78:79]
	v_pk_mul_f32 v[72:73], v[72:73], v[72:73]
	v_pk_mul_f32 v[74:75], v[74:75], v[74:75]
	v_cvt_pk_bf16_f32 v76, v76, v77
	v_cvt_pk_bf16_f32 v77, v78, v79
	v_cvt_pk_bf16_f32 v78, v72, v73
	v_cvt_pk_bf16_f32 v79, v74, v75
	global_store_dwordx4 v[150:151], v[76:79], off
	v_max_f32_e32 v68, 0, v68
	v_max_f32_e32 v69, 0, v69
	v_max_f32_e32 v70, 0, v70
	v_max_f32_e32 v71, 0, v71
	v_max_f32_e32 v64, 0, v64
	v_max_f32_e32 v65, 0, v65
	v_max_f32_e32 v66, 0, v66
	v_max_f32_e32 v67, 0, v67
	v_pk_mul_f32 v[68:69], v[68:69], v[68:69]
	v_pk_mul_f32 v[70:71], v[70:71], v[70:71]
; __device__ __forceinline__ u32x4 pack8(f32x4 a, f32x4 b) { u32x4 w; w.x = pk2(a[0], a[1]); w.y = pk2(a[2], a[3]); w.z = pk2(b[0], b[1]); w.w = pk2(b[2], b[3]); return w; }
;     __device__ __forceinline__ void operator()(const Acc& acc, const pg8::Unit& u, int wid) const {
;     ...
;         for (int ai = 0; ai < 2; ++ai)
; #pragma unroll
;             for (int m = 0; m < 4; ++m) {
;                 const int row = row0 + ai * 128 + m * 16;
;                 const float sc = ssq ? __builtin_amdgcn_rsqf(scv[ai * 4 + m] * inv_n + EPS) : 1.f;
; #pragma unroll
;                 for (int bj = 0; bj < 2; ++bj) {
;                     f32x4 v0 = acc[ai][bj][m][0] * sc, v1 = acc[ai][bj][m][1] * sc;
;                     if (ACT == 1) {
; #pragma unroll
;                         for (int e = 0; e < 4; ++e) { float a = fmaxf(v0[e], 0.f), b = fmaxf(v1[e], 0.f); v0[e] = a * a; v1[e] = b * b; }
;                     }
;                     *(u32x4*)(O + (size_t)row * ldc + col0 + bj * 128) = pack8(v0, v1);
	v_pk_mul_f32 v[64:65], v[64:65], v[64:65]
	v_pk_mul_f32 v[66:67], v[66:67], v[66:67]
	v_cvt_pk_bf16_f32 v68, v68, v69
	v_cvt_pk_bf16_f32 v69, v70, v71
	v_cvt_pk_bf16_f32 v70, v64, v65
	v_cvt_pk_bf16_f32 v71, v66, v67
	global_store_dwordx4 v[150:151], v[68:71], off offset:256
	v_add_co_u32_e32 v150, vcc, 0x100000, v152
	s_nop 1
	v_addc_co_u32_e32 v151, vcc, 0, v153, vcc
	v_max_f32_e32 v60, 0, v60
	v_max_f32_e32 v61, 0, v61
	v_max_f32_e32 v62, 0, v62
	v_max_f32_e32 v63, 0, v63
	v_max_f32_e32 v56, 0, v56
	v_max_f32_e32 v57, 0, v57
	v_max_f32_e32 v58, 0, v58
	v_max_f32_e32 v59, 0, v59
	v_pk_mul_f32 v[60:61], v[60:61], v[60:61]
	v_pk_mul_f32 v[62:63], v[62:63], v[62:63]
	v_pk_mul_f32 v[56:57], v[56:57], v[56:57]
	v_pk_mul_f32 v[58:59], v[58:59], v[58:59]
	v_cvt_pk_bf16_f32 v60, v60, v61
	v_cvt_pk_bf16_f32 v61, v62, v63
	v_cvt_pk_bf16_f32 v62, v56, v57
	v_cvt_pk_bf16_f32 v63, v58, v59
	global_store_dwordx4 v[150:151], v[60:63], off
	v_max_f32_e32 v52, 0, v52
	v_max_f32_e32 v53, 0, v53
	v_max_f32_e32 v54, 0, v54
	v_max_f32_e32 v55, 0, v55
	v_max_f32_e32 v48, 0, v48
	v_max_f32_e32 v49, 0, v49
	v_max_f32_e32 v50, 0, v50
	v_max_f32_e32 v51, 0, v51
	v_pk_mul_f32 v[52:53], v[52:53], v[52:53]
	v_pk_mul_f32 v[54:55], v[54:55], v[54:55]
	v_pk_mul_f32 v[48:49], v[48:49], v[48:49]
	v_pk_mul_f32 v[50:51], v[50:51], v[50:51]
	v_cvt_pk_bf16_f32 v52, v52, v53
	v_cvt_pk_bf16_f32 v53, v54, v55
	v_cvt_pk_bf16_f32 v54, v48, v49
	v_cvt_pk_bf16_f32 v55, v50, v51
	global_store_dwordx4 v[150:151], v[52:55], off offset:256
	v_add_co_u32_e32 v150, vcc, 0x120000, v152
	s_nop 1
	v_addc_co_u32_e32 v151, vcc, 0, v153, vcc
	v_max_f32_e32 v44, 0, v44
	v_max_f32_e32 v45, 0, v45
	v_max_f32_e32 v46, 0, v46
	v_max_f32_e32 v47, 0, v47
	v_max_f32_e32 v40, 0, v40
	v_max_f32_e32 v41, 0, v41
	v_max_f32_e32 v42, 0, v42
	v_max_f32_e32 v43, 0, v43
	v_pk_mul_f32 v[44:45], v[44:45], v[44:45]
	v_pk_mul_f32 v[46:47], v[46:47], v[46:47]
	v_pk_mul_f32 v[40:41], v[40:41], v[40:41]
	v_pk_mul_f32 v[42:43], v[42:43], v[42:43]
	v_cvt_pk_bf16_f32 v44, v44, v45
	v_cvt_pk_bf16_f32 v45, v46, v47
	v_cvt_pk_bf16_f32 v46, v40, v41
	v_cvt_pk_bf16_f32 v47, v42, v43
	global_store_dwordx4 v[150:151], v[44:47], off
	v_max_f32_e32 v36, 0, v36
	v_max_f32_e32 v37, 0, v37
	v_max_f32_e32 v38, 0, v38
	v_max_f32_e32 v39, 0, v39
	v_max_f32_e32 v32, 0, v32
	v_max_f32_e32 v33, 0, v33
	v_max_f32_e32 v34, 0, v34
	v_max_f32_e32 v35, 0, v35
	v_pk_mul_f32 v[36:37], v[36:37], v[36:37]
	v_pk_mul_f32 v[38:39], v[38:39], v[38:39]
	v_pk_mul_f32 v[32:33], v[32:33], v[32:33]
	v_pk_mul_f32 v[34:35], v[34:35], v[34:35]
	v_cvt_pk_bf16_f32 v36, v36, v37
	v_cvt_pk_bf16_f32 v37, v38, v39
	v_cvt_pk_bf16_f32 v38, v32, v33
	v_cvt_pk_bf16_f32 v39, v34, v35
	global_store_dwordx4 v[150:151], v[36:39], off offset:256
	v_add_co_u32_e32 v150, vcc, 0x140000, v152
	s_nop 1
	v_addc_co_u32_e32 v151, vcc, 0, v153, vcc
	v_max_f32_e32 v28, 0, v28
	v_max_f32_e32 v29, 0, v29
	v_max_f32_e32 v30, 0, v30
	v_max_f32_e32 v31, 0, v31
	v_max_f32_e32 v24, 0, v24
	v_max_f32_e32 v25, 0, v25
	v_max_f32_e32 v26, 0, v26
	v_max_f32_e32 v27, 0, v27
	v_pk_mul_f32 v[28:29], v[28:29], v[28:29]
	v_pk_mul_f32 v[30:31], v[30:31], v[30:31]
	v_pk_mul_f32 v[24:25], v[24:25], v[24:25]
	v_pk_mul_f32 v[26:27], v[26:27], v[26:27]
	v_cvt_pk_bf16_f32 v28, v28, v29
	v_cvt_pk_bf16_f32 v29, v30, v31
	v_cvt_pk_bf16_f32 v30, v24, v25
	v_cvt_pk_bf16_f32 v31, v26, v27
	global_store_dwordx4 v[150:151], v[28:31], off
	v_max_f32_e32 v20, 0, v20
	v_max_f32_e32 v21, 0, v21
	v_max_f32_e32 v22, 0, v22
	v_max_f32_e32 v23, 0, v23
	v_max_f32_e32 v16, 0, v16
	v_max_f32_e32 v17, 0, v17
	v_max_f32_e32 v18, 0, v18
	v_max_f32_e32 v19, 0, v19
	v_pk_mul_f32 v[20:21], v[20:21], v[20:21]
	v_pk_mul_f32 v[22:23], v[22:23], v[22:23]
	v_pk_mul_f32 v[16:17], v[16:17], v[16:17]
	v_pk_mul_f32 v[18:19], v[18:19], v[18:19]
	v_cvt_pk_bf16_f32 v20, v20, v21
	v_cvt_pk_bf16_f32 v21, v22, v23
	v_cvt_pk_bf16_f32 v22, v16, v17
	v_cvt_pk_bf16_f32 v23, v18, v19
	global_store_dwordx4 v[150:151], v[20:23], off offset:256
	v_add_co_u32_e32 v150, vcc, 0x160000, v152
	s_nop 1
	v_addc_co_u32_e32 v151, vcc, 0, v153, vcc
	v_max_f32_e32 v12, 0, v12
	v_max_f32_e32 v13, 0, v13
	v_max_f32_e32 v14, 0, v14
	v_max_f32_e32 v15, 0, v15
	v_max_f32_e32 v8, 0, v8
	v_max_f32_e32 v9, 0, v9
	v_max_f32_e32 v10, 0, v10
	v_max_f32_e32 v11, 0, v11
	v_pk_mul_f32 v[12:13], v[12:13], v[12:13]
	v_pk_mul_f32 v[14:15], v[14:15], v[14:15]
	v_pk_mul_f32 v[8:9], v[8:9], v[8:9]
	v_pk_mul_f32 v[10:11], v[10:11], v[10:11]
	v_cvt_pk_bf16_f32 v12, v12, v13
	v_cvt_pk_bf16_f32 v13, v14, v15
	v_cvt_pk_bf16_f32 v14, v8, v9
	v_cvt_pk_bf16_f32 v15, v10, v11
	global_store_dwordx4 v[150:151], v[12:15], off
	v_max_f32_e32 v4, 0, v4
	v_max_f32_e32 v5, 0, v5
	v_max_f32_e32 v6, 0, v6
	v_max_f32_e32 v7, 0, v7
	v_max_f32_e32 v0, 0, v0
	v_max_f32_e32 v1, 0, v1
	v_max_f32_e32 v2, 0, v2
	v_max_f32_e32 v3, 0, v3
	v_pk_mul_f32 v[4:5], v[4:5], v[4:5]
	v_pk_mul_f32 v[6:7], v[6:7], v[6:7]
	v_pk_mul_f32 v[0:1], v[0:1], v[0:1]
	v_pk_mul_f32 v[2:3], v[2:3], v[2:3]
	v_cvt_pk_bf16_f32 v4, v4, v5
	v_cvt_pk_bf16_f32 v5, v6, v7
	v_cvt_pk_bf16_f32 v6, v0, v1
	v_cvt_pk_bf16_f32 v7, v2, v3
	s_andn2_b64 vcc, exec, s[6:7]
	s_mov_b64 s[6:7], -1
	global_store_dwordx4 v[150:151], v[4:7], off offset:256
	s_cbranch_vccnz .LBB0_477
	s_andn2_b64 vcc, exec, s[0:1]
	s_cbranch_vccnz .LBB0_476
	s_barrier
	s_branch .LBB0_476

; __device__ __forceinline__ int lane_id_asm() { int l; asm volatile("v_mbcnt_lo_u32_b32 %0, -1, 0\n\tv_mbcnt_hi_u32_b32 %0, -1, %0" : "=v"(l)); return l; }
; __device__ __forceinline__ u32x4 pack8(f32x4 a, f32x4 b) { u32x4 w; w.x = pk2(a[0], a[1]); w.y = pk2(a[2], a[3]); w.z = pk2(b[0], b[1]); w.w = pk2(b[2], b[3]); return w; }
;     __device__ __forceinline__ void operator()(const Acc& acc, const pg8::Unit& u, int wid) const {
;         const int lane_ = lane_id_asm(), wr = wid >> 2, wc = wid & 3, fr = lane_ & 15, fq = lane_ >> 4;
;         const int row0 = u.pm * 256 + wr * 64 + fr, col0 = u.pn * 256 + wc * 32 + 8 * fq;
; #pragma unroll
;         for (int ai = 0; ai < 2; ++ai)
; #pragma unroll
;             for (int m = 0; m < 4; ++m)
; #pragma unroll
;                 for (int bj = 0; bj < 2; ++bj) *(u32x4*)(O + (size_t)(row0 + ai * 128 + m * 16) * 1024 + col0 + bj * 128) = pack8(acc[ai][bj][m][0], acc[ai][bj][m][1]);
;     }
.LBB0_642:
	s_lshl_b32 s4, s18, 8
	v_mbcnt_lo_u32_b32 v145, -1, 0
	v_mbcnt_hi_u32_b32 v145, -1, v145
	s_add_i32 s4, s4, s83
	v_and_or_b32 v144, v145, 15, s4
	s_lshl_b32 s4, s93, 8
	v_ashrrev_i32_e32 v145, 1, v145
	s_or_b32 s4, s4, s69
	v_and_b32_e32 v145, -8, v145
	v_add_u32_e32 v146, s4, v145
	v_ashrrev_i32_e32 v145, 31, v144
	v_ashrrev_i32_e32 v147, 31, v146
	v_lshlrev_b64 v[148:149], 11, v[144:145]
	v_cvt_pk_bf16_f32 v124, v124, v125
	v_cvt_pk_bf16_f32 v125, v126, v127
	v_cvt_pk_bf16_f32 v126, v120, v121
	v_cvt_pk_bf16_f32 v127, v122, v123
	v_lshl_add_u64 v[120:121], s[48:49], 0, v[148:149]
	v_lshlrev_b64 v[122:123], 1, v[146:147]
	v_lshl_add_u64 v[120:121], v[120:121], 0, v[122:123]
	v_cvt_pk_bf16_f32 v108, v108, v109
	v_cvt_pk_bf16_f32 v109, v110, v111
	v_cvt_pk_bf16_f32 v110, v104, v105
	v_or_b32_e32 v104, 16, v144
	s_mov_b64 s[4:5], 0x40000
	v_cvt_pk_bf16_f32 v111, v106, v107
	v_ashrrev_i32_e32 v105, 31, v104
	v_cvt_pk_bf16_f32 v60, v60, v61
	v_cvt_pk_bf16_f32 v61, v62, v63
	v_cvt_pk_bf16_f32 v62, v56, v57
	v_lshl_add_u64 v[56:57], v[120:121], 0, s[4:5]
	s_mov_b32 s4, 0x40000
	global_store_dwordx4 v[120:121], v[108:111], off offset:256
	v_cvt_pk_bf16_f32 v63, v58, v59
	v_add_co_u32_e32 v58, vcc, s4, v120
	v_lshlrev_b64 v[108:109], 11, v[104:105]
	v_cvt_pk_bf16_f32 v44, v44, v45
	v_cvt_pk_bf16_f32 v45, v46, v47
	v_cvt_pk_bf16_f32 v46, v40, v41
	v_cvt_pk_bf16_f32 v47, v42, v43
	s_mov_b64 s[4:5], 0x48000
	v_lshl_add_u64 v[108:109], s[48:49], 0, v[108:109]
	v_cvt_pk_bf16_f32 v92, v92, v93
	v_cvt_pk_bf16_f32 v93, v94, v95
	v_cvt_pk_bf16_f32 v94, v88, v89
	v_or_b32_e32 v88, 32, v144
	v_addc_co_u32_e32 v59, vcc, 0, v121, vcc
	global_store_dwordx4 v[56:57], v[44:47], off offset:256
	v_lshl_add_u64 v[108:109], v[108:109], 0, v[122:123]
	v_cvt_pk_bf16_f32 v95, v90, v91
	v_lshl_add_u64 v[44:45], v[120:121], 0, s[4:5]
	s_mov_b32 s4, 0x48000
	v_ashrrev_i32_e32 v89, 31, v88
	v_add_co_u32_e32 v46, vcc, s4, v120
	v_cvt_pk_bf16_f32 v28, v28, v29
	v_cvt_pk_bf16_f32 v29, v30, v31
	v_cvt_pk_bf16_f32 v30, v24, v25
	v_cvt_pk_bf16_f32 v31, v26, v27
	s_mov_b64 s[4:5], 0x50000
	global_store_dwordx4 v[108:109], v[92:95], off offset:256
	v_addc_co_u32_e32 v47, vcc, 0, v121, vcc
	s_nop 0
	v_lshlrev_b64 v[92:93], 11, v[88:89]
	global_store_dwordx4 v[44:45], v[28:31], off offset:256
	v_lshl_add_u64 v[92:93], s[48:49], 0, v[92:93]
	v_cvt_pk_bf16_f32 v76, v76, v77
	v_lshl_add_u64 v[28:29], v[120:121], 0, s[4:5]
	s_mov_b32 s4, 0x50000
	v_cvt_pk_bf16_f32 v77, v78, v79
	v_cvt_pk_bf16_f32 v78, v72, v73
	v_or_b32_e32 v72, 48, v144
	v_add_co_u32_e32 v30, vcc, s4, v120
	v_cvt_pk_bf16_f32 v12, v12, v13
	v_cvt_pk_bf16_f32 v13, v14, v15
	v_cvt_pk_bf16_f32 v14, v8, v9
	v_cvt_pk_bf16_f32 v15, v10, v11
	s_mov_b64 s[4:5], 0x58000
	v_lshl_add_u64 v[92:93], v[92:93], 0, v[122:123]
	v_cvt_pk_bf16_f32 v79, v74, v75
	v_ashrrev_i32_e32 v73, 31, v72
	v_addc_co_u32_e32 v31, vcc, 0, v121, vcc
	global_store_dwordx4 v[28:29], v[12:15], off offset:256
	global_store_dwordx4 v[92:93], v[76:79], off offset:256
	v_cvt_pk_bf16_f32 v104, v116, v117
	v_lshl_add_u64 v[12:13], v[120:121], 0, s[4:5]
	s_mov_b32 s4, 0x58000
	v_lshlrev_b64 v[76:77], 11, v[72:73]
	v_add_co_u32_e32 v14, vcc, s4, v120
	v_lshl_add_u64 v[76:77], s[48:49], 0, v[76:77]
	s_nop 0
	v_addc_co_u32_e32 v15, vcc, 0, v121, vcc
	v_cvt_pk_bf16_f32 v105, v118, v119
	v_cvt_pk_bf16_f32 v106, v112, v113
	v_cvt_pk_bf16_f32 v107, v114, v115
	v_cvt_pk_bf16_f32 v88, v100, v101
	v_cvt_pk_bf16_f32 v89, v102, v103
	v_cvt_pk_bf16_f32 v90, v96, v97
	v_cvt_pk_bf16_f32 v91, v98, v99
	v_cvt_pk_bf16_f32 v72, v84, v85
	v_cvt_pk_bf16_f32 v73, v86, v87
	v_cvt_pk_bf16_f32 v74, v80, v81
	v_cvt_pk_bf16_f32 v75, v82, v83
	v_lshl_add_u64 v[76:77], v[76:77], 0, v[122:123]
	v_cvt_pk_bf16_f32 v68, v68, v69
	v_cvt_pk_bf16_f32 v69, v70, v71
	v_cvt_pk_bf16_f32 v70, v64, v65
	v_cvt_pk_bf16_f32 v71, v66, v67
	v_cvt_pk_bf16_f32 v40, v52, v53
	v_cvt_pk_bf16_f32 v41, v54, v55
	v_cvt_pk_bf16_f32 v42, v48, v49
	v_cvt_pk_bf16_f32 v43, v50, v51
	v_cvt_pk_bf16_f32 v24, v36, v37
	v_cvt_pk_bf16_f32 v25, v38, v39
	v_cvt_pk_bf16_f32 v26, v32, v33
	v_cvt_pk_bf16_f32 v27, v34, v35
	v_cvt_pk_bf16_f32 v8, v20, v21
	v_cvt_pk_bf16_f32 v9, v22, v23
	v_cvt_pk_bf16_f32 v10, v16, v17
	v_cvt_pk_bf16_f32 v11, v18, v19
	v_cvt_pk_bf16_f32 v4, v4, v5
	v_cvt_pk_bf16_f32 v5, v6, v7
	v_cvt_pk_bf16_f32 v6, v0, v1
	v_cvt_pk_bf16_f32 v7, v2, v3
	s_andn2_b64 vcc, exec, s[6:7]
	s_mov_b64 s[6:7], -1
	global_store_dwordx4 v[120:121], v[124:127], off
	global_store_dwordx4 v[108:109], v[104:107], off
	global_store_dwordx4 v[92:93], v[88:91], off
	global_store_dwordx4 v[76:77], v[72:75], off
	global_store_dwordx4 v[76:77], v[68:71], off offset:256
	global_store_dwordx4 v[58:59], v[60:63], off
	global_store_dwordx4 v[46:47], v[40:43], off
	global_store_dwordx4 v[30:31], v[24:27], off
	global_store_dwordx4 v[14:15], v[8:11], off
	global_store_dwordx4 v[12:13], v[4:7], off offset:256
	s_cbranch_vccnz .LBB0_631
	s_andn2_b64 vcc, exec, s[0:1]
	s_cbranch_vccnz .LBB0_630
	s_barrier
	s_branch .LBB0_630

; __device__ __forceinline__ int lane_id_asm() { int l; asm volatile("v_mbcnt_lo_u32_b32 %0, -1, 0\n\tv_mbcnt_hi_u32_b32 %0, -1, %0" : "=v"(l)); return l; }
; __device__ __forceinline__ u32x4 pack8(f32x4 a, f32x4 b) { u32x4 w; w.x = pk2(a[0], a[1]); w.y = pk2(a[2], a[3]); w.z = pk2(b[0], b[1]); w.w = pk2(b[2], b[3]); return w; }
;     __device__ __forceinline__ void operator()(const Acc& acc, const pg8::Unit& u, int wid) const {
;         const int lane_ = lane_id_asm(), wr = wid >> 2, wc = wid & 3, fr = lane_ & 15, fq = lane_ >> 4;
;         const int row0 = u.pm * 256 + wr * 64 + fr, col0 = u.pn * 256 + wc * 32 + 8 * fq;
;         float scv[8];
; #pragma unroll
;         for (int i = 0; i < 8; ++i) scv[i] = ssq ? ssq[row0 + (i >> 2) * 128 + (i & 3) * 16] : 0.f;
; #pragma unroll
;         for (int ai = 0; ai < 2; ++ai)
; #pragma unroll
;             for (int m = 0; m < 4; ++m) {
;                 const int row = row0 + ai * 128 + m * 16;
;                 const float sc = ssq ? __builtin_amdgcn_rsqf(scv[ai * 4 + m] * inv_n + EPS) : 1.f;
; #pragma unroll
;                 for (int bj = 0; bj < 2; ++bj) {
;                     f32x4 v0 = acc[ai][bj][m][0] * sc, v1 = acc[ai][bj][m][1] * sc;
;                     if (ACT == 1) {
; #pragma unroll
;                         for (int e = 0; e < 4; ++e) { float a = fmaxf(v0[e], 0.f), b = fmaxf(v1[e], 0.f); v0[e] = a * a; v1[e] = b * b; }
;                     }
;                     *(u32x4*)(O + (size_t)row * ldc + col0 + bj * 128) = pack8(v0, v1);
;                     if (SSQP) {
;                         float s = 0.f;
; #pragma unroll
;                         for (int e = 0; e < 4; ++e) s += v0[e] * v0[e] + v1[e] * v1[e];
;                         s += __shfl_xor(s, 16); s += __shfl_xor(s, 32);
;                         const int hidx = 2 * u.pn + bj;
;                         if (fq == 0 && hidx < 5) atomicAdd((hidx < 3 ? ssqA : ssqB) + row, s);
;                     }
.LBB0_778:
	s_lshl_b32 s0, s0, 8
	s_add_i32 s0, s0, s76
	v_mbcnt_lo_u32_b32 v148, -1, 0
	v_mbcnt_hi_u32_b32 v148, -1, v148
	v_xor_b32_e32 v156, 32, v154
	v_and_or_b32 v144, v148, 15, s0
	v_ashrrev_i32_e32 v145, 31, v144
	v_lshl_add_u64 v[146:147], v[144:145], 2, s[58:59]
	global_load_dword v149, v[146:147], off
	global_load_dword v164, v[146:147], off offset:64
	global_load_dword v163, v[146:147], off offset:128
	global_load_dword v162, v[146:147], off offset:192
	global_load_dword v161, v[146:147], off offset:512
	global_load_dword v160, v[146:147], off offset:576
	global_load_dword v159, v[146:147], off offset:640
	global_load_dword v158, v[146:147], off offset:704
	v_and_b32_e32 v147, 64, v154
	s_lshl_b32 s0, s8, 8
	v_xor_b32_e32 v146, 16, v154
	v_ashrrev_i32_e32 v157, 1, v148
	v_add_u32_e32 v147, 64, v147
	s_or_b32 s4, s0, s69
	v_cmp_gt_u32_e32 vcc, 16, v148
	v_and_b32_e32 v148, -8, v157
	v_cmp_lt_i32_e64 s[0:1], v146, v147
	s_cmp_lt_i32 s8, 3
	s_nop 0
	v_cndmask_b32_e64 v157, v154, v146, s[0:1]
	v_add_u32_e32 v146, s4, v148
	v_lshlrev_b32_e32 v157, 2, v157
	v_cmp_lt_i32_e64 s[0:1], v156, v147
	s_waitcnt vmcnt(0) lgkmcnt(0)
	v_fmamk_f32 v148, v149, 0x3a800000, v155
	v_rsq_f32_e32 v148, v148
	v_cndmask_b32_e64 v147, v154, v156, s[0:1]
	v_lshlrev_b32_e32 v156, 2, v147
	v_ashrrev_i32_e32 v147, 31, v146
	v_pk_mul_f32 v[120:121], v[120:121], v[148:149] op_sel_hi:[1,0]
	v_pk_mul_f32 v[166:167], v[126:127], v[148:149] op_sel_hi:[1,0]
	v_pk_mul_f32 v[168:169], v[124:125], v[148:149] op_sel_hi:[1,0]
	v_pk_mul_f32 v[122:123], v[122:123], v[148:149] op_sel_hi:[1,0]
	v_cvt_pk_bf16_f32 v126, v120, v121
	v_mul_f32_e32 v120, v120, v120
	v_mul_f32_e32 v121, v121, v121
	v_cvt_pk_bf16_f32 v127, v122, v123
	v_mul_f32_e32 v122, v122, v122
	v_fmac_f32_e32 v120, v168, v168
	v_fmac_f32_e32 v121, v169, v169
	v_mul_f32_e32 v123, v123, v123
	v_fmac_f32_e32 v122, v166, v166
	v_add_f32_e32 v120, v120, v121
	v_add_f32_e32 v120, v122, v120
	v_fmac_f32_e32 v123, v167, v167
	v_add_f32_e32 v122, v123, v120
	ds_bpermute_b32 v123, v157, v122
	v_mov_b64_e32 v[120:121], s[44:45]
	v_mad_i64_i32 v[120:121], s[0:1], v144, s82, v[120:121]
	s_cselect_b64 s[0:1], -1, 0
	s_waitcnt lgkmcnt(0)
	v_add_f32_e32 v122, v122, v123
	ds_bpermute_b32 v123, v156, v122
	v_cvt_pk_bf16_f32 v124, v168, v169
	v_cvt_pk_bf16_f32 v125, v166, v167
	v_lshl_add_u64 v[120:121], v[146:147], 1, v[120:121]
	s_and_b64 s[0:1], vcc, s[0:1]
	global_store_dwordx4 v[120:121], v[124:127], off
	s_and_saveexec_b64 s[30:31], s[0:1]
	s_cbranch_execz .LBB0_780
	s_cmp_lt_i32 s8, 2
	s_cselect_b32 s4, s67, s61
	s_cselect_b32 s5, s66, s60
	v_mov_b32_e32 v124, s5
	v_mov_b32_e32 v125, s4
	v_lshl_add_u64 v[124:125], v[144:145], 2, v[124:125]
	s_waitcnt lgkmcnt(0)
	v_add_f32_e32 v122, v122, v123
	global_atomic_add_f32 v[124:125], v122, off
.LBB0_780:
	s_or_b64 exec, exec, s[30:31]
	v_mov_b32_e32 v149, v148
	v_mov_b32_e32 v122, v148
	s_waitcnt lgkmcnt(0)
	v_mov_b32_e32 v123, v148
	v_pk_mul_f32 v[118:119], v[118:119], v[122:123]
	v_pk_mul_f32 v[122:123], v[114:115], v[122:123]
	v_pk_mul_f32 v[114:115], v[112:113], v[148:149]
	v_pk_mul_f32 v[116:117], v[116:117], v[148:149]
	v_mul_f32_e32 v113, v114, v114
	v_cvt_pk_bf16_f32 v112, v116, v117
	v_fmac_f32_e32 v113, v116, v116
	v_mul_f32_e32 v116, v115, v115
	v_fmac_f32_e32 v116, v117, v117
	v_add_f32_e32 v113, v113, v116
	v_mul_f32_e32 v116, v122, v122
	v_fmac_f32_e32 v116, v118, v118
	v_add_f32_e32 v113, v116, v113
	v_mul_f32_e32 v116, v123, v123
	v_fmac_f32_e32 v116, v119, v119
	v_add_f32_e32 v116, v116, v113
	ds_bpermute_b32 v117, v157, v116
	v_cvt_pk_bf16_f32 v113, v118, v119
	v_cvt_pk_bf16_f32 v114, v114, v115
	v_cvt_pk_bf16_f32 v115, v122, v123
	global_store_dwordx4 v[120:121], v[112:115], off offset:256
	s_lshl_b32 s4, s8, 1
	s_or_b32 s23, s4, 1
	s_waitcnt lgkmcnt(0)
	v_add_f32_e32 v112, v116, v117
	ds_bpermute_b32 v113, v156, v112
	s_cmp_lt_i32 s23, 5
	s_cselect_b64 s[4:5], -1, 0
	s_and_b64 s[30:31], vcc, s[4:5]
	s_and_saveexec_b64 s[34:35], s[30:31]
	s_cbranch_execz .LBB0_782
	s_cmp_lt_i32 s23, 3
	s_cselect_b32 s4, s67, s61
	s_cselect_b32 s5, s66, s60
	v_mov_b32_e32 v114, s5
	v_mov_b32_e32 v115, s4
	v_lshl_add_u64 v[114:115], v[144:145], 2, v[114:115]
	s_waitcnt lgkmcnt(0)
	v_add_f32_e32 v112, v112, v113
	global_atomic_add_f32 v[114:115], v112, off
.LBB0_782:
	s_or_b64 exec, exec, s[34:35]
	v_fmamk_f32 v112, v164, 0x3a800000, v155
	v_rsq_f32_e32 v112, v112
	s_waitcnt lgkmcnt(0)
	v_or_b32_e32 v113, 16, v144
	v_cndmask_b32_e64 v112, v112, 1.0, s[20:21]
	v_pk_mul_f32 v[104:105], v[104:105], v[112:113] op_sel_hi:[1,0]
	v_pk_mul_f32 v[114:115], v[108:109], v[112:113] op_sel_hi:[1,0]
	v_mul_f32_e32 v109, v104, v104
	v_cvt_pk_bf16_f32 v108, v114, v115
	v_fmac_f32_e32 v109, v114, v114
	v_mul_f32_e32 v114, v105, v105
	v_pk_mul_f32 v[106:107], v[106:107], v[112:113] op_sel_hi:[1,0]
	v_fmac_f32_e32 v114, v115, v115
	v_pk_mul_f32 v[110:111], v[110:111], v[112:113] op_sel_hi:[1,0]
	v_add_f32_e32 v109, v109, v114
	v_mul_f32_e32 v114, v106, v106
	v_fmac_f32_e32 v114, v110, v110
	v_add_f32_e32 v109, v114, v109
	v_mul_f32_e32 v114, v107, v107
	v_fmac_f32_e32 v114, v111, v111
	v_add_f32_e32 v114, v114, v109
	ds_bpermute_b32 v115, v157, v114
	v_cvt_pk_bf16_f32 v109, v110, v111
	v_cvt_pk_bf16_f32 v111, v106, v107
	v_cvt_pk_bf16_f32 v110, v104, v105
	v_mov_b64_e32 v[104:105], s[44:45]
	s_waitcnt lgkmcnt(0)
	v_add_f32_e32 v106, v114, v115
	ds_bpermute_b32 v107, v156, v106
	v_mad_i64_i32 v[104:105], s[4:5], v113, s82, v[104:105]
	v_lshl_add_u64 v[104:105], v[146:147], 1, v[104:105]
	global_store_dwordx4 v[104:105], v[108:111], off
	s_and_saveexec_b64 s[34:35], s[0:1]
	s_cbranch_execz .LBB0_784
	s_cmp_lt_i32 s8, 2
	s_cselect_b32 s4, s67, s61
	s_cselect_b32 s5, s66, s60
	v_mov_b32_e32 v108, s5
	v_mov_b32_e32 v109, s4
	v_lshl_add_u64 v[108:109], v[144:145], 2, v[108:109]
	s_waitcnt lgkmcnt(0)
	v_add_f32_e32 v106, v106, v107
	global_atomic_add_f32 v[108:109], v106, off offset:64
; __device__ __forceinline__ u32x4 pack8(f32x4 a, f32x4 b) { u32x4 w; w.x = pk2(a[0], a[1]); w.y = pk2(a[2], a[3]); w.z = pk2(b[0], b[1]); w.w = pk2(b[2], b[3]); return w; }
;     __device__ __forceinline__ void operator()(const Acc& acc, const pg8::Unit& u, int wid) const {
;     ...
;         for (int ai = 0; ai < 2; ++ai)
; #pragma unroll
;             for (int m = 0; m < 4; ++m) {
;                 const int row = row0 + ai * 128 + m * 16;
;                 const float sc = ssq ? __builtin_amdgcn_rsqf(scv[ai * 4 + m] * inv_n + EPS) : 1.f;
; #pragma unroll
;                 for (int bj = 0; bj < 2; ++bj) {
;                     f32x4 v0 = acc[ai][bj][m][0] * sc, v1 = acc[ai][bj][m][1] * sc;
;                     if (ACT == 1) {
; #pragma unroll
;                         for (int e = 0; e < 4; ++e) { float a = fmaxf(v0[e], 0.f), b = fmaxf(v1[e], 0.f); v0[e] = a * a; v1[e] = b * b; }
;                     }
;                     *(u32x4*)(O + (size_t)row * ldc + col0 + bj * 128) = pack8(v0, v1);
;                     if (SSQP) {
;                         float s = 0.f;
; #pragma unroll
;                         for (int e = 0; e < 4; ++e) s += v0[e] * v0[e] + v1[e] * v1[e];
;                         s += __shfl_xor(s, 16); s += __shfl_xor(s, 32);
;                         const int hidx = 2 * u.pn + bj;
;                         if (fq == 0 && hidx < 5) atomicAdd((hidx < 3 ? ssqA : ssqB) + row, s);
;                     }
.LBB0_784:
	s_or_b64 exec, exec, s[34:35]
	v_mov_b32_e32 v113, v112
	v_pk_mul_f32 v[108:109], v[96:97], v[112:113]
	v_mov_b32_e32 v106, v112
	s_waitcnt lgkmcnt(0)
	v_mov_b32_e32 v107, v112
	v_pk_mul_f32 v[100:101], v[100:101], v[112:113]
	v_mul_f32_e32 v96, v108, v108
	v_mul_f32_e32 v97, v109, v109
	v_pk_mul_f32 v[102:103], v[102:103], v[106:107]
	v_pk_mul_f32 v[106:107], v[98:99], v[106:107]
	v_fmac_f32_e32 v96, v100, v100
	v_fmac_f32_e32 v97, v101, v101
	v_add_f32_e32 v96, v96, v97
	v_mul_f32_e32 v97, v106, v106
	v_fmac_f32_e32 v97, v102, v102
	v_add_f32_e32 v96, v97, v96
	v_mul_f32_e32 v97, v107, v107
	v_fmac_f32_e32 v97, v103, v103
	v_add_f32_e32 v96, v97, v96
	ds_bpermute_b32 v97, v157, v96
	v_cvt_pk_bf16_f32 v98, v100, v101
	v_cvt_pk_bf16_f32 v99, v102, v103
	v_cvt_pk_bf16_f32 v100, v108, v109
	v_cvt_pk_bf16_f32 v101, v106, v107
	s_waitcnt lgkmcnt(0)
	v_add_f32_e32 v96, v96, v97
	ds_bpermute_b32 v97, v156, v96
	global_store_dwordx4 v[104:105], v[98:101], off offset:256
	s_and_saveexec_b64 s[34:35], s[30:31]
	s_cbranch_execz .LBB0_786
	s_cmp_lt_i32 s23, 3
	s_cselect_b32 s4, s67, s61
	s_cselect_b32 s5, s66, s60
	v_mov_b32_e32 v98, s5
	v_mov_b32_e32 v99, s4
	v_lshl_add_u64 v[98:99], v[144:145], 2, v[98:99]
	s_waitcnt lgkmcnt(0)
	v_add_f32_e32 v96, v96, v97
	global_atomic_add_f32 v[98:99], v96, off offset:64
.LBB0_786:
	s_or_b64 exec, exec, s[34:35]
	v_fmamk_f32 v96, v163, 0x3a800000, v155
	v_rsq_f32_e32 v96, v96
	s_waitcnt lgkmcnt(0)
	v_or_b32_e32 v97, 32, v144
	v_cndmask_b32_e64 v96, v96, 1.0, s[20:21]
	v_pk_mul_f32 v[88:89], v[88:89], v[96:97] op_sel_hi:[1,0]
	v_pk_mul_f32 v[98:99], v[92:93], v[96:97] op_sel_hi:[1,0]
	v_mul_f32_e32 v93, v88, v88
	v_cvt_pk_bf16_f32 v92, v98, v99
	v_fmac_f32_e32 v93, v98, v98
	v_mul_f32_e32 v98, v89, v89
	v_pk_mul_f32 v[90:91], v[90:91], v[96:97] op_sel_hi:[1,0]
	v_fmac_f32_e32 v98, v99, v99
	v_pk_mul_f32 v[94:95], v[94:95], v[96:97] op_sel_hi:[1,0]
	v_add_f32_e32 v93, v93, v98
	v_mul_f32_e32 v98, v90, v90
	v_fmac_f32_e32 v98, v94, v94
	v_add_f32_e32 v93, v98, v93
	v_mul_f32_e32 v98, v91, v91
	v_fmac_f32_e32 v98, v95, v95
	v_add_f32_e32 v98, v98, v93
	ds_bpermute_b32 v99, v157, v98
	v_cvt_pk_bf16_f32 v93, v94, v95
	v_cvt_pk_bf16_f32 v95, v90, v91
	v_cvt_pk_bf16_f32 v94, v88, v89
	v_mov_b64_e32 v[88:89], s[44:45]
	s_waitcnt lgkmcnt(0)
	v_add_f32_e32 v90, v98, v99
	ds_bpermute_b32 v91, v156, v90
	v_mad_i64_i32 v[88:89], s[4:5], v97, s82, v[88:89]
	v_lshl_add_u64 v[88:89], v[146:147], 1, v[88:89]
	global_store_dwordx4 v[88:89], v[92:95], off
	s_and_saveexec_b64 s[34:35], s[0:1]
	s_cbranch_execz .LBB0_788
	s_cmp_lt_i32 s8, 2
	s_cselect_b32 s4, s67, s61
	s_cselect_b32 s5, s66, s60
	v_mov_b32_e32 v92, s5
	v_mov_b32_e32 v93, s4
	v_lshl_add_u64 v[92:93], v[144:145], 2, v[92:93]
	s_waitcnt lgkmcnt(0)
	v_add_f32_e32 v90, v90, v91
	global_atomic_add_f32 v[92:93], v90, off offset:128
.LBB0_788:
	s_or_b64 exec, exec, s[34:35]
	v_mov_b32_e32 v97, v96
	v_pk_mul_f32 v[92:93], v[80:81], v[96:97]
	v_mov_b32_e32 v90, v96
	s_waitcnt lgkmcnt(0)
	v_mov_b32_e32 v91, v96
	v_pk_mul_f32 v[84:85], v[84:85], v[96:97]
	v_mul_f32_e32 v80, v92, v92
	v_mul_f32_e32 v81, v93, v93
	v_pk_mul_f32 v[86:87], v[86:87], v[90:91]
	v_pk_mul_f32 v[90:91], v[82:83], v[90:91]
	v_fmac_f32_e32 v80, v84, v84
	v_fmac_f32_e32 v81, v85, v85
	v_add_f32_e32 v80, v80, v81
	v_mul_f32_e32 v81, v90, v90
	v_fmac_f32_e32 v81, v86, v86
	v_add_f32_e32 v80, v81, v80
	v_mul_f32_e32 v81, v91, v91
	v_fmac_f32_e32 v81, v87, v87
	v_add_f32_e32 v80, v81, v80
	ds_bpermute_b32 v81, v157, v80
	v_cvt_pk_bf16_f32 v82, v84, v85
	v_cvt_pk_bf16_f32 v83, v86, v87
	v_cvt_pk_bf16_f32 v84, v92, v93
	v_cvt_pk_bf16_f32 v85, v90, v91
	s_waitcnt lgkmcnt(0)
	v_add_f32_e32 v80, v80, v81
	ds_bpermute_b32 v81, v156, v80
	global_store_dwordx4 v[88:89], v[82:85], off offset:256
	s_and_saveexec_b64 s[34:35], s[30:31]
	s_cbranch_execz .LBB0_790
	s_cmp_lt_i32 s23, 3
	s_cselect_b32 s4, s67, s61
	s_cselect_b32 s5, s66, s60
	v_mov_b32_e32 v82, s5
	v_mov_b32_e32 v83, s4
	v_lshl_add_u64 v[82:83], v[144:145], 2, v[82:83]
	s_waitcnt lgkmcnt(0)
	v_add_f32_e32 v80, v80, v81
	global_atomic_add_f32 v[82:83], v80, off offset:128
.LBB0_790:
	s_or_b64 exec, exec, s[34:35]
	v_fmamk_f32 v80, v162, 0x3a800000, v155
	v_rsq_f32_e32 v80, v80
	s_waitcnt lgkmcnt(0)
	v_or_b32_e32 v81, 48, v144
	v_cndmask_b32_e64 v80, v80, 1.0, s[20:21]
	v_pk_mul_f32 v[72:73], v[72:73], v[80:81] op_sel_hi:[1,0]
	v_pk_mul_f32 v[82:83], v[76:77], v[80:81] op_sel_hi:[1,0]
	v_mul_f32_e32 v77, v72, v72
	v_cvt_pk_bf16_f32 v76, v82, v83
	v_fmac_f32_e32 v77, v82, v82
	v_mul_f32_e32 v82, v73, v73
	v_pk_mul_f32 v[74:75], v[74:75], v[80:81] op_sel_hi:[1,0]
	v_fmac_f32_e32 v82, v83, v83
	v_pk_mul_f32 v[78:79], v[78:79], v[80:81] op_sel_hi:[1,0]
	v_add_f32_e32 v77, v77, v82
	v_mul_f32_e32 v82, v74, v74
	v_fmac_f32_e32 v82, v78, v78
	v_add_f32_e32 v77, v82, v77
	v_mul_f32_e32 v82, v75, v75
	v_fmac_f32_e32 v82, v79, v79
	v_add_f32_e32 v82, v82, v77
	ds_bpermute_b32 v83, v157, v82
	v_cvt_pk_bf16_f32 v77, v78, v79
	v_cvt_pk_bf16_f32 v79, v74, v75
	v_cvt_pk_bf16_f32 v78, v72, v73
	v_mov_b64_e32 v[72:73], s[44:45]
	s_waitcnt lgkmcnt(0)
	v_add_f32_e32 v74, v82, v83
	ds_bpermute_b32 v75, v156, v74
	v_mad_i64_i32 v[72:73], s[4:5], v81, s82, v[72:73]
	v_lshl_add_u64 v[72:73], v[146:147], 1, v[72:73]
	global_store_dwordx4 v[72:73], v[76:79], off
	s_and_saveexec_b64 s[34:35], s[0:1]
	s_cbranch_execz .LBB0_792
	s_cmp_lt_i32 s8, 2
	s_cselect_b32 s4, s67, s61
	s_cselect_b32 s5, s66, s60
	v_mov_b32_e32 v76, s5
	v_mov_b32_e32 v77, s4
	v_lshl_add_u64 v[76:77], v[144:145], 2, v[76:77]
	s_waitcnt lgkmcnt(0)
	v_add_f32_e32 v74, v74, v75
	global_atomic_add_f32 v[76:77], v74, off offset:192
; __device__ __forceinline__ u32x4 pack8(f32x4 a, f32x4 b) { u32x4 w; w.x = pk2(a[0], a[1]); w.y = pk2(a[2], a[3]); w.z = pk2(b[0], b[1]); w.w = pk2(b[2], b[3]); return w; }
;     __device__ __forceinline__ void operator()(const Acc& acc, const pg8::Unit& u, int wid) const {
;     ...
;         for (int ai = 0; ai < 2; ++ai)
; #pragma unroll
;             for (int m = 0; m < 4; ++m) {
;                 const int row = row0 + ai * 128 + m * 16;
;                 const float sc = ssq ? __builtin_amdgcn_rsqf(scv[ai * 4 + m] * inv_n + EPS) : 1.f;
; #pragma unroll
;                 for (int bj = 0; bj < 2; ++bj) {
;                     f32x4 v0 = acc[ai][bj][m][0] * sc, v1 = acc[ai][bj][m][1] * sc;
;                     if (ACT == 1) {
; #pragma unroll
;                         for (int e = 0; e < 4; ++e) { float a = fmaxf(v0[e], 0.f), b = fmaxf(v1[e], 0.f); v0[e] = a * a; v1[e] = b * b; }
;                     }
;                     *(u32x4*)(O + (size_t)row * ldc + col0 + bj * 128) = pack8(v0, v1);
;                     if (SSQP) {
;                         float s = 0.f;
; #pragma unroll
;                         for (int e = 0; e < 4; ++e) s += v0[e] * v0[e] + v1[e] * v1[e];
;                         s += __shfl_xor(s, 16); s += __shfl_xor(s, 32);
;                         const int hidx = 2 * u.pn + bj;
;                         if (fq == 0 && hidx < 5) atomicAdd((hidx < 3 ? ssqA : ssqB) + row, s);
;                     }
.LBB0_792:
	s_or_b64 exec, exec, s[34:35]
	v_mov_b32_e32 v81, v80
	v_pk_mul_f32 v[76:77], v[64:65], v[80:81]
	v_mov_b32_e32 v74, v80
	s_waitcnt lgkmcnt(0)
	v_mov_b32_e32 v75, v80
	v_pk_mul_f32 v[68:69], v[68:69], v[80:81]
	v_mul_f32_e32 v64, v76, v76
	v_mul_f32_e32 v65, v77, v77
	v_pk_mul_f32 v[70:71], v[70:71], v[74:75]
	v_pk_mul_f32 v[74:75], v[66:67], v[74:75]
	v_fmac_f32_e32 v64, v68, v68
	v_fmac_f32_e32 v65, v69, v69
	v_add_f32_e32 v64, v64, v65
	v_mul_f32_e32 v65, v74, v74
	v_fmac_f32_e32 v65, v70, v70
	v_add_f32_e32 v64, v65, v64
	v_mul_f32_e32 v65, v75, v75
	v_fmac_f32_e32 v65, v71, v71
	v_add_f32_e32 v64, v65, v64
	ds_bpermute_b32 v65, v157, v64
	v_cvt_pk_bf16_f32 v66, v68, v69
	v_cvt_pk_bf16_f32 v67, v70, v71
	v_cvt_pk_bf16_f32 v68, v76, v77
	v_cvt_pk_bf16_f32 v69, v74, v75
	s_waitcnt lgkmcnt(0)
	v_add_f32_e32 v64, v64, v65
	ds_bpermute_b32 v65, v156, v64
	global_store_dwordx4 v[72:73], v[66:69], off offset:256
	s_and_saveexec_b64 s[34:35], s[30:31]
	s_cbranch_execz .LBB0_794
	s_cmp_lt_i32 s23, 3
	s_cselect_b32 s4, s67, s61
	s_cselect_b32 s5, s66, s60
	v_mov_b32_e32 v66, s5
	v_mov_b32_e32 v67, s4
	v_lshl_add_u64 v[66:67], v[144:145], 2, v[66:67]
	s_waitcnt lgkmcnt(0)
	v_add_f32_e32 v64, v64, v65
	global_atomic_add_f32 v[66:67], v64, off offset:192
.LBB0_794:
	s_or_b64 exec, exec, s[34:35]
	v_fmamk_f32 v64, v161, 0x3a800000, v155
	v_rsq_f32_e32 v64, v64
	s_waitcnt lgkmcnt(0)
	v_add_u32_e32 v65, 0x80, v144
	v_cndmask_b32_e64 v64, v64, 1.0, s[20:21]
	v_pk_mul_f32 v[56:57], v[56:57], v[64:65] op_sel_hi:[1,0]
	v_pk_mul_f32 v[66:67], v[60:61], v[64:65] op_sel_hi:[1,0]
	v_mul_f32_e32 v61, v56, v56
	v_cvt_pk_bf16_f32 v60, v66, v67
	v_fmac_f32_e32 v61, v66, v66
	v_mul_f32_e32 v66, v57, v57
	v_pk_mul_f32 v[58:59], v[58:59], v[64:65] op_sel_hi:[1,0]
	v_fmac_f32_e32 v66, v67, v67
	v_pk_mul_f32 v[62:63], v[62:63], v[64:65] op_sel_hi:[1,0]
	v_add_f32_e32 v61, v61, v66
	v_mul_f32_e32 v66, v58, v58
	v_fmac_f32_e32 v66, v62, v62
	v_add_f32_e32 v61, v66, v61
	v_mul_f32_e32 v66, v59, v59
	v_fmac_f32_e32 v66, v63, v63
	v_add_f32_e32 v66, v66, v61
	ds_bpermute_b32 v67, v157, v66
	v_cvt_pk_bf16_f32 v61, v62, v63
	v_cvt_pk_bf16_f32 v63, v58, v59
	v_cvt_pk_bf16_f32 v62, v56, v57
	v_mov_b64_e32 v[56:57], s[44:45]
	s_waitcnt lgkmcnt(0)
	v_add_f32_e32 v58, v66, v67
	ds_bpermute_b32 v59, v156, v58
	v_mad_i64_i32 v[56:57], s[4:5], v65, s82, v[56:57]
	v_lshl_add_u64 v[56:57], v[146:147], 1, v[56:57]
	global_store_dwordx4 v[56:57], v[60:63], off
	s_and_saveexec_b64 s[34:35], s[0:1]
	s_cbranch_execz .LBB0_796
	s_cmp_lt_i32 s8, 2
	s_cselect_b32 s4, s67, s61
	s_cselect_b32 s5, s66, s60
	v_mov_b32_e32 v60, s5
	v_mov_b32_e32 v61, s4
	v_lshl_add_u64 v[60:61], v[144:145], 2, v[60:61]
	s_waitcnt lgkmcnt(0)
	v_add_f32_e32 v58, v58, v59
	global_atomic_add_f32 v[60:61], v58, off offset:512
.LBB0_796:
	s_or_b64 exec, exec, s[34:35]
	v_mov_b32_e32 v65, v64
	v_pk_mul_f32 v[60:61], v[48:49], v[64:65]
	v_mov_b32_e32 v58, v64
	s_waitcnt lgkmcnt(0)
	v_mov_b32_e32 v59, v64
	v_pk_mul_f32 v[52:53], v[52:53], v[64:65]
	v_mul_f32_e32 v48, v60, v60
	v_mul_f32_e32 v49, v61, v61
	v_pk_mul_f32 v[54:55], v[54:55], v[58:59]
	v_pk_mul_f32 v[58:59], v[50:51], v[58:59]
	v_fmac_f32_e32 v48, v52, v52
	v_fmac_f32_e32 v49, v53, v53
	v_add_f32_e32 v48, v48, v49
	v_mul_f32_e32 v49, v58, v58
	v_fmac_f32_e32 v49, v54, v54
	v_add_f32_e32 v48, v49, v48
	v_mul_f32_e32 v49, v59, v59
	v_fmac_f32_e32 v49, v55, v55
	v_add_f32_e32 v48, v49, v48
	ds_bpermute_b32 v49, v157, v48
	v_cvt_pk_bf16_f32 v50, v52, v53
	v_cvt_pk_bf16_f32 v51, v54, v55
	v_cvt_pk_bf16_f32 v52, v60, v61
	v_cvt_pk_bf16_f32 v53, v58, v59
	s_waitcnt lgkmcnt(0)
	v_add_f32_e32 v48, v48, v49
	ds_bpermute_b32 v49, v156, v48
	global_store_dwordx4 v[56:57], v[50:53], off offset:256
	s_and_saveexec_b64 s[34:35], s[30:31]
	s_cbranch_execz .LBB0_798
	s_cmp_lt_i32 s23, 3
	s_cselect_b32 s4, s67, s61
	s_cselect_b32 s5, s66, s60
	v_mov_b32_e32 v50, s5
	v_mov_b32_e32 v51, s4
	v_lshl_add_u64 v[50:51], v[144:145], 2, v[50:51]
	s_waitcnt lgkmcnt(0)
	v_add_f32_e32 v48, v48, v49
	global_atomic_add_f32 v[50:51], v48, off offset:512
.LBB0_798:
	s_or_b64 exec, exec, s[34:35]
	v_fmamk_f32 v48, v160, 0x3a800000, v155
	v_rsq_f32_e32 v48, v48
	s_waitcnt lgkmcnt(0)
	v_add_u32_e32 v49, 0x90, v144
	v_cndmask_b32_e64 v48, v48, 1.0, s[20:21]
	v_pk_mul_f32 v[40:41], v[40:41], v[48:49] op_sel_hi:[1,0]
	v_pk_mul_f32 v[50:51], v[44:45], v[48:49] op_sel_hi:[1,0]
	v_mul_f32_e32 v45, v40, v40
	v_cvt_pk_bf16_f32 v44, v50, v51
	v_fmac_f32_e32 v45, v50, v50
	v_mul_f32_e32 v50, v41, v41
	v_pk_mul_f32 v[42:43], v[42:43], v[48:49] op_sel_hi:[1,0]
	v_fmac_f32_e32 v50, v51, v51
	v_pk_mul_f32 v[46:47], v[46:47], v[48:49] op_sel_hi:[1,0]
	v_add_f32_e32 v45, v45, v50
	v_mul_f32_e32 v50, v42, v42
	v_fmac_f32_e32 v50, v46, v46
	v_add_f32_e32 v45, v50, v45
	v_mul_f32_e32 v50, v43, v43
	v_fmac_f32_e32 v50, v47, v47
	v_add_f32_e32 v50, v50, v45
	ds_bpermute_b32 v51, v157, v50
	v_cvt_pk_bf16_f32 v45, v46, v47
	v_cvt_pk_bf16_f32 v47, v42, v43
	v_cvt_pk_bf16_f32 v46, v40, v41
	v_mov_b64_e32 v[40:41], s[44:45]
	s_waitcnt lgkmcnt(0)
	v_add_f32_e32 v42, v50, v51
	ds_bpermute_b32 v43, v156, v42
	v_mad_i64_i32 v[40:41], s[4:5], v49, s82, v[40:41]
	v_lshl_add_u64 v[40:41], v[146:147], 1, v[40:41]
	global_store_dwordx4 v[40:41], v[44:47], off
	s_and_saveexec_b64 s[34:35], s[0:1]
	s_cbranch_execz .LBB0_800
	s_cmp_lt_i32 s8, 2
	s_cselect_b32 s4, s67, s61
	s_cselect_b32 s5, s66, s60
	v_mov_b32_e32 v44, s5
	v_mov_b32_e32 v45, s4
	v_lshl_add_u64 v[44:45], v[144:145], 2, v[44:45]
	s_waitcnt lgkmcnt(0)
	v_add_f32_e32 v42, v42, v43
	global_atomic_add_f32 v[44:45], v42, off offset:576
; __device__ __forceinline__ u32x4 pack8(f32x4 a, f32x4 b) { u32x4 w; w.x = pk2(a[0], a[1]); w.y = pk2(a[2], a[3]); w.z = pk2(b[0], b[1]); w.w = pk2(b[2], b[3]); return w; }
;     __device__ __forceinline__ void operator()(const Acc& acc, const pg8::Unit& u, int wid) const {
;     ...
;                 const int row = row0 + ai * 128 + m * 16;
;                 const float sc = ssq ? __builtin_amdgcn_rsqf(scv[ai * 4 + m] * inv_n + EPS) : 1.f;
; #pragma unroll
;                 for (int bj = 0; bj < 2; ++bj) {
;                     f32x4 v0 = acc[ai][bj][m][0] * sc, v1 = acc[ai][bj][m][1] * sc;
;                     if (ACT == 1) {
; #pragma unroll
;                         for (int e = 0; e < 4; ++e) { float a = fmaxf(v0[e], 0.f), b = fmaxf(v1[e], 0.f); v0[e] = a * a; v1[e] = b * b; }
;                     }
;                     *(u32x4*)(O + (size_t)row * ldc + col0 + bj * 128) = pack8(v0, v1);
;                     if (SSQP) {
;                         float s = 0.f;
; #pragma unroll
;                         for (int e = 0; e < 4; ++e) s += v0[e] * v0[e] + v1[e] * v1[e];
;                         s += __shfl_xor(s, 16); s += __shfl_xor(s, 32);
;                         const int hidx = 2 * u.pn + bj;
;                         if (fq == 0 && hidx < 5) atomicAdd((hidx < 3 ? ssqA : ssqB) + row, s);
;                     }
.LBB0_800:
	s_or_b64 exec, exec, s[34:35]
	v_mov_b32_e32 v49, v48
	v_pk_mul_f32 v[44:45], v[32:33], v[48:49]
	v_mov_b32_e32 v42, v48
	s_waitcnt lgkmcnt(0)
	v_mov_b32_e32 v43, v48
	v_pk_mul_f32 v[36:37], v[36:37], v[48:49]
	v_mul_f32_e32 v32, v44, v44
	v_mul_f32_e32 v33, v45, v45
	v_pk_mul_f32 v[38:39], v[38:39], v[42:43]
	v_pk_mul_f32 v[42:43], v[34:35], v[42:43]
	v_fmac_f32_e32 v32, v36, v36
	v_fmac_f32_e32 v33, v37, v37
	v_add_f32_e32 v32, v32, v33
	v_mul_f32_e32 v33, v42, v42
	v_fmac_f32_e32 v33, v38, v38
	v_add_f32_e32 v32, v33, v32
	v_mul_f32_e32 v33, v43, v43
	v_fmac_f32_e32 v33, v39, v39
	v_add_f32_e32 v32, v33, v32
	ds_bpermute_b32 v33, v157, v32
	v_cvt_pk_bf16_f32 v34, v36, v37
	v_cvt_pk_bf16_f32 v35, v38, v39
	v_cvt_pk_bf16_f32 v36, v44, v45
	v_cvt_pk_bf16_f32 v37, v42, v43
	s_waitcnt lgkmcnt(0)
	v_add_f32_e32 v32, v32, v33
	ds_bpermute_b32 v33, v156, v32
	global_store_dwordx4 v[40:41], v[34:37], off offset:256
	s_and_saveexec_b64 s[34:35], s[30:31]
	s_cbranch_execz .LBB0_802
	s_cmp_lt_i32 s23, 3
	s_cselect_b32 s4, s67, s61
	s_cselect_b32 s5, s66, s60
	v_mov_b32_e32 v34, s5
	v_mov_b32_e32 v35, s4
	v_lshl_add_u64 v[34:35], v[144:145], 2, v[34:35]
	s_waitcnt lgkmcnt(0)
	v_add_f32_e32 v32, v32, v33
	global_atomic_add_f32 v[34:35], v32, off offset:576
.LBB0_802:
	s_or_b64 exec, exec, s[34:35]
	v_fmamk_f32 v32, v159, 0x3a800000, v155
	v_rsq_f32_e32 v32, v32
	s_waitcnt lgkmcnt(0)
	v_add_u32_e32 v33, 0xa0, v144
	v_cndmask_b32_e64 v32, v32, 1.0, s[20:21]
	v_pk_mul_f32 v[24:25], v[24:25], v[32:33] op_sel_hi:[1,0]
	v_pk_mul_f32 v[34:35], v[28:29], v[32:33] op_sel_hi:[1,0]
	v_mul_f32_e32 v29, v24, v24
	v_cvt_pk_bf16_f32 v28, v34, v35
	v_fmac_f32_e32 v29, v34, v34
	v_mul_f32_e32 v34, v25, v25
	v_pk_mul_f32 v[26:27], v[26:27], v[32:33] op_sel_hi:[1,0]
	v_fmac_f32_e32 v34, v35, v35
	v_pk_mul_f32 v[30:31], v[30:31], v[32:33] op_sel_hi:[1,0]
	v_add_f32_e32 v29, v29, v34
	v_mul_f32_e32 v34, v26, v26
	v_fmac_f32_e32 v34, v30, v30
	v_add_f32_e32 v29, v34, v29
	v_mul_f32_e32 v34, v27, v27
	v_fmac_f32_e32 v34, v31, v31
	v_add_f32_e32 v34, v34, v29
	ds_bpermute_b32 v35, v157, v34
	v_cvt_pk_bf16_f32 v29, v30, v31
	v_cvt_pk_bf16_f32 v31, v26, v27
	v_cvt_pk_bf16_f32 v30, v24, v25
	v_mov_b64_e32 v[24:25], s[44:45]
	s_waitcnt lgkmcnt(0)
	v_add_f32_e32 v26, v34, v35
	ds_bpermute_b32 v27, v156, v26
	v_mad_i64_i32 v[24:25], s[4:5], v33, s82, v[24:25]
	v_lshl_add_u64 v[24:25], v[146:147], 1, v[24:25]
	global_store_dwordx4 v[24:25], v[28:31], off
	s_and_saveexec_b64 s[34:35], s[0:1]
	s_cbranch_execz .LBB0_804
	s_cmp_lt_i32 s8, 2
	s_cselect_b32 s4, s67, s61
	s_cselect_b32 s5, s66, s60
	v_mov_b32_e32 v28, s5
	v_mov_b32_e32 v29, s4
	v_lshl_add_u64 v[28:29], v[144:145], 2, v[28:29]
	s_waitcnt lgkmcnt(0)
	v_add_f32_e32 v26, v26, v27
	global_atomic_add_f32 v[28:29], v26, off offset:640
.LBB0_804:
	s_or_b64 exec, exec, s[34:35]
	v_mov_b32_e32 v33, v32
	v_pk_mul_f32 v[28:29], v[16:17], v[32:33]
	v_mov_b32_e32 v26, v32
	s_waitcnt lgkmcnt(0)
	v_mov_b32_e32 v27, v32
	v_pk_mul_f32 v[20:21], v[20:21], v[32:33]
	v_mul_f32_e32 v16, v28, v28
	v_mul_f32_e32 v17, v29, v29
	v_pk_mul_f32 v[22:23], v[22:23], v[26:27]
	v_pk_mul_f32 v[26:27], v[18:19], v[26:27]
	v_fmac_f32_e32 v16, v20, v20
	v_fmac_f32_e32 v17, v21, v21
	v_add_f32_e32 v16, v16, v17
	v_mul_f32_e32 v17, v26, v26
	v_fmac_f32_e32 v17, v22, v22
	v_add_f32_e32 v16, v17, v16
	v_mul_f32_e32 v17, v27, v27
	v_fmac_f32_e32 v17, v23, v23
	v_add_f32_e32 v16, v17, v16
	ds_bpermute_b32 v17, v157, v16
	v_cvt_pk_bf16_f32 v18, v20, v21
	v_cvt_pk_bf16_f32 v19, v22, v23
	v_cvt_pk_bf16_f32 v20, v28, v29
	v_cvt_pk_bf16_f32 v21, v26, v27
	s_waitcnt lgkmcnt(0)
	v_add_f32_e32 v16, v16, v17
	ds_bpermute_b32 v17, v156, v16
	global_store_dwordx4 v[24:25], v[18:21], off offset:256
	s_and_saveexec_b64 s[34:35], s[30:31]
	s_cbranch_execz .LBB0_806
	s_cmp_lt_i32 s23, 3
	s_cselect_b32 s4, s67, s61
	s_cselect_b32 s5, s66, s60
	v_mov_b32_e32 v18, s5
	v_mov_b32_e32 v19, s4
	v_lshl_add_u64 v[18:19], v[144:145], 2, v[18:19]
	s_waitcnt lgkmcnt(0)
	v_add_f32_e32 v16, v16, v17
	global_atomic_add_f32 v[18:19], v16, off offset:640
.LBB0_806:
	s_or_b64 exec, exec, s[34:35]
	v_fmamk_f32 v16, v158, 0x3a800000, v155
	v_rsq_f32_e32 v16, v16
	s_waitcnt lgkmcnt(0)
	v_add_u32_e32 v17, 0xb0, v144
	v_cndmask_b32_e64 v16, v16, 1.0, s[20:21]
	v_pk_mul_f32 v[8:9], v[8:9], v[16:17] op_sel_hi:[1,0]
	v_pk_mul_f32 v[18:19], v[12:13], v[16:17] op_sel_hi:[1,0]
	v_mul_f32_e32 v13, v8, v8
	v_cvt_pk_bf16_f32 v12, v18, v19
	v_fmac_f32_e32 v13, v18, v18
	v_mul_f32_e32 v18, v9, v9
	v_pk_mul_f32 v[10:11], v[10:11], v[16:17] op_sel_hi:[1,0]
	v_fmac_f32_e32 v18, v19, v19
	v_pk_mul_f32 v[14:15], v[14:15], v[16:17] op_sel_hi:[1,0]
	v_add_f32_e32 v13, v13, v18
	v_mul_f32_e32 v18, v10, v10
	v_fmac_f32_e32 v18, v14, v14
	v_add_f32_e32 v13, v18, v13
	v_mul_f32_e32 v18, v11, v11
	v_fmac_f32_e32 v18, v15, v15
	v_add_f32_e32 v18, v18, v13
	ds_bpermute_b32 v19, v157, v18
	v_cvt_pk_bf16_f32 v13, v14, v15
	v_cvt_pk_bf16_f32 v15, v10, v11
	v_cvt_pk_bf16_f32 v14, v8, v9
	v_mov_b64_e32 v[8:9], s[44:45]
	s_waitcnt lgkmcnt(0)
	v_add_f32_e32 v10, v18, v19
	ds_bpermute_b32 v11, v156, v10
	v_mad_i64_i32 v[8:9], s[4:5], v17, s82, v[8:9]
	v_lshl_add_u64 v[8:9], v[146:147], 1, v[8:9]
	global_store_dwordx4 v[8:9], v[12:15], off
	s_and_saveexec_b64 s[34:35], s[0:1]
	s_cbranch_execz .LBB0_808
	s_cmp_lt_i32 s8, 2
	s_cselect_b32 s0, s67, s61
	s_cselect_b32 s1, s66, s60
	v_mov_b32_e32 v12, s1
	v_mov_b32_e32 v13, s0
	v_lshl_add_u64 v[12:13], v[144:145], 2, v[12:13]
	s_waitcnt lgkmcnt(0)
	v_add_f32_e32 v10, v10, v11
	global_atomic_add_f32 v[12:13], v10, off offset:704
.LBB0_808:
	s_or_b64 exec, exec, s[34:35]
	v_mov_b32_e32 v17, v16
	v_pk_mul_f32 v[12:13], v[0:1], v[16:17]
	v_mov_b32_e32 v10, v16
	s_waitcnt lgkmcnt(0)
	v_mov_b32_e32 v11, v16
	v_pk_mul_f32 v[4:5], v[4:5], v[16:17]
	v_mul_f32_e32 v0, v12, v12
	v_mul_f32_e32 v1, v13, v13
	v_pk_mul_f32 v[6:7], v[6:7], v[10:11]
	v_pk_mul_f32 v[10:11], v[2:3], v[10:11]
	v_fmac_f32_e32 v0, v4, v4
	v_fmac_f32_e32 v1, v5, v5
	v_add_f32_e32 v0, v0, v1
	v_mul_f32_e32 v1, v10, v10
	v_fmac_f32_e32 v1, v6, v6
	v_add_f32_e32 v0, v1, v0
	v_mul_f32_e32 v1, v11, v11
	v_fmac_f32_e32 v1, v7, v7
	v_add_f32_e32 v0, v1, v0
	ds_bpermute_b32 v1, v157, v0
	v_cvt_pk_bf16_f32 v2, v4, v5
	v_cvt_pk_bf16_f32 v3, v6, v7
	v_cvt_pk_bf16_f32 v4, v12, v13
	v_cvt_pk_bf16_f32 v5, v10, v11
	s_waitcnt lgkmcnt(0)
	v_add_f32_e32 v0, v0, v1
	ds_bpermute_b32 v1, v156, v0
	global_store_dwordx4 v[8:9], v[2:5], off offset:256
	s_and_saveexec_b64 s[0:1], s[30:31]
	s_cbranch_execz .LBB0_810
	s_cmp_lt_i32 s23, 3
	s_cselect_b32 s4, s67, s61
	s_cselect_b32 s5, s66, s60
	v_mov_b32_e32 v2, s5
	v_mov_b32_e32 v3, s4
	v_lshl_add_u64 v[2:3], v[144:145], 2, v[2:3]
	s_waitcnt lgkmcnt(0)
	v_add_f32_e32 v0, v0, v1
	global_atomic_add_f32 v[2:3], v0, off offset:704

; __device__ __forceinline__ u32x4 pack8(f32x4 a, f32x4 b) { u32x4 w; w.x = pk2(a[0], a[1]); w.y = pk2(a[2], a[3]); w.z = pk2(b[0], b[1]); w.w = pk2(b[2], b[3]); return w; }
;     __device__ __forceinline__ void operator()(const Acc& acc, const pg8::Unit& u, int wid) const {
;     ...
;         for (int ai = 0; ai < 2; ++ai)
; #pragma unroll
;             for (int m = 0; m < 4; ++m) {
;                 const int row = row0 + ai * 128 + m * 16;
;                 const float sc = ssq ? __builtin_amdgcn_rsqf(scv[ai * 4 + m] * inv_n + EPS) : 1.f;
; #pragma unroll
;                 for (int bj = 0; bj < 2; ++bj) {
;                     f32x4 v0 = acc[ai][bj][m][0] * sc, v1 = acc[ai][bj][m][1] * sc;
;                     if (ACT == 1) {
; #pragma unroll
;                         for (int e = 0; e < 4; ++e) { float a = fmaxf(v0[e], 0.f), b = fmaxf(v1[e], 0.f); v0[e] = a * a; v1[e] = b * b; }
;                     }
;                     *(u32x4*)(O + (size_t)row * ldc + col0 + bj * 128) = pack8(v0, v1);
.LBB0_874:
	s_lshl_b32 s4, s75, 8
	v_mbcnt_lo_u32_b32 v148, -1, 0
	v_mbcnt_hi_u32_b32 v148, -1, v148
	s_add_i32 s4, s4, s63
	v_and_or_b32 v150, v148, 15, s4
	v_ashrrev_i32_e32 v148, 1, v148
	s_lshl_b32 s4, s78, 8
	v_and_b32_e32 v148, -8, v148
	s_or_b32 s4, s4, s69
	v_add_u32_e32 v148, s4, v148
	v_add_u32_e32 v151, 0x80, v150
	v_ashrrev_i32_e32 v149, 31, v148
	v_cvt_pk_bf16_f32 v124, v124, v125
	v_cvt_pk_bf16_f32 v125, v126, v127
	v_cvt_pk_bf16_f32 v126, v120, v121
	v_mov_b64_e32 v[120:121], s[58:59]
	v_cvt_pk_bf16_f32 v127, v122, v123
	v_mad_i64_i32 v[122:123], s[4:5], v150, s74, v[120:121]
	v_lshlrev_b64 v[148:149], 1, v[148:149]
	v_cvt_pk_bf16_f32 v60, v60, v61
	v_cvt_pk_bf16_f32 v61, v62, v63
	v_cvt_pk_bf16_f32 v62, v56, v57
	v_mad_i64_i32 v[56:57], s[4:5], v151, s74, v[120:121]
	v_lshl_add_u64 v[122:123], v[122:123], 0, v[148:149]
	v_cvt_pk_bf16_f32 v108, v108, v109
	v_cvt_pk_bf16_f32 v109, v110, v111
	v_cvt_pk_bf16_f32 v110, v104, v105
	v_cvt_pk_bf16_f32 v111, v106, v107
	v_lshl_add_u64 v[56:57], v[56:57], 0, v[148:149]
	v_cvt_pk_bf16_f32 v44, v44, v45
	v_cvt_pk_bf16_f32 v45, v46, v47
	v_cvt_pk_bf16_f32 v46, v40, v41
	v_cvt_pk_bf16_f32 v47, v42, v43
	global_store_dwordx4 v[122:123], v[108:111], off offset:256
	global_store_dwordx4 v[56:57], v[44:47], off offset:256
	v_cvt_pk_bf16_f32 v92, v92, v93
	v_or_b32_e32 v108, 16, v150
	v_add_u32_e32 v44, 0x90, v150
	v_mad_i64_i32 v[108:109], s[4:5], v108, s74, v[120:121]
	v_mad_i64_i32 v[44:45], s[4:5], v44, s74, v[120:121]
	v_lshl_add_u64 v[108:109], v[108:109], 0, v[148:149]
	v_cvt_pk_bf16_f32 v93, v94, v95
	v_cvt_pk_bf16_f32 v94, v88, v89
	v_cvt_pk_bf16_f32 v95, v90, v91
	v_lshl_add_u64 v[44:45], v[44:45], 0, v[148:149]
	v_cvt_pk_bf16_f32 v28, v28, v29
	v_cvt_pk_bf16_f32 v29, v30, v31
	v_cvt_pk_bf16_f32 v30, v24, v25
	v_cvt_pk_bf16_f32 v31, v26, v27
	global_store_dwordx4 v[108:109], v[92:95], off offset:256
	global_store_dwordx4 v[44:45], v[28:31], off offset:256
	v_cvt_pk_bf16_f32 v76, v76, v77
	v_or_b32_e32 v92, 32, v150
	v_add_u32_e32 v28, 0xa0, v150
	v_mad_i64_i32 v[92:93], s[4:5], v92, s74, v[120:121]
	v_mad_i64_i32 v[28:29], s[4:5], v28, s74, v[120:121]
	v_lshl_add_u64 v[92:93], v[92:93], 0, v[148:149]
	v_cvt_pk_bf16_f32 v77, v78, v79
	v_cvt_pk_bf16_f32 v78, v72, v73
	v_cvt_pk_bf16_f32 v79, v74, v75
	v_lshl_add_u64 v[28:29], v[28:29], 0, v[148:149]
	v_cvt_pk_bf16_f32 v12, v12, v13
	v_cvt_pk_bf16_f32 v13, v14, v15
	v_cvt_pk_bf16_f32 v14, v8, v9
	v_cvt_pk_bf16_f32 v15, v10, v11
	global_store_dwordx4 v[92:93], v[76:79], off offset:256
	global_store_dwordx4 v[28:29], v[12:15], off offset:256
	v_cvt_pk_bf16_f32 v104, v116, v117
	v_or_b32_e32 v76, 48, v150
	v_add_u32_e32 v12, 0xb0, v150
	v_mad_i64_i32 v[76:77], s[4:5], v76, s74, v[120:121]
	v_mad_i64_i32 v[12:13], s[4:5], v12, s74, v[120:121]
	v_cvt_pk_bf16_f32 v105, v118, v119
	v_cvt_pk_bf16_f32 v106, v112, v113
	v_cvt_pk_bf16_f32 v107, v114, v115
	v_cvt_pk_bf16_f32 v88, v100, v101
	v_cvt_pk_bf16_f32 v89, v102, v103
	v_cvt_pk_bf16_f32 v90, v96, v97
	v_cvt_pk_bf16_f32 v91, v98, v99
	v_cvt_pk_bf16_f32 v72, v84, v85
	v_cvt_pk_bf16_f32 v73, v86, v87
	v_cvt_pk_bf16_f32 v74, v80, v81
	v_cvt_pk_bf16_f32 v75, v82, v83
	v_lshl_add_u64 v[76:77], v[76:77], 0, v[148:149]
	v_cvt_pk_bf16_f32 v68, v68, v69
	v_cvt_pk_bf16_f32 v69, v70, v71
	v_cvt_pk_bf16_f32 v70, v64, v65
	v_cvt_pk_bf16_f32 v71, v66, v67
	v_cvt_pk_bf16_f32 v63, v58, v59
	v_cvt_pk_bf16_f32 v40, v52, v53
	v_cvt_pk_bf16_f32 v41, v54, v55
	v_cvt_pk_bf16_f32 v42, v48, v49
	v_cvt_pk_bf16_f32 v43, v50, v51
	v_cvt_pk_bf16_f32 v24, v36, v37
	v_cvt_pk_bf16_f32 v25, v38, v39
	v_cvt_pk_bf16_f32 v26, v32, v33
	v_cvt_pk_bf16_f32 v27, v34, v35
	v_cvt_pk_bf16_f32 v8, v20, v21
	v_cvt_pk_bf16_f32 v9, v22, v23
	v_cvt_pk_bf16_f32 v10, v16, v17
	v_cvt_pk_bf16_f32 v11, v18, v19
	v_lshl_add_u64 v[12:13], v[12:13], 0, v[148:149]
	v_cvt_pk_bf16_f32 v4, v4, v5
	v_cvt_pk_bf16_f32 v5, v6, v7
	v_cvt_pk_bf16_f32 v6, v0, v1
	v_cvt_pk_bf16_f32 v7, v2, v3
	s_and_b64 vcc, exec, s[6:7]
	s_mov_b64 s[6:7], -1
	global_store_dwordx4 v[122:123], v[124:127], off
	global_store_dwordx4 v[108:109], v[104:107], off
	global_store_dwordx4 v[92:93], v[88:91], off
	global_store_dwordx4 v[76:77], v[72:75], off
	global_store_dwordx4 v[76:77], v[68:71], off offset:256
	global_store_dwordx4 v[56:57], v[60:63], off
	global_store_dwordx4 v[44:45], v[40:43], off
	global_store_dwordx4 v[28:29], v[24:27], off
	global_store_dwordx4 v[12:13], v[8:11], off
	global_store_dwordx4 v[12:13], v[4:7], off offset:256
	s_cbranch_vccnz .LBB0_863
	s_andn2_b64 vcc, exec, s[0:1]
	s_cbranch_vccnz .LBB0_862
	s_barrier
	s_branch .LBB0_862

; __device__ __forceinline__ u32x4 pack8(f32x4 a, f32x4 b) { u32x4 w; w.x = pk2(a[0], a[1]); w.y = pk2(a[2], a[3]); w.z = pk2(b[0], b[1]); w.w = pk2(b[2], b[3]); return w; }
;     __device__ __forceinline__ void operator()(const Acc& acc, const pg8::Unit& u, int wid) const {
;     ...
;         const int row0 = u.pm * 256 + wr * 64 + fr, col0 = u.pn * 256 + wc * 32 + 8 * fq;
;         float scv[8];
; #pragma unroll
;         for (int i = 0; i < 8; ++i) scv[i] = ssq ? ssq[row0 + (i >> 2) * 128 + (i & 3) * 16] : 0.f;
; #pragma unroll
;         for (int ai = 0; ai < 2; ++ai)
; #pragma unroll
;             for (int m = 0; m < 4; ++m) {
;                 const int row = row0 + ai * 128 + m * 16;
;                 const float sc = ssq ? __builtin_amdgcn_rsqf(scv[ai * 4 + m] * inv_n + EPS) : 1.f;
; #pragma unroll
;                 for (int bj = 0; bj < 2; ++bj) {
;                     f32x4 v0 = acc[ai][bj][m][0] * sc, v1 = acc[ai][bj][m][1] * sc;
;                     if (ACT == 1) {
; #pragma unroll
;                         for (int e = 0; e < 4; ++e) { float a = fmaxf(v0[e], 0.f), b = fmaxf(v1[e], 0.f); v0[e] = a * a; v1[e] = b * b; }
;                     }
;                     *(u32x4*)(O + (size_t)row * ldc + col0 + bj * 128) = pack8(v0, v1);
.LBB0_892:
	s_lshl_b32 s4, s89, 8
	s_add_i32 s4, s4, s83
	v_mbcnt_lo_u32_b32 v151, -1, 0
	v_mbcnt_hi_u32_b32 v151, -1, v151
	v_mov_b64_e32 v[142:143], s[48:49]
	v_and_or_b32 v140, v151, 15, s4
	v_ashrrev_i32_e32 v141, 31, v140
	v_lshl_add_u64 v[144:145], v[140:141], 2, s[60:61]
	s_lshl_b32 s4, s96, 8
	v_ashrrev_i32_e32 v151, 1, v151
	s_or_b32 s4, s4, s69
	v_and_b32_e32 v151, -8, v151
	v_add_u32_e32 v152, s4, v151
	v_or_b32_e32 v151, 16, v140
	v_mad_i64_i32 v[156:157], s[4:5], v151, s94, v[142:143]
	v_or_b32_e32 v158, 32, v140
	v_ashrrev_i32_e32 v153, 31, v152
	v_mad_i64_i32 v[154:155], s[4:5], v140, s94, v[142:143]
	v_mad_i64_i32 v[158:159], s[4:5], v158, s94, v[142:143]
	v_lshlrev_b64 v[144:145], 1, v[152:153]
	v_lshl_add_u64 v[152:153], v[154:155], 0, v[144:145]
	v_lshl_add_u64 v[154:155], v[156:157], 0, v[144:145]
	v_lshl_add_u64 v[156:157], v[158:159], 0, v[144:145]
	v_add_u32_e32 v170, 0x80, v140
	s_and_b64 vcc, exec, s[6:7]
	s_mov_b64 s[6:7], -1
	s_waitcnt lgkmcnt(0)
	v_fmamk_f32 v141, v228, 0x3b800000, v150
	v_fmamk_f32 v159, v229, 0x3b800000, v150
	v_fmamk_f32 v161, v230, 0x3b800000, v150
	v_rsq_f32_e32 v158, v141
	v_fmamk_f32 v141, v231, 0x3b800000, v150
	v_rsq_f32_e32 v160, v159
	v_rsq_f32_e32 v162, v161
	v_pk_mul_f32 v[126:127], v[126:127], v[158:159] op_sel_hi:[1,0]
	v_pk_mul_f32 v[124:125], v[124:125], v[158:159] op_sel_hi:[1,0]
	v_pk_mul_f32 v[122:123], v[122:123], v[158:159] op_sel_hi:[1,0]
	v_pk_mul_f32 v[120:121], v[120:121], v[158:159] op_sel_hi:[1,0]
	v_pk_mul_f32 v[106:107], v[106:107], v[158:159] op_sel_hi:[1,0]
	v_pk_mul_f32 v[104:105], v[104:105], v[158:159] op_sel_hi:[1,0]
	v_pk_mul_f32 v[98:99], v[98:99], v[158:159] op_sel_hi:[1,0]
	v_pk_mul_f32 v[96:97], v[96:97], v[158:159] op_sel_hi:[1,0]
	v_pk_mul_f32 v[118:119], v[118:119], v[160:161] op_sel_hi:[1,0]
	v_pk_mul_f32 v[116:117], v[116:117], v[160:161] op_sel_hi:[1,0]
	v_pk_mul_f32 v[114:115], v[114:115], v[160:161] op_sel_hi:[1,0]
	v_pk_mul_f32 v[112:113], v[112:113], v[160:161] op_sel_hi:[1,0]
	v_pk_mul_f32 v[94:95], v[94:95], v[160:161] op_sel_hi:[1,0]
	v_pk_mul_f32 v[92:93], v[92:93], v[160:161] op_sel_hi:[1,0]
	v_pk_mul_f32 v[158:159], v[90:91], v[160:161] op_sel_hi:[1,0]
	v_pk_mul_f32 v[160:161], v[88:89], v[160:161] op_sel_hi:[1,0]
	v_pk_mul_f32 v[110:111], v[110:111], v[162:163] op_sel_hi:[1,0]
	v_pk_mul_f32 v[108:109], v[108:109], v[162:163] op_sel_hi:[1,0]
	v_pk_mul_f32 v[102:103], v[102:103], v[162:163] op_sel_hi:[1,0]
	v_pk_mul_f32 v[100:101], v[100:101], v[162:163] op_sel_hi:[1,0]
	v_pk_mul_f32 v[164:165], v[86:87], v[162:163] op_sel_hi:[1,0]
	v_pk_mul_f32 v[166:167], v[84:85], v[162:163] op_sel_hi:[1,0]
	v_pk_mul_f32 v[168:169], v[82:83], v[162:163] op_sel_hi:[1,0]
	v_pk_mul_f32 v[162:163], v[80:81], v[162:163] op_sel_hi:[1,0]
	v_cvt_pk_bf16_f32 v80, v124, v125
	v_cvt_pk_bf16_f32 v81, v126, v127
	v_cvt_pk_bf16_f32 v82, v120, v121
	v_cvt_pk_bf16_f32 v83, v122, v123
	v_cvt_pk_bf16_f32 v84, v104, v105
	v_cvt_pk_bf16_f32 v85, v106, v107
	v_cvt_pk_bf16_f32 v86, v96, v97
	v_cvt_pk_bf16_f32 v87, v98, v99
	v_cvt_pk_bf16_f32 v88, v116, v117
	v_cvt_pk_bf16_f32 v89, v118, v119
	v_cvt_pk_bf16_f32 v90, v112, v113
	v_cvt_pk_bf16_f32 v91, v114, v115
	v_cvt_pk_bf16_f32 v92, v92, v93
	v_cvt_pk_bf16_f32 v93, v94, v95
	v_cvt_pk_bf16_f32 v94, v160, v161
	v_cvt_pk_bf16_f32 v95, v158, v159
	v_cvt_pk_bf16_f32 v96, v108, v109
	v_cvt_pk_bf16_f32 v97, v110, v111
	v_cvt_pk_bf16_f32 v98, v100, v101
	v_cvt_pk_bf16_f32 v99, v102, v103
	global_store_dwordx4 v[152:153], v[80:83], off
	global_store_dwordx4 v[152:153], v[84:87], off offset:256
	global_store_dwordx4 v[154:155], v[88:91], off
	global_store_dwordx4 v[154:155], v[92:95], off offset:256
	global_store_dwordx4 v[156:157], v[96:99], off
	v_rsq_f32_e32 v80, v141
	v_or_b32_e32 v81, 48, v140
	v_cvt_pk_bf16_f32 v100, v166, v167
	v_cvt_pk_bf16_f32 v101, v164, v165
	v_pk_mul_f32 v[76:77], v[76:77], v[80:81] op_sel_hi:[1,0]
	v_pk_mul_f32 v[78:79], v[78:79], v[80:81] op_sel_hi:[1,0]
	v_pk_mul_f32 v[82:83], v[74:75], v[80:81] op_sel_hi:[1,0]
	v_pk_mul_f32 v[74:75], v[72:73], v[80:81] op_sel_hi:[1,0]
	v_cvt_pk_bf16_f32 v72, v76, v77
	v_mad_i64_i32 v[76:77], s[4:5], v81, s94, v[142:143]
	v_cvt_pk_bf16_f32 v73, v78, v79
	v_cvt_pk_bf16_f32 v74, v74, v75
	v_cvt_pk_bf16_f32 v75, v82, v83
	v_lshl_add_u64 v[76:77], v[76:77], 0, v[144:145]
	v_pk_mul_f32 v[68:69], v[68:69], v[80:81] op_sel_hi:[1,0]
	global_store_dwordx4 v[76:77], v[72:75], off
	v_pk_mul_f32 v[70:71], v[70:71], v[80:81] op_sel_hi:[1,0]
	v_cvt_pk_bf16_f32 v102, v162, v163
	v_pk_mul_f32 v[72:73], v[66:67], v[80:81] op_sel_hi:[1,0]
	v_pk_mul_f32 v[66:67], v[64:65], v[80:81] op_sel_hi:[1,0]
	v_cvt_pk_bf16_f32 v64, v68, v69
	v_fmamk_f32 v68, v232, 0x3b800000, v150
	v_rsq_f32_e32 v68, v68
	v_cvt_pk_bf16_f32 v65, v70, v71
	v_cvt_pk_bf16_f32 v66, v66, v67
	v_cvt_pk_bf16_f32 v67, v72, v73
	v_pk_mul_f32 v[60:61], v[60:61], v[68:69] op_sel_hi:[1,0]
; __device__ __forceinline__ u32x4 pack8(f32x4 a, f32x4 b) { u32x4 w; w.x = pk2(a[0], a[1]); w.y = pk2(a[2], a[3]); w.z = pk2(b[0], b[1]); w.w = pk2(b[2], b[3]); return w; }
;     __device__ __forceinline__ void operator()(const Acc& acc, const pg8::Unit& u, int wid) const {
;     ...
;         for (int i = 0; i < 8; ++i) scv[i] = ssq ? ssq[row0 + (i >> 2) * 128 + (i & 3) * 16] : 0.f;
; #pragma unroll
;         for (int ai = 0; ai < 2; ++ai)
; #pragma unroll
;             for (int m = 0; m < 4; ++m) {
;                 const int row = row0 + ai * 128 + m * 16;
;                 const float sc = ssq ? __builtin_amdgcn_rsqf(scv[ai * 4 + m] * inv_n + EPS) : 1.f;
; #pragma unroll
;                 for (int bj = 0; bj < 2; ++bj) {
;                     f32x4 v0 = acc[ai][bj][m][0] * sc, v1 = acc[ai][bj][m][1] * sc;
;                     if (ACT == 1) {
; #pragma unroll
;                         for (int e = 0; e < 4; ++e) { float a = fmaxf(v0[e], 0.f), b = fmaxf(v1[e], 0.f); v0[e] = a * a; v1[e] = b * b; }
;                     }
;                     *(u32x4*)(O + (size_t)row * ldc + col0 + bj * 128) = pack8(v0, v1);
	global_store_dwordx4 v[76:77], v[64:67], off offset:256
	v_pk_mul_f32 v[62:63], v[62:63], v[68:69] op_sel_hi:[1,0]
	v_pk_mul_f32 v[48:49], v[48:49], v[68:69] op_sel_hi:[1,0]
	v_pk_mul_f32 v[64:65], v[58:59], v[68:69] op_sel_hi:[1,0]
	v_pk_mul_f32 v[58:59], v[56:57], v[68:69] op_sel_hi:[1,0]
	v_cvt_pk_bf16_f32 v56, v60, v61
	v_mad_i64_i32 v[60:61], s[4:5], v170, s94, v[142:143]
	v_cvt_pk_bf16_f32 v57, v62, v63
	v_cvt_pk_bf16_f32 v58, v58, v59
	v_cvt_pk_bf16_f32 v59, v64, v65
	v_lshl_add_u64 v[60:61], v[60:61], 0, v[144:145]
	global_store_dwordx4 v[60:61], v[56:59], off
	v_pk_mul_f32 v[50:51], v[50:51], v[68:69] op_sel_hi:[1,0]
	v_cvt_pk_bf16_f32 v103, v168, v169
	v_pk_mul_f32 v[56:57], v[42:43], v[68:69] op_sel_hi:[1,0]
	v_pk_mul_f32 v[42:43], v[40:41], v[68:69] op_sel_hi:[1,0]
	v_cvt_pk_bf16_f32 v40, v48, v49
	v_cvt_pk_bf16_f32 v42, v42, v43
	v_fmamk_f32 v43, v233, 0x3b800000, v150
	v_rsq_f32_e32 v48, v43
	v_cvt_pk_bf16_f32 v41, v50, v51
	v_cvt_pk_bf16_f32 v43, v56, v57
	v_add_u32_e32 v49, 0x90, v140
	global_store_dwordx4 v[60:61], v[40:43], off offset:256
	v_pk_mul_f32 v[44:45], v[44:45], v[48:49] op_sel_hi:[1,0]
	v_pk_mul_f32 v[46:47], v[46:47], v[48:49] op_sel_hi:[1,0]
	v_pk_mul_f32 v[42:43], v[54:55], v[48:49] op_sel_hi:[1,0]
	v_pk_mul_f32 v[40:41], v[52:53], v[48:49] op_sel_hi:[1,0]
	v_pk_mul_f32 v[32:33], v[32:33], v[48:49] op_sel_hi:[1,0]
	v_cvt_pk_bf16_f32 v40, v40, v41
	v_cvt_pk_bf16_f32 v41, v42, v43
	v_cvt_pk_bf16_f32 v42, v44, v45
	v_mad_i64_i32 v[44:45], s[4:5], v49, s94, v[142:143]
	v_cvt_pk_bf16_f32 v43, v46, v47
	v_lshl_add_u64 v[44:45], v[44:45], 0, v[144:145]
	global_store_dwordx4 v[44:45], v[40:43], off
	v_pk_mul_f32 v[34:35], v[34:35], v[48:49] op_sel_hi:[1,0]
	global_store_dwordx4 v[156:157], v[100:103], off offset:256
	v_pk_mul_f32 v[40:41], v[26:27], v[48:49] op_sel_hi:[1,0]
	v_pk_mul_f32 v[26:27], v[24:25], v[48:49] op_sel_hi:[1,0]
	v_cvt_pk_bf16_f32 v24, v32, v33
	v_cvt_pk_bf16_f32 v26, v26, v27
	v_fmamk_f32 v27, v234, 0x3b800000, v150
	v_rsq_f32_e32 v32, v27
	v_cvt_pk_bf16_f32 v25, v34, v35
	v_cvt_pk_bf16_f32 v27, v40, v41
	v_add_u32_e32 v33, 0xa0, v140
	global_store_dwordx4 v[44:45], v[24:27], off offset:256
	v_pk_mul_f32 v[28:29], v[28:29], v[32:33] op_sel_hi:[1,0]
	v_pk_mul_f32 v[30:31], v[30:31], v[32:33] op_sel_hi:[1,0]
	v_pk_mul_f32 v[26:27], v[38:39], v[32:33] op_sel_hi:[1,0]
	v_pk_mul_f32 v[24:25], v[36:37], v[32:33] op_sel_hi:[1,0]
	v_pk_mul_f32 v[16:17], v[16:17], v[32:33] op_sel_hi:[1,0]
	v_cvt_pk_bf16_f32 v24, v24, v25
	v_cvt_pk_bf16_f32 v25, v26, v27
	v_cvt_pk_bf16_f32 v26, v28, v29
	v_mad_i64_i32 v[28:29], s[4:5], v33, s94, v[142:143]
	v_cvt_pk_bf16_f32 v27, v30, v31
	v_lshl_add_u64 v[28:29], v[28:29], 0, v[144:145]
	global_store_dwordx4 v[28:29], v[24:27], off
	v_pk_mul_f32 v[18:19], v[18:19], v[32:33] op_sel_hi:[1,0]
	s_nop 0
	v_pk_mul_f32 v[24:25], v[10:11], v[32:33] op_sel_hi:[1,0]
	v_pk_mul_f32 v[10:11], v[8:9], v[32:33] op_sel_hi:[1,0]
	v_cvt_pk_bf16_f32 v8, v16, v17
	v_cvt_pk_bf16_f32 v10, v10, v11
	v_fmamk_f32 v11, v235, 0x3b800000, v150
	s_min_u32 s4, s95, 0x7f
	s_lshl_b32 s4, s4, 8
	s_add_i32 s4, s4, s83
	v_mbcnt_lo_u32_b32 v238, -1, 0
	v_mbcnt_hi_u32_b32 v238, -1, v238
	v_and_or_b32 v238, v238, 15, s4
	v_ashrrev_i32_e32 v239, 31, v238
	v_lshl_add_u64 v[238:239], v[238:239], 2, s[60:61]
	global_load_dword v228, v[238:239], off
	global_load_dword v229, v[238:239], off offset:64
	global_load_dword v230, v[238:239], off offset:128
	global_load_dword v231, v[238:239], off offset:192
	global_load_dword v232, v[238:239], off offset:512
	global_load_dword v233, v[238:239], off offset:576
	global_load_dword v234, v[238:239], off offset:640
	global_load_dword v235, v[238:239], off offset:704
	v_rsq_f32_e32 v16, v11
	v_cvt_pk_bf16_f32 v9, v18, v19
	v_cvt_pk_bf16_f32 v11, v24, v25
	v_add_u32_e32 v17, 0xb0, v140
	global_store_dwordx4 v[28:29], v[8:11], off offset:256
	v_pk_mul_f32 v[12:13], v[12:13], v[16:17] op_sel_hi:[1,0]
	v_pk_mul_f32 v[14:15], v[14:15], v[16:17] op_sel_hi:[1,0]
	v_pk_mul_f32 v[10:11], v[22:23], v[16:17] op_sel_hi:[1,0]
	v_pk_mul_f32 v[8:9], v[20:21], v[16:17] op_sel_hi:[1,0]
	v_pk_mul_f32 v[6:7], v[6:7], v[16:17] op_sel_hi:[1,0]
	v_cvt_pk_bf16_f32 v8, v8, v9
	v_cvt_pk_bf16_f32 v9, v10, v11
	v_cvt_pk_bf16_f32 v10, v12, v13
	v_mad_i64_i32 v[12:13], s[4:5], v17, s94, v[142:143]
	v_cvt_pk_bf16_f32 v11, v14, v15
	v_lshl_add_u64 v[12:13], v[12:13], 0, v[144:145]
	global_store_dwordx4 v[12:13], v[8:11], off
	v_pk_mul_f32 v[4:5], v[4:5], v[16:17] op_sel_hi:[1,0]
	s_nop 0
	v_pk_mul_f32 v[8:9], v[2:3], v[16:17] op_sel_hi:[1,0]
	v_pk_mul_f32 v[2:3], v[0:1], v[16:17] op_sel_hi:[1,0]
	v_cvt_pk_bf16_f32 v0, v4, v5
	v_cvt_pk_bf16_f32 v1, v6, v7
	v_cvt_pk_bf16_f32 v2, v2, v3
	v_cvt_pk_bf16_f32 v3, v8, v9
	global_store_dwordx4 v[12:13], v[0:3], off offset:256
	s_cbranch_vccnz .LBB0_883
	s_andn2_b64 vcc, exec, s[0:1]
	s_cbranch_vccnz .LBB0_882
	s_barrier
	s_branch .LBB0_882

; __device__ __forceinline__ u32x4 pack8(f32x4 a, f32x4 b) { u32x4 w; w.x = pk2(a[0], a[1]); w.y = pk2(a[2], a[3]); w.z = pk2(b[0], b[1]); w.w = pk2(b[2], b[3]); return w; }
;     __device__ __forceinline__ void operator()(const Acc& acc, const pg8::Unit& u, int wid) const {
;     ...
;                     f32x4 v0 = acc[ai][bj][m][0] * sc, v1 = acc[ai][bj][m][1] * sc;
;                     if (ACT == 1) {
; #pragma unroll
;                         for (int e = 0; e < 4; ++e) { float a = fmaxf(v0[e], 0.f), b = fmaxf(v1[e], 0.f); v0[e] = a * a; v1[e] = b * b; }
;                     }
;                     *(u32x4*)(O + (size_t)row * ldc + col0 + bj * 128) = pack8(v0, v1);
.LBB0_1178:
	s_lshl_b32 s23, s30, 8
	v_mbcnt_lo_u32_b32 v149, -1, 0
	v_mbcnt_hi_u32_b32 v149, -1, v149
	s_add_i32 s23, s23, s65
	v_and_or_b32 v148, v149, 15, s23
	v_ashrrev_i32_e32 v149, 1, v149
	s_lshl_b32 s23, s79, 8
	v_and_b32_e32 v149, -8, v149
	s_or_b32 s23, s23, s69
	v_add_u32_e32 v150, s23, v149
	v_mov_b32_e32 v149, 0
	v_mov_b32_e32 v151, 0
	v_lshlrev_b64 v[152:153], 13, v[148:149]
	v_lshl_add_u64 v[152:153], s[44:45], 0, v[152:153]
	v_lshlrev_b64 v[150:151], 1, v[150:151]
	v_lshl_add_u64 v[152:153], v[152:153], 0, v[150:151]
	v_max_f32_e32 v124, 0, v124
	v_max_f32_e32 v125, 0, v125
	v_max_f32_e32 v126, 0, v126
	v_max_f32_e32 v127, 0, v127
	v_max_f32_e32 v120, 0, v120
	v_max_f32_e32 v121, 0, v121
	v_max_f32_e32 v122, 0, v122
	v_max_f32_e32 v123, 0, v123
	v_pk_mul_f32 v[124:125], v[124:125], v[124:125]
	v_pk_mul_f32 v[126:127], v[126:127], v[126:127]
	v_pk_mul_f32 v[120:121], v[120:121], v[120:121]
	v_pk_mul_f32 v[122:123], v[122:123], v[122:123]
	v_cvt_pk_bf16_f32 v124, v124, v125
	v_cvt_pk_bf16_f32 v125, v126, v127
	v_cvt_pk_bf16_f32 v126, v120, v121
	v_cvt_pk_bf16_f32 v127, v122, v123
	global_store_dwordx4 v[152:153], v[124:127], off
	v_max_f32_e32 v116, 0, v116
	v_max_f32_e32 v117, 0, v117
	v_max_f32_e32 v118, 0, v118
	v_max_f32_e32 v119, 0, v119
	v_max_f32_e32 v112, 0, v112
	v_max_f32_e32 v113, 0, v113
	v_max_f32_e32 v114, 0, v114
	v_max_f32_e32 v115, 0, v115
	v_pk_mul_f32 v[116:117], v[116:117], v[116:117]
	v_pk_mul_f32 v[118:119], v[118:119], v[118:119]
	v_pk_mul_f32 v[112:113], v[112:113], v[112:113]
	v_pk_mul_f32 v[114:115], v[114:115], v[114:115]
	v_cvt_pk_bf16_f32 v116, v116, v117
	v_cvt_pk_bf16_f32 v117, v118, v119
	v_cvt_pk_bf16_f32 v118, v112, v113
	v_cvt_pk_bf16_f32 v119, v114, v115
	global_store_dwordx4 v[152:153], v[116:119], off offset:256
	v_add_co_u32_e32 v150, vcc, 0x20000, v152
	s_nop 1
	v_addc_co_u32_e32 v151, vcc, 0, v153, vcc
	v_max_f32_e32 v108, 0, v108
	v_max_f32_e32 v109, 0, v109
	v_max_f32_e32 v110, 0, v110
	v_max_f32_e32 v111, 0, v111
	v_max_f32_e32 v104, 0, v104
	v_max_f32_e32 v105, 0, v105
	v_max_f32_e32 v106, 0, v106
	v_max_f32_e32 v107, 0, v107
	v_pk_mul_f32 v[108:109], v[108:109], v[108:109]
	v_pk_mul_f32 v[110:111], v[110:111], v[110:111]
	v_pk_mul_f32 v[104:105], v[104:105], v[104:105]
	v_pk_mul_f32 v[106:107], v[106:107], v[106:107]
	v_cvt_pk_bf16_f32 v108, v108, v109
	v_cvt_pk_bf16_f32 v109, v110, v111
	v_cvt_pk_bf16_f32 v110, v104, v105
	v_cvt_pk_bf16_f32 v111, v106, v107
	global_store_dwordx4 v[150:151], v[108:111], off
	v_max_f32_e32 v100, 0, v100
	v_max_f32_e32 v101, 0, v101
	v_max_f32_e32 v102, 0, v102
	v_max_f32_e32 v103, 0, v103
	v_max_f32_e32 v96, 0, v96
	v_max_f32_e32 v97, 0, v97
	v_max_f32_e32 v98, 0, v98
	v_max_f32_e32 v99, 0, v99
	v_pk_mul_f32 v[100:101], v[100:101], v[100:101]
	v_pk_mul_f32 v[102:103], v[102:103], v[102:103]
	v_pk_mul_f32 v[96:97], v[96:97], v[96:97]
	v_pk_mul_f32 v[98:99], v[98:99], v[98:99]
	v_cvt_pk_bf16_f32 v100, v100, v101
	v_cvt_pk_bf16_f32 v101, v102, v103
	v_cvt_pk_bf16_f32 v102, v96, v97
	v_cvt_pk_bf16_f32 v103, v98, v99
	global_store_dwordx4 v[150:151], v[100:103], off offset:256
	v_add_co_u32_e32 v150, vcc, 0x40000, v152
	s_nop 1
	v_addc_co_u32_e32 v151, vcc, 0, v153, vcc
	v_max_f32_e32 v92, 0, v92
	v_max_f32_e32 v93, 0, v93
	v_max_f32_e32 v94, 0, v94
	v_max_f32_e32 v95, 0, v95
	v_max_f32_e32 v88, 0, v88
	v_max_f32_e32 v89, 0, v89
	v_max_f32_e32 v90, 0, v90
	v_max_f32_e32 v91, 0, v91
	v_pk_mul_f32 v[92:93], v[92:93], v[92:93]
	v_pk_mul_f32 v[94:95], v[94:95], v[94:95]
	v_pk_mul_f32 v[88:89], v[88:89], v[88:89]
	v_pk_mul_f32 v[90:91], v[90:91], v[90:91]
	v_cvt_pk_bf16_f32 v92, v92, v93
	v_cvt_pk_bf16_f32 v93, v94, v95
	v_cvt_pk_bf16_f32 v94, v88, v89
	v_cvt_pk_bf16_f32 v95, v90, v91
	global_store_dwordx4 v[150:151], v[92:95], off
	v_max_f32_e32 v84, 0, v84
	v_max_f32_e32 v85, 0, v85
	v_max_f32_e32 v86, 0, v86
	v_max_f32_e32 v87, 0, v87
	v_max_f32_e32 v80, 0, v80
	v_max_f32_e32 v81, 0, v81
	v_max_f32_e32 v82, 0, v82
	v_max_f32_e32 v83, 0, v83
	v_pk_mul_f32 v[84:85], v[84:85], v[84:85]
	v_pk_mul_f32 v[86:87], v[86:87], v[86:87]
	v_pk_mul_f32 v[80:81], v[80:81], v[80:81]
	v_pk_mul_f32 v[82:83], v[82:83], v[82:83]
	v_cvt_pk_bf16_f32 v84, v84, v85
	v_cvt_pk_bf16_f32 v85, v86, v87
	v_cvt_pk_bf16_f32 v86, v80, v81
	v_cvt_pk_bf16_f32 v87, v82, v83
	global_store_dwordx4 v[150:151], v[84:87], off offset:256
	v_add_co_u32_e32 v150, vcc, 0x60000, v152
	s_nop 1
	v_addc_co_u32_e32 v151, vcc, 0, v153, vcc
	v_max_f32_e32 v76, 0, v76
	v_max_f32_e32 v77, 0, v77
	v_max_f32_e32 v78, 0, v78
	v_max_f32_e32 v79, 0, v79
	v_max_f32_e32 v72, 0, v72
	v_max_f32_e32 v73, 0, v73
	v_max_f32_e32 v74, 0, v74
	v_max_f32_e32 v75, 0, v75
	v_pk_mul_f32 v[76:77], v[76:77], v[76:77]
	v_pk_mul_f32 v[78:79], v[78:79], v[78:79]
	v_pk_mul_f32 v[72:73], v[72:73], v[72:73]
	v_pk_mul_f32 v[74:75], v[74:75], v[74:75]
	v_cvt_pk_bf16_f32 v76, v76, v77
	v_cvt_pk_bf16_f32 v77, v78, v79
	v_cvt_pk_bf16_f32 v78, v72, v73
	v_cvt_pk_bf16_f32 v79, v74, v75
	global_store_dwordx4 v[150:151], v[76:79], off
	v_max_f32_e32 v68, 0, v68
	v_max_f32_e32 v69, 0, v69
	v_max_f32_e32 v70, 0, v70
	v_max_f32_e32 v71, 0, v71
	v_max_f32_e32 v64, 0, v64
	v_max_f32_e32 v65, 0, v65
	v_max_f32_e32 v66, 0, v66
	v_max_f32_e32 v67, 0, v67
	v_pk_mul_f32 v[68:69], v[68:69], v[68:69]
	v_pk_mul_f32 v[70:71], v[70:71], v[70:71]
; __device__ __forceinline__ u32x4 pack8(f32x4 a, f32x4 b) { u32x4 w; w.x = pk2(a[0], a[1]); w.y = pk2(a[2], a[3]); w.z = pk2(b[0], b[1]); w.w = pk2(b[2], b[3]); return w; }
;     __device__ __forceinline__ void operator()(const Acc& acc, const pg8::Unit& u, int wid) const {
;     ...
;                     f32x4 v0 = acc[ai][bj][m][0] * sc, v1 = acc[ai][bj][m][1] * sc;
;                     if (ACT == 1) {
; #pragma unroll
;                         for (int e = 0; e < 4; ++e) { float a = fmaxf(v0[e], 0.f), b = fmaxf(v1[e], 0.f); v0[e] = a * a; v1[e] = b * b; }
;                     }
;                     *(u32x4*)(O + (size_t)row * ldc + col0 + bj * 128) = pack8(v0, v1);
	v_pk_mul_f32 v[64:65], v[64:65], v[64:65]
	v_pk_mul_f32 v[66:67], v[66:67], v[66:67]
	v_cvt_pk_bf16_f32 v68, v68, v69
	v_cvt_pk_bf16_f32 v69, v70, v71
	v_cvt_pk_bf16_f32 v70, v64, v65
	v_cvt_pk_bf16_f32 v71, v66, v67
	global_store_dwordx4 v[150:151], v[68:71], off offset:256
	v_add_co_u32_e32 v150, vcc, 0x100000, v152
	s_nop 1
	v_addc_co_u32_e32 v151, vcc, 0, v153, vcc
	v_max_f32_e32 v60, 0, v60
	v_max_f32_e32 v61, 0, v61
	v_max_f32_e32 v62, 0, v62
	v_max_f32_e32 v63, 0, v63
	v_max_f32_e32 v56, 0, v56
	v_max_f32_e32 v57, 0, v57
	v_max_f32_e32 v58, 0, v58
	v_max_f32_e32 v59, 0, v59
	v_pk_mul_f32 v[60:61], v[60:61], v[60:61]
	v_pk_mul_f32 v[62:63], v[62:63], v[62:63]
	v_pk_mul_f32 v[56:57], v[56:57], v[56:57]
	v_pk_mul_f32 v[58:59], v[58:59], v[58:59]
	v_cvt_pk_bf16_f32 v60, v60, v61
	v_cvt_pk_bf16_f32 v61, v62, v63
	v_cvt_pk_bf16_f32 v62, v56, v57
	v_cvt_pk_bf16_f32 v63, v58, v59
	global_store_dwordx4 v[150:151], v[60:63], off
	v_max_f32_e32 v52, 0, v52
	v_max_f32_e32 v53, 0, v53
	v_max_f32_e32 v54, 0, v54
	v_max_f32_e32 v55, 0, v55
	v_max_f32_e32 v48, 0, v48
	v_max_f32_e32 v49, 0, v49
	v_max_f32_e32 v50, 0, v50
	v_max_f32_e32 v51, 0, v51
	v_pk_mul_f32 v[52:53], v[52:53], v[52:53]
	v_pk_mul_f32 v[54:55], v[54:55], v[54:55]
	v_pk_mul_f32 v[48:49], v[48:49], v[48:49]
	v_pk_mul_f32 v[50:51], v[50:51], v[50:51]
	v_cvt_pk_bf16_f32 v52, v52, v53
	v_cvt_pk_bf16_f32 v53, v54, v55
	v_cvt_pk_bf16_f32 v54, v48, v49
	v_cvt_pk_bf16_f32 v55, v50, v51
	global_store_dwordx4 v[150:151], v[52:55], off offset:256
	v_add_co_u32_e32 v150, vcc, 0x120000, v152
	s_nop 1
	v_addc_co_u32_e32 v151, vcc, 0, v153, vcc
	v_max_f32_e32 v44, 0, v44
	v_max_f32_e32 v45, 0, v45
	v_max_f32_e32 v46, 0, v46
	v_max_f32_e32 v47, 0, v47
	v_max_f32_e32 v40, 0, v40
	v_max_f32_e32 v41, 0, v41
	v_max_f32_e32 v42, 0, v42
	v_max_f32_e32 v43, 0, v43
	v_pk_mul_f32 v[44:45], v[44:45], v[44:45]
	v_pk_mul_f32 v[46:47], v[46:47], v[46:47]
	v_pk_mul_f32 v[40:41], v[40:41], v[40:41]
	v_pk_mul_f32 v[42:43], v[42:43], v[42:43]
	v_cvt_pk_bf16_f32 v44, v44, v45
	v_cvt_pk_bf16_f32 v45, v46, v47
	v_cvt_pk_bf16_f32 v46, v40, v41
	v_cvt_pk_bf16_f32 v47, v42, v43
	global_store_dwordx4 v[150:151], v[44:47], off
	v_max_f32_e32 v36, 0, v36
	v_max_f32_e32 v37, 0, v37
	v_max_f32_e32 v38, 0, v38
	v_max_f32_e32 v39, 0, v39
	v_max_f32_e32 v32, 0, v32
	v_max_f32_e32 v33, 0, v33
	v_max_f32_e32 v34, 0, v34
	v_max_f32_e32 v35, 0, v35
	v_pk_mul_f32 v[36:37], v[36:37], v[36:37]
	v_pk_mul_f32 v[38:39], v[38:39], v[38:39]
	v_pk_mul_f32 v[32:33], v[32:33], v[32:33]
	v_pk_mul_f32 v[34:35], v[34:35], v[34:35]
	v_cvt_pk_bf16_f32 v36, v36, v37
	v_cvt_pk_bf16_f32 v37, v38, v39
	v_cvt_pk_bf16_f32 v38, v32, v33
	v_cvt_pk_bf16_f32 v39, v34, v35
	global_store_dwordx4 v[150:151], v[36:39], off offset:256
	v_add_co_u32_e32 v150, vcc, 0x140000, v152
	s_nop 1
	v_addc_co_u32_e32 v151, vcc, 0, v153, vcc
	v_max_f32_e32 v28, 0, v28
	v_max_f32_e32 v29, 0, v29
	v_max_f32_e32 v30, 0, v30
	v_max_f32_e32 v31, 0, v31
	v_max_f32_e32 v24, 0, v24
	v_max_f32_e32 v25, 0, v25
	v_max_f32_e32 v26, 0, v26
	v_max_f32_e32 v27, 0, v27
	v_pk_mul_f32 v[28:29], v[28:29], v[28:29]
	v_pk_mul_f32 v[30:31], v[30:31], v[30:31]
	v_pk_mul_f32 v[24:25], v[24:25], v[24:25]
	v_pk_mul_f32 v[26:27], v[26:27], v[26:27]
	v_cvt_pk_bf16_f32 v28, v28, v29
	v_cvt_pk_bf16_f32 v29, v30, v31
	v_cvt_pk_bf16_f32 v30, v24, v25
	v_cvt_pk_bf16_f32 v31, v26, v27
	global_store_dwordx4 v[150:151], v[28:31], off
	v_max_f32_e32 v20, 0, v20
	v_max_f32_e32 v21, 0, v21
	v_max_f32_e32 v22, 0, v22
	v_max_f32_e32 v23, 0, v23
	v_max_f32_e32 v16, 0, v16
	v_max_f32_e32 v17, 0, v17
	v_max_f32_e32 v18, 0, v18
	v_max_f32_e32 v19, 0, v19
	v_pk_mul_f32 v[20:21], v[20:21], v[20:21]
	v_pk_mul_f32 v[22:23], v[22:23], v[22:23]
	v_pk_mul_f32 v[16:17], v[16:17], v[16:17]
	v_pk_mul_f32 v[18:19], v[18:19], v[18:19]
	v_cvt_pk_bf16_f32 v20, v20, v21
	v_cvt_pk_bf16_f32 v21, v22, v23
	v_cvt_pk_bf16_f32 v22, v16, v17
	v_cvt_pk_bf16_f32 v23, v18, v19
	global_store_dwordx4 v[150:151], v[20:23], off offset:256
	v_add_co_u32_e32 v150, vcc, 0x160000, v152
	s_nop 1
	v_addc_co_u32_e32 v151, vcc, 0, v153, vcc
	v_max_f32_e32 v12, 0, v12
	v_max_f32_e32 v13, 0, v13
	v_max_f32_e32 v14, 0, v14
	v_max_f32_e32 v15, 0, v15
	v_max_f32_e32 v8, 0, v8
	v_max_f32_e32 v9, 0, v9
	v_max_f32_e32 v10, 0, v10
	v_max_f32_e32 v11, 0, v11
	v_pk_mul_f32 v[12:13], v[12:13], v[12:13]
	v_pk_mul_f32 v[14:15], v[14:15], v[14:15]
	v_pk_mul_f32 v[8:9], v[8:9], v[8:9]
	v_pk_mul_f32 v[10:11], v[10:11], v[10:11]
	v_cvt_pk_bf16_f32 v12, v12, v13
	v_cvt_pk_bf16_f32 v13, v14, v15
	v_cvt_pk_bf16_f32 v14, v8, v9
	v_cvt_pk_bf16_f32 v15, v10, v11
	global_store_dwordx4 v[150:151], v[12:15], off
	v_max_f32_e32 v4, 0, v4
	v_max_f32_e32 v5, 0, v5
	v_max_f32_e32 v6, 0, v6
	v_max_f32_e32 v7, 0, v7
	v_max_f32_e32 v0, 0, v0
	v_max_f32_e32 v1, 0, v1
	v_max_f32_e32 v2, 0, v2
	v_max_f32_e32 v3, 0, v3
	v_pk_mul_f32 v[4:5], v[4:5], v[4:5]
	v_pk_mul_f32 v[6:7], v[6:7], v[6:7]
	v_pk_mul_f32 v[0:1], v[0:1], v[0:1]
	v_pk_mul_f32 v[2:3], v[2:3], v[2:3]
	v_cvt_pk_bf16_f32 v4, v4, v5
	v_cvt_pk_bf16_f32 v5, v6, v7
	v_cvt_pk_bf16_f32 v6, v0, v1
	v_cvt_pk_bf16_f32 v7, v2, v3
	s_andn2_b64 vcc, exec, s[4:5]
	s_mov_b64 s[4:5], -1
	global_store_dwordx4 v[150:151], v[4:7], off offset:256
	s_cbranch_vccnz .LBB0_1167
	s_andn2_b64 vcc, exec, s[0:1]
	s_cbranch_vccnz .LBB0_1166
	s_barrier
	s_branch .LBB0_1166

; __device__ __forceinline__ int lane_id_asm() { int l; asm volatile("v_mbcnt_lo_u32_b32 %0, -1, 0\n\tv_mbcnt_hi_u32_b32 %0, -1, %0" : "=v"(l)); return l; }
; __device__ __forceinline__ u32x4 pack8(f32x4 a, f32x4 b) { u32x4 w; w.x = pk2(a[0], a[1]); w.y = pk2(a[2], a[3]); w.z = pk2(b[0], b[1]); w.w = pk2(b[2], b[3]); return w; }
;     __device__ __forceinline__ void operator()(const Acc& acc, const pg8::Unit& u, int wid) const {
;         const int lane_ = lane_id_asm(), wr = wid >> 2, wc = wid & 3, fr = lane_ & 15, fq = lane_ >> 4;
;         const int row0 = u.pm * 256 + wr * 64 + fr, col0 = u.pn * 256 + wc * 32 + 8 * fq;
; #pragma unroll
;         for (int ai = 0; ai < 2; ++ai)
; #pragma unroll
;             for (int m = 0; m < 4; ++m)
; #pragma unroll
;                 for (int bj = 0; bj < 2; ++bj) *(u32x4*)(O + (size_t)(row0 + ai * 128 + m * 16) * 1024 + col0 + bj * 128) = pack8(acc[ai][bj][m][0], acc[ai][bj][m][1]);
;     }
.LBB0_1332:
	s_lshl_b32 s20, s20, 8
	v_mbcnt_lo_u32_b32 v145, -1, 0
	v_mbcnt_hi_u32_b32 v145, -1, v145
	s_add_i32 s20, s20, s79
	v_and_or_b32 v144, v145, 15, s20
	s_lshl_b32 s20, s87, 8
	v_ashrrev_i32_e32 v145, 1, v145
	s_or_b32 s20, s20, s69
	v_and_b32_e32 v145, -8, v145
	v_add_u32_e32 v146, s20, v145
	v_ashrrev_i32_e32 v145, 31, v144
	v_ashrrev_i32_e32 v147, 31, v146
	v_lshlrev_b64 v[148:149], 11, v[144:145]
	v_cvt_pk_bf16_f32 v124, v124, v125
	v_cvt_pk_bf16_f32 v125, v126, v127
	v_cvt_pk_bf16_f32 v126, v120, v121
	v_cvt_pk_bf16_f32 v127, v122, v123
	v_lshl_add_u64 v[120:121], s[48:49], 0, v[148:149]
	v_lshlrev_b64 v[122:123], 1, v[146:147]
	v_cvt_pk_bf16_f32 v108, v108, v109
	v_cvt_pk_bf16_f32 v109, v110, v111
	v_cvt_pk_bf16_f32 v110, v104, v105
	v_or_b32_e32 v104, 16, v144
	v_lshl_add_u64 v[120:121], v[120:121], 0, v[122:123]
	v_cvt_pk_bf16_f32 v111, v106, v107
	v_ashrrev_i32_e32 v105, 31, v104
	global_store_dwordx4 v[120:121], v[108:111], off offset:256
	v_cvt_pk_bf16_f32 v60, v60, v61
	v_cvt_pk_bf16_f32 v61, v62, v63
	v_lshlrev_b64 v[108:109], 11, v[104:105]
	v_cvt_pk_bf16_f32 v63, v58, v59
	v_add_co_u32_e32 v58, vcc, s83, v120
	v_lshl_add_u64 v[108:109], s[48:49], 0, v[108:109]
	v_cvt_pk_bf16_f32 v92, v92, v93
	v_cvt_pk_bf16_f32 v93, v94, v95
	v_cvt_pk_bf16_f32 v94, v88, v89
	v_or_b32_e32 v88, 32, v144
	v_cvt_pk_bf16_f32 v62, v56, v57
	v_lshl_add_u64 v[56:57], v[120:121], 0, s[10:11]
	v_addc_co_u32_e32 v59, vcc, 0, v121, vcc
	v_cvt_pk_bf16_f32 v44, v44, v45
	v_cvt_pk_bf16_f32 v45, v46, v47
	v_cvt_pk_bf16_f32 v46, v40, v41
	v_cvt_pk_bf16_f32 v47, v42, v43
	v_lshl_add_u64 v[108:109], v[108:109], 0, v[122:123]
	v_cvt_pk_bf16_f32 v95, v90, v91
	v_ashrrev_i32_e32 v89, 31, v88
	global_store_dwordx4 v[56:57], v[44:47], off offset:256
	global_store_dwordx4 v[108:109], v[92:95], off offset:256
	v_cvt_pk_bf16_f32 v28, v28, v29
	v_add_co_u32_e32 v46, vcc, s84, v120
	v_lshlrev_b64 v[92:93], 11, v[88:89]
	v_lshl_add_u64 v[44:45], v[120:121], 0, s[12:13]
	v_addc_co_u32_e32 v47, vcc, 0, v121, vcc
	v_cvt_pk_bf16_f32 v29, v30, v31
	v_cvt_pk_bf16_f32 v30, v24, v25
	v_cvt_pk_bf16_f32 v31, v26, v27
	v_lshl_add_u64 v[92:93], s[48:49], 0, v[92:93]
	v_cvt_pk_bf16_f32 v76, v76, v77
	v_cvt_pk_bf16_f32 v77, v78, v79
	v_cvt_pk_bf16_f32 v78, v72, v73
	v_or_b32_e32 v72, 48, v144
	global_store_dwordx4 v[44:45], v[28:31], off offset:256
	v_lshl_add_u64 v[92:93], v[92:93], 0, v[122:123]
	v_cvt_pk_bf16_f32 v79, v74, v75
	v_add_co_u32_e32 v30, vcc, s85, v120
	v_ashrrev_i32_e32 v73, 31, v72
	v_lshl_add_u64 v[28:29], v[120:121], 0, s[16:17]
	v_addc_co_u32_e32 v31, vcc, 0, v121, vcc
	v_cvt_pk_bf16_f32 v12, v12, v13
	v_cvt_pk_bf16_f32 v13, v14, v15
	v_cvt_pk_bf16_f32 v14, v8, v9
	v_cvt_pk_bf16_f32 v15, v10, v11
	global_store_dwordx4 v[92:93], v[76:79], off offset:256
	global_store_dwordx4 v[28:29], v[12:15], off offset:256
	v_cvt_pk_bf16_f32 v104, v116, v117
	v_lshlrev_b64 v[76:77], 11, v[72:73]
	v_add_co_u32_e32 v14, vcc, s86, v120
	v_lshl_add_u64 v[76:77], s[48:49], 0, v[76:77]
	s_nop 0
	v_addc_co_u32_e32 v15, vcc, 0, v121, vcc
	v_cvt_pk_bf16_f32 v105, v118, v119
	v_cvt_pk_bf16_f32 v106, v112, v113
	v_cvt_pk_bf16_f32 v107, v114, v115
	v_cvt_pk_bf16_f32 v88, v100, v101
	v_cvt_pk_bf16_f32 v89, v102, v103
	v_cvt_pk_bf16_f32 v90, v96, v97
	v_cvt_pk_bf16_f32 v91, v98, v99
	v_cvt_pk_bf16_f32 v72, v84, v85
	v_cvt_pk_bf16_f32 v73, v86, v87
	v_cvt_pk_bf16_f32 v74, v80, v81
	v_cvt_pk_bf16_f32 v75, v82, v83
	v_lshl_add_u64 v[76:77], v[76:77], 0, v[122:123]
	v_cvt_pk_bf16_f32 v68, v68, v69
	v_cvt_pk_bf16_f32 v69, v70, v71
	v_cvt_pk_bf16_f32 v70, v64, v65
	v_cvt_pk_bf16_f32 v71, v66, v67
	v_cvt_pk_bf16_f32 v40, v52, v53
	v_cvt_pk_bf16_f32 v41, v54, v55
	v_cvt_pk_bf16_f32 v42, v48, v49
	v_cvt_pk_bf16_f32 v43, v50, v51
	v_cvt_pk_bf16_f32 v24, v36, v37
	v_cvt_pk_bf16_f32 v25, v38, v39
	v_cvt_pk_bf16_f32 v26, v32, v33
	v_cvt_pk_bf16_f32 v27, v34, v35
	v_cvt_pk_bf16_f32 v8, v20, v21
	v_cvt_pk_bf16_f32 v9, v22, v23
	v_cvt_pk_bf16_f32 v10, v16, v17
	v_cvt_pk_bf16_f32 v11, v18, v19
	v_lshl_add_u64 v[12:13], v[120:121], 0, s[18:19]
	v_cvt_pk_bf16_f32 v4, v4, v5
	v_cvt_pk_bf16_f32 v5, v6, v7
	v_cvt_pk_bf16_f32 v6, v0, v1
	v_cvt_pk_bf16_f32 v7, v2, v3
	s_andn2_b64 vcc, exec, s[0:1]
	s_mov_b64 s[0:1], -1
	global_store_dwordx4 v[120:121], v[124:127], off
	global_store_dwordx4 v[108:109], v[104:107], off
	global_store_dwordx4 v[92:93], v[88:91], off
	global_store_dwordx4 v[76:77], v[72:75], off
	global_store_dwordx4 v[76:77], v[68:71], off offset:256
	global_store_dwordx4 v[58:59], v[60:63], off
	global_store_dwordx4 v[46:47], v[40:43], off
	global_store_dwordx4 v[30:31], v[24:27], off
	global_store_dwordx4 v[14:15], v[8:11], off
	global_store_dwordx4 v[12:13], v[4:7], off offset:256
	s_cbranch_vccnz .LBB0_1321
	s_andn2_b64 vcc, exec, s[4:5]
	s_cbranch_vccnz .LBB0_1320
	s_barrier
	s_branch .LBB0_1320
